# adds pipelined K-loops (LDS reads 2 groups ahead, DMA interleaved with MFMAs) for the FFN-down s=0 and s=1 (T rows) GEMMs
# speedup vs baseline: 1.0656x; 1.0106x over previous
; template <int EPI, int MI>
; DI void gemm_phase(const GemmDesc& g, char* smem, int vb, int nvb) {
;     ...
;   for (int q = start; q < local; q += step) {
;     const int mg = q / per;
;     const int rem = q - mg * per;
;     const int tn = rem / PM;
;     const int tm = mbase + mg * PM + (rem - tn * PM);
;     gemm_tile<EPI, MI>(g, tm, tn, smem);
.LBB0_202:
	s_abs_i32 s1, s5
	v_readlane_b32 s15, v219, 45
	s_mul_hi_u32 s15, s1, s15
	v_readlane_b32 s18, v219, 44
	s_mul_i32 s16, s15, s18
	s_sub_i32 s1, s1, s16
	s_ashr_i32 s0, s5, 31
	s_add_i32 s16, s15, 1
	s_sub_i32 s17, s1, s18
	s_cmp_ge_u32 s1, s18
	s_cselect_b32 s15, s16, s15
	s_cselect_b32 s1, s17, s1
	s_add_i32 s16, s15, 1
	s_cmp_ge_u32 s1, s18
	s_cselect_b32 s1, s16, s15
	s_xor_b32 s1, s1, s0
	s_sub_i32 s15, s1, s0
	s_mul_i32 s16, s15, s18
	s_sub_i32 s16, s5, s16
	s_abs_i32 s18, s16
	v_readlane_b32 s19, v219, 46
	s_mul_hi_u32 s19, s18, s19
	v_readlane_b32 s42, v218, 32
	s_mul_i32 s38, s19, s42
	s_sub_i32 s18, s18, s38
	s_ashr_i32 s17, s16, 31
	s_add_i32 s38, s19, 1
	s_sub_i32 s39, s18, s42
	s_cmp_ge_u32 s18, s42
	s_cselect_b32 s19, s38, s19
	s_cselect_b32 s18, s39, s18
	s_add_i32 s38, s19, 1
	s_cmp_ge_u32 s18, s42
	s_cselect_b32 s18, s38, s19
	s_xor_b32 s18, s18, s17
	s_sub_i32 s39, s18, s17
	s_sub_i32 s15, s15, s39
	v_mov_b32_e32 v4, v132
	s_mul_i32 s15, s15, s42
	s_add_i32 s16, s16, s54
	s_add_i32 s38, s16, s15
	v_ashrrev_i32_e32 v97, 3, v4
	v_ashrrev_i32_e32 v120, 7, v4
	v_bfe_u32 v0, v4, 6, 2
	v_xor_b32_e32 v1, v97, v4
	s_mulk_i32 s38, 0xc0
	v_and_b32_e32 v121, 31, v4
	v_bitop3_b32 v2, v1, v0, 7 bitop3:0x6c
	v_mul_lo_u32 v0, v120, s6
	v_and_b32_e32 v115, 7, v4
	v_or_b32_e32 v5, v0, v121
	v_lshrrev_b32_e32 v0, 3, v4
	s_waitcnt vmcnt(10)
	v_add_u32_e32 v98, s38, v97
	v_bfe_u32 v122, v4, 5, 1
	v_bitop3_b32 v0, v0, v115, 3 bitop3:0x6c
	v_ashrrev_i32_e32 v99, 31, v98
	v_xor_b32_e32 v6, v0, v122
	v_lshlrev_b64 v[0:1], 11, v[98:99]
	v_readlane_b32 s42, v223, 59
	v_lshlrev_b32_e32 v99, 4, v4
	v_readlane_b32 s43, v223, 60
	v_lshlrev_b32_e32 v100, 4, v2
	v_lshl_add_u32 v2, s39, 7, v97
	v_add_u32_e32 v124, 0, v99
	v_lshl_add_u64 v[0:1], s[42:43], 0, v[0:1]
	v_mov_b32_e32 v101, v96
	v_ashrrev_i32_e32 v3, 31, v2
	v_readfirstlane_b32 s15, v124
	v_add_u32_e32 v125, 0x1000, v124
	v_lshl_add_u64 v[0:1], v[0:1], 0, v[100:101]
	v_lshlrev_b64 v[2:3], 11, v[2:3]
	s_mov_b32 m0, s15
	s_mov_b64 s[42:43], 0x10000
	v_readfirstlane_b32 s15, v125
	v_add_u32_e32 v126, 0x2000, v124
	s_waitcnt vmcnt(9)
	v_lshl_add_u64 v[102:103], s[70:71], 0, v[2:3]
	global_load_lds_dwordx4 v[0:1], off
	v_lshl_add_u64 v[2:3], v[0:1], 0, s[42:43]
	s_mov_b32 m0, s15
	s_mov_b64 s[44:45], 0x20000
	v_readfirstlane_b32 s15, v126
	v_add_u32_e32 v127, 0x3000, v124
	global_load_lds_dwordx4 v[2:3], off
	v_lshl_add_u64 v[2:3], v[0:1], 0, s[44:45]
	s_mov_b32 m0, s15
	s_mov_b64 s[46:47], 0x30000
	v_readfirstlane_b32 s15, v127
	v_add_u32_e32 v128, 0x4000, v124
	global_load_lds_dwordx4 v[2:3], off
	v_lshl_add_u64 v[2:3], v[0:1], 0, s[46:47]
	s_mov_b32 m0, s15
	s_mov_b64 s[52:53], 0x40000
	v_readfirstlane_b32 s15, v128
	v_add_u32_e32 v129, 0x5000, v124
	global_load_lds_dwordx4 v[2:3], off
	v_lshl_add_u64 v[2:3], v[0:1], 0, s[52:53]
	s_mov_b32 m0, s15
	s_mov_b64 s[52:53], 0x50000
	v_readfirstlane_b32 s15, v129
	v_add_u32_e32 v130, 0xc000, v124
	global_load_lds_dwordx4 v[2:3], off
	v_lshl_add_u64 v[0:1], v[0:1], 0, s[52:53]
	s_mov_b32 m0, s15
	v_readfirstlane_b32 s15, v130
	v_add_u32_e32 v131, 0xd000, v124
	global_load_lds_dwordx4 v[0:1], off
	v_lshl_add_u64 v[0:1], v[102:103], 0, v[100:101]
	s_mov_b32 m0, s15
	v_readfirstlane_b32 s15, v131
	v_add_u32_e32 v153, 0xe000, v124
	global_load_lds_dwordx4 v[0:1], off
	v_lshl_add_u64 v[2:3], v[0:1], 0, s[42:43]
	s_mov_b32 m0, s15
	v_readfirstlane_b32 s15, v153
	v_add_u32_e32 v154, 0xf000, v124
	global_load_lds_dwordx4 v[2:3], off
	v_lshl_add_u64 v[2:3], v[0:1], 0, s[44:45]
	s_mov_b32 m0, s15
	v_readfirstlane_b32 s15, v154
	global_load_lds_dwordx4 v[2:3], off
	v_lshl_add_u64 v[0:1], v[0:1], 0, s[46:47]
	s_mov_b32 m0, s15
	s_mul_i32 s0, s0, 43
	global_load_lds_dwordx4 v[0:1], off
	s_add_i32 s17, s17, s0
	s_sub_i32 s0, s17, s18
	s_mul_i32 s1, s1, 43
	s_sub_i32 s0, s0, s1
	v_readlane_b32 s1, v218, 33
	v_bfe_u32 v123, v4, 6, 1
	v_lshlrev_b32_e32 v0, 7, v121
	s_mul_i32 s0, s1, s0
	v_lshl_or_b32 v0, v123, 13, v0
	s_add_i32 s0, s0, s4
	v_add_u32_e32 v156, 0, v0
	v_add_u32_e32 v158, s10, v0
	v_add_u32_e32 v0, s0, v97
	v_ashrrev_i32_e32 v1, 31, v0
	s_waitcnt vmcnt(0)
; template <int EPI, int MI>
; DI void gemm_tile(const GemmDesc& g, int tm, int tn, char* smem) {
;     ...
;   const int nk = g.K >> 6;
;   f32x16 acc[MI][2];
; #pragma unroll
;   for (int a = 0; a < MI; ++a)
; #pragma unroll
;     for (int b = 0; b < 2; ++b)
; #pragma unroll
;       for (int i = 0; i < 16; ++i) acc[a][b][i] = 0.f;
;   const int srow = tid >> 3;
;   const int schunk = (tid & 7) ^ ((srow & 7) ^ ((srow >> 3) & 3));
;     ...
;   G_GLDS(0, 0);
;   asm volatile("s_waitcnt vmcnt(0)" ::: "memory");
;   __syncthreads();
	v_lshlrev_b64 v[0:1], 11, v[0:1]
	v_lshlrev_b32_e32 v157, 4, v6
	v_lshl_add_u64 v[104:105], s[70:71], 0, v[0:1]
	v_mov_b32_e32 v0, 0
	v_lshl_add_u32 v155, v5, 7, 0
	s_mov_b32 s15, 0
	v_mov_b32_e32 v1, v0
	v_mov_b32_e32 v2, v0
	v_mov_b32_e32 v3, v0
	v_mov_b32_e32 v4, v0
	v_mov_b32_e32 v5, v0
	v_mov_b32_e32 v6, v0
	v_mov_b32_e32 v7, v0
	v_mov_b32_e32 v8, v0
	v_mov_b32_e32 v9, v0
	v_mov_b32_e32 v10, v0
	v_mov_b32_e32 v11, v0
	v_mov_b32_e32 v12, v0
	v_mov_b32_e32 v13, v0
	v_mov_b32_e32 v14, v0
	v_mov_b32_e32 v15, v0
	v_mov_b32_e32 v16, v0
	v_mov_b32_e32 v17, v0
	v_mov_b32_e32 v18, v0
	v_mov_b32_e32 v19, v0
	v_mov_b32_e32 v20, v0
	v_mov_b32_e32 v21, v0
	v_mov_b32_e32 v22, v0
	v_mov_b32_e32 v23, v0
	v_mov_b32_e32 v24, v0
	v_mov_b32_e32 v25, v0
	v_mov_b32_e32 v26, v0
	v_mov_b32_e32 v27, v0
	v_mov_b32_e32 v28, v0
	v_mov_b32_e32 v29, v0
	v_mov_b32_e32 v30, v0
	v_mov_b32_e32 v31, v0
	v_mov_b32_e32 v32, v0
	v_mov_b32_e32 v33, v0
	v_mov_b32_e32 v34, v0
	v_mov_b32_e32 v35, v0
	v_mov_b32_e32 v36, v0
	v_mov_b32_e32 v37, v0
	v_mov_b32_e32 v38, v0
	v_mov_b32_e32 v39, v0
	v_mov_b32_e32 v40, v0
	v_mov_b32_e32 v41, v0
	v_mov_b32_e32 v42, v0
	v_mov_b32_e32 v43, v0
	v_mov_b32_e32 v44, v0
	v_mov_b32_e32 v45, v0
	v_mov_b32_e32 v46, v0
	v_mov_b32_e32 v47, v0
	v_mov_b32_e32 v48, v0
	s_waitcnt vmcnt(0)
	v_mov_b32_e32 v49, v0
	v_mov_b32_e32 v50, v0
	v_mov_b32_e32 v51, v0
	v_mov_b32_e32 v52, v0
	v_mov_b32_e32 v53, v0
	v_mov_b32_e32 v54, v0
	v_mov_b32_e32 v55, v0
	v_mov_b32_e32 v56, v0
	v_mov_b32_e32 v57, v0
	v_mov_b32_e32 v58, v0
	v_mov_b32_e32 v59, v0
	v_mov_b32_e32 v60, v0
	v_mov_b32_e32 v61, v0
	v_mov_b32_e32 v62, v0
	v_mov_b32_e32 v63, v0
	v_mov_b32_e32 v64, v0
	v_mov_b32_e32 v65, v0
	v_mov_b32_e32 v66, v0
	v_mov_b32_e32 v67, v0
	v_mov_b32_e32 v68, v0
	v_mov_b32_e32 v69, v0
	v_mov_b32_e32 v70, v0
	v_mov_b32_e32 v71, v0
	v_mov_b32_e32 v72, v0
	v_mov_b32_e32 v73, v0
	v_mov_b32_e32 v74, v0
	v_mov_b32_e32 v75, v0
	v_mov_b32_e32 v76, v0
	v_mov_b32_e32 v77, v0
	v_mov_b32_e32 v78, v0
	v_mov_b32_e32 v79, v0
	v_mov_b32_e32 v80, v0
	v_mov_b32_e32 v81, v0
	v_mov_b32_e32 v82, v0
	v_mov_b32_e32 v83, v0
	v_mov_b32_e32 v84, v0
	v_mov_b32_e32 v85, v0
	v_mov_b32_e32 v86, v0
	v_mov_b32_e32 v87, v0
	v_mov_b32_e32 v88, v0
	v_mov_b32_e32 v89, v0
	v_mov_b32_e32 v90, v0
	v_mov_b32_e32 v91, v0
	v_mov_b32_e32 v92, v0
	v_mov_b32_e32 v93, v0
	v_mov_b32_e32 v94, v0
	v_mov_b32_e32 v95, v0
	v_xor_b32_e32 v159, 32, v157
	v_xor_b32_e32 v160, 64, v157
	v_xor_b32_e32 v161, 0x60, v157
	s_mov_b64 s[18:19], 0x80
	s_mov_b64 s[42:43], 0x10080
	v_add_u32_e32 v162, v155, v157
	v_add_u32_e32 v163, v155, v159
	v_add_u32_e32 v164, v155, v160
	v_add_u32_e32 v165, v155, v161
	v_add_u32_e32 v166, v156, v157
	v_add_u32_e32 v167, v156, v159
	v_add_u32_e32 v168, v156, v160
	v_add_u32_e32 v169, v156, v161
	v_add_u32_e32 v170, v158, v157
	v_add_u32_e32 v171, v158, v159
	v_add_u32_e32 v172, v158, v160
	v_add_u32_e32 v173, v158, v161
	v_lshl_add_u64 v[174:175], v[104:105], 0, v[100:101]
	v_lshl_add_u64 v[176:177], v[102:103], 0, v[100:101]
	v_readfirstlane_b32 s100, v124
	s_waitcnt vmcnt(0) lgkmcnt(0)
	s_barrier
	ds_read_b128 v[236:239], v166 offset:49152
	ds_read_b128 v[240:243], v166 offset:53248
	ds_read_b128 v[224:227], v162
	ds_read_b128 v[228:231], v162 offset:4096
	s_mov_b32 s15, 0

; template <int EPI, int MI>
; DI void gemm_tile(const GemmDesc& g, int tm, int tn, char* smem) {
;     ...
; #pragma unroll
;   for (int a = 0; a < MI; ++a)
; #pragma unroll
;     for (int b = 0; b < 2; ++b)
; #pragma unroll
;       for (int i = 0; i < 16; ++i) acc[a][b][i] = 0.f;
; template <int EPI, int MI>
; DI void gemm_phase(const GemmDesc& g, char* smem, int vb, int nvb) {
;     ...
;   for (int q = start; q < local; q += step) {
;     const int mg = q / per;
;     const int rem = q - mg * per;
;     const int tn = rem / PM;
;     const int tm = mbase + mg * PM + (rem - tn * PM);
;     gemm_tile<EPI, MI>(g, tm, tn, smem);
.LBB0_254:
	s_abs_i32 s0, s42
	v_readlane_b32 s1, v219, 48
	s_mul_hi_u32 s1, s0, s1
	v_readlane_b32 s17, v219, 47
	s_mul_i32 s4, s1, s17
	s_sub_i32 s0, s0, s4
	s_ashr_i32 s15, s42, 31
	s_add_i32 s4, s1, 1
	s_sub_i32 s5, s0, s17
	s_cmp_ge_u32 s0, s17
	s_cselect_b32 s1, s4, s1
	s_cselect_b32 s0, s5, s0
	s_add_i32 s4, s1, 1
	s_cmp_ge_u32 s0, s17
	s_cselect_b32 s0, s4, s1
	s_xor_b32 s16, s0, s15
	s_sub_i32 s0, s16, s15
	s_mul_i32 s1, s0, s17
	s_sub_i32 s1, s42, s1
	s_abs_i32 s4, s1
	v_readlane_b32 s5, v219, 46
	s_mul_hi_u32 s5, s4, s5
	v_readlane_b32 s43, v218, 32
	s_mul_i32 s18, s5, s43
	s_sub_i32 s4, s4, s18
	s_ashr_i32 s17, s1, 31
	s_add_i32 s18, s5, 1
	s_sub_i32 s19, s4, s43
	s_cmp_ge_u32 s4, s43
	s_cselect_b32 s5, s18, s5
	s_cselect_b32 s4, s19, s4
	s_add_i32 s18, s5, 1
	s_cmp_ge_u32 s4, s43
	s_cselect_b32 s4, s18, s5
	s_xor_b32 s18, s4, s17
	v_mov_b32_e32 v97, v132
	s_sub_i32 s4, s18, s17
	s_mul_i32 s0, s0, s43
	v_ashrrev_i32_e32 v6, 3, v97
	s_mul_i32 s5, s4, s43
	s_waitcnt vmcnt(8)
	v_ashrrev_i32_e32 v109, 7, v97
	v_bfe_u32 v1, v97, 6, 2
	v_xor_b32_e32 v2, v6, v97
	s_add_i32 s0, s0, s54
	s_sub_i32 s1, s1, s5
	v_and_b32_e32 v108, 31, v97
	v_bitop3_b32 v2, v2, v1, 7 bitop3:0x6c
	v_mul_lo_u32 v1, v109, s6
	s_add_i32 s1, s0, s1
	s_lshl_b32 s0, s4, 7
	v_and_b32_e32 v0, 7, v97
	v_or_b32_e32 v7, v1, v108
	v_lshrrev_b32_e32 v1, 3, v97
	v_readlane_b32 s4, v221, 5
	s_mul_i32 s43, s1, 0xc0
	v_bfe_u32 v115, v97, 5, 1
	v_bitop3_b32 v0, v1, v0, 3 bitop3:0x6c
	v_readlane_b32 s5, v221, 6
	v_xor_b32_e32 v8, v0, v115
	v_add_u32_e32 v3, s43, v6
	v_mov_b64_e32 v[0:1], s[4:5]
	s_movk_i32 s19, 0x1600
	v_mad_i64_i32 v[0:1], s[4:5], v3, s19, v[0:1]
	v_readlane_b32 s4, v221, 10
	v_readlane_b32 s5, v221, 11
	v_lshlrev_b32_e32 v98, 4, v2
	v_add_u32_e32 v9, s0, v6
	v_mov_b64_e32 v[2:3], s[4:5]
	v_lshlrev_b32_e32 v120, 4, v97
	v_mad_i64_i32 v[2:3], s[4:5], v9, s19, v[2:3]
	v_add_u32_e32 v121, 0, v120
	v_mov_b32_e32 v99, v96
	v_readfirstlane_b32 s4, v121
	v_add_u32_e32 v122, 0x1000, v121
	v_lshl_add_u64 v[0:1], v[0:1], 0, v[98:99]
	s_mov_b32 m0, s4
	s_mov_b64 s[44:45], 0x2c000
	v_readfirstlane_b32 s4, v122
	v_add_u32_e32 v123, 0x2000, v121
	global_load_lds_dwordx4 v[0:1], off
	v_lshl_add_u64 v[4:5], v[0:1], 0, s[44:45]
	s_mov_b32 m0, s4
	s_mov_b64 s[46:47], 0x58000
	v_readfirstlane_b32 s4, v123
	v_add_u32_e32 v124, 0x3000, v121
	global_load_lds_dwordx4 v[4:5], off
	v_lshl_add_u64 v[4:5], v[0:1], 0, s[46:47]
	s_mov_b32 m0, s4
	s_mov_b64 s[52:53], 0x84000
	v_readfirstlane_b32 s4, v124
	global_load_lds_dwordx4 v[4:5], off
	v_lshl_add_u64 v[4:5], v[0:1], 0, s[52:53]
	s_mov_b32 m0, s4
	s_mov_b64 s[4:5], 0xb0000
	v_add_u32_e32 v125, 0x4000, v121
	global_load_lds_dwordx4 v[4:5], off
	v_lshl_add_u64 v[4:5], v[0:1], 0, s[4:5]
	v_readfirstlane_b32 s4, v125
	s_mov_b32 m0, s4
	s_mov_b64 s[4:5], 0xdc000
	v_add_u32_e32 v126, 0x5000, v121
	v_lshl_add_u64 v[0:1], v[0:1], 0, s[4:5]
	v_readfirstlane_b32 s4, v126
	v_add_u32_e32 v127, 0xc000, v121
	global_load_lds_dwordx4 v[4:5], off
	s_mov_b32 m0, s4
	v_readfirstlane_b32 s4, v127
	v_add_u32_e32 v128, 0xd000, v121
	global_load_lds_dwordx4 v[0:1], off
	v_lshl_add_u64 v[0:1], v[2:3], 0, v[98:99]
	s_mov_b32 m0, s4
	v_readfirstlane_b32 s4, v128
	v_add_u32_e32 v129, 0xe000, v121
	global_load_lds_dwordx4 v[0:1], off
	v_lshl_add_u64 v[2:3], v[0:1], 0, s[44:45]
	s_mov_b32 m0, s4
	v_readfirstlane_b32 s4, v129
	v_add_u32_e32 v130, 0xf000, v121
	global_load_lds_dwordx4 v[2:3], off
	v_lshl_add_u64 v[2:3], v[0:1], 0, s[46:47]
	s_mov_b32 m0, s4
	v_readfirstlane_b32 s4, v130
	global_load_lds_dwordx4 v[2:3], off
	v_lshl_add_u64 v[0:1], v[0:1], 0, s[52:53]
	s_mov_b32 m0, s4
	s_mul_i32 s15, s15, 7
	global_load_lds_dwordx4 v[0:1], off
	s_add_i32 s17, s17, s15
	s_sub_i32 s4, s17, s18
	s_mul_i32 s16, s16, 7
	s_sub_i32 s4, s4, s16
	v_readlane_b32 s5, v218, 33
	v_lshlrev_b32_e32 v0, 7, v97
	s_mul_i32 s4, s5, s4
	v_and_b32_e32 v0, 0x2f80, v0
	s_add_i32 s4, s4, s39
	s_waitcnt vmcnt(0)
	v_add_u32_e32 v153, 0, v0
	v_add_u32_e32 v155, s10, v0
	v_add_u32_e32 v2, s4, v6
	v_mov_b64_e32 v[0:1], s[70:71]
	v_lshlrev_b32_e32 v154, 4, v8
	v_mad_i64_i32 v[100:101], s[4:5], v2, s19, v[0:1]
	v_mad_i64_i32 v[102:103], s[4:5], v9, s19, v[0:1]
	v_mov_b32_e32 v0, 0
	v_lshl_add_u32 v131, v7, 7, 0
	v_xor_b32_e32 v156, 32, v154
	v_xor_b32_e32 v157, 64, v154
	v_xor_b32_e32 v158, 0x60, v154
	s_mov_b32 s15, 0
	v_mov_b32_e32 v1, v0
	v_mov_b32_e32 v2, v0
	v_mov_b32_e32 v3, v0
	v_mov_b32_e32 v4, v0
	v_mov_b32_e32 v5, v0
	v_mov_b32_e32 v6, v0
	v_mov_b32_e32 v7, v0
	v_mov_b32_e32 v8, v0
	v_mov_b32_e32 v9, v0
	v_mov_b32_e32 v10, v0
	v_mov_b32_e32 v11, v0
	v_mov_b32_e32 v12, v0
	v_mov_b32_e32 v13, v0
	v_mov_b32_e32 v14, v0
	v_mov_b32_e32 v15, v0
	v_mov_b32_e32 v16, v0
	v_mov_b32_e32 v17, v0
	v_mov_b32_e32 v18, v0
	v_mov_b32_e32 v19, v0
	v_mov_b32_e32 v20, v0
	v_mov_b32_e32 v21, v0
	v_mov_b32_e32 v22, v0
	v_mov_b32_e32 v23, v0
	v_mov_b32_e32 v24, v0
	v_mov_b32_e32 v25, v0
	v_mov_b32_e32 v26, v0
	v_mov_b32_e32 v27, v0
	v_mov_b32_e32 v28, v0
	v_mov_b32_e32 v29, v0
	v_mov_b32_e32 v30, v0
	v_mov_b32_e32 v31, v0
	v_mov_b32_e32 v32, v0
	v_mov_b32_e32 v33, v0
	v_mov_b32_e32 v34, v0
	v_mov_b32_e32 v35, v0
	v_mov_b32_e32 v36, v0
	v_mov_b32_e32 v37, v0
	v_mov_b32_e32 v38, v0
	v_mov_b32_e32 v39, v0
	v_mov_b32_e32 v40, v0
	v_mov_b32_e32 v41, v0
	v_mov_b32_e32 v42, v0
	v_mov_b32_e32 v43, v0
	v_mov_b32_e32 v44, v0
	v_mov_b32_e32 v45, v0
	v_mov_b32_e32 v46, v0
	v_mov_b32_e32 v47, v0
	v_mov_b32_e32 v48, v0
	s_waitcnt vmcnt(0)
; template <int EPI, int MI>
; DI void gemm_tile(const GemmDesc& g, int tm, int tn, char* smem) {
;     ...
;   const int nk = g.K >> 6;
;   f32x16 acc[MI][2];
; #pragma unroll
;   for (int a = 0; a < MI; ++a)
; #pragma unroll
;     for (int b = 0; b < 2; ++b)
; #pragma unroll
;       for (int i = 0; i < 16; ++i) acc[a][b][i] = 0.f;
;     ...
;   G_GLDS(0, 0);
;   asm volatile("s_waitcnt vmcnt(0)" ::: "memory");
;   __syncthreads();
;   for (int kt = 0; kt < nk; kt += 2) {
;     if (kt + 1 < nk) G_GLDS(kt + 1, 1);
;     G_COMPUTE(0);
;     asm volatile("s_waitcnt vmcnt(0)" ::: "memory");
;     __syncthreads();
;     if (kt + 1 < nk) {
;       if (kt + 2 < nk) G_GLDS(kt + 2, 0);
;       G_COMPUTE(1);
;       asm volatile("s_waitcnt vmcnt(0)" ::: "memory");
;       __syncthreads();
;     }
;   }
	v_mov_b32_e32 v49, v0
	v_mov_b32_e32 v50, v0
	v_mov_b32_e32 v51, v0
	v_mov_b32_e32 v52, v0
	v_mov_b32_e32 v53, v0
	v_mov_b32_e32 v54, v0
	v_mov_b32_e32 v55, v0
	v_mov_b32_e32 v56, v0
	v_mov_b32_e32 v57, v0
	v_mov_b32_e32 v58, v0
	v_mov_b32_e32 v59, v0
	v_mov_b32_e32 v60, v0
	v_mov_b32_e32 v61, v0
	v_mov_b32_e32 v62, v0
	v_mov_b32_e32 v63, v0
	v_mov_b32_e32 v64, v0
	v_mov_b32_e32 v65, v0
	v_mov_b32_e32 v66, v0
	v_mov_b32_e32 v67, v0
	v_mov_b32_e32 v68, v0
	v_mov_b32_e32 v69, v0
	v_mov_b32_e32 v70, v0
	v_mov_b32_e32 v71, v0
	v_mov_b32_e32 v72, v0
	v_mov_b32_e32 v73, v0
	v_mov_b32_e32 v74, v0
	v_mov_b32_e32 v75, v0
	v_mov_b32_e32 v76, v0
	v_mov_b32_e32 v77, v0
	v_mov_b32_e32 v78, v0
	v_mov_b32_e32 v79, v0
	v_mov_b32_e32 v80, v0
	v_mov_b32_e32 v81, v0
	v_mov_b32_e32 v82, v0
	v_mov_b32_e32 v83, v0
	v_mov_b32_e32 v84, v0
	v_mov_b32_e32 v85, v0
	v_mov_b32_e32 v86, v0
	v_mov_b32_e32 v87, v0
	v_mov_b32_e32 v88, v0
	v_mov_b32_e32 v89, v0
	v_mov_b32_e32 v90, v0
	v_mov_b32_e32 v91, v0
	v_mov_b32_e32 v92, v0
	v_mov_b32_e32 v93, v0
	v_mov_b32_e32 v94, v0
	v_mov_b32_e32 v95, v0
	v_add_u32_e32 v162, v131, v154
	v_add_u32_e32 v163, v131, v156
	v_add_u32_e32 v164, v131, v157
	v_add_u32_e32 v165, v131, v158
	v_add_u32_e32 v166, v153, v154
	v_add_u32_e32 v167, v153, v156
	v_add_u32_e32 v168, v153, v157
	v_add_u32_e32 v169, v153, v158
	v_add_u32_e32 v170, v155, v154
	v_add_u32_e32 v171, v155, v156
	v_add_u32_e32 v172, v155, v157
	v_add_u32_e32 v173, v155, v158
	v_lshl_add_u64 v[252:253], v[100:101], 0, v[98:99]
	v_lshl_add_u64 v[254:255], v[102:103], 0, v[98:99]
	v_readfirstlane_b32 s100, v121
	s_mov_b64 s[4:5], 0x80
	s_waitcnt vmcnt(0) lgkmcnt(0)
	s_barrier
	ds_read_b128 v[236:239], v166 offset:49152
	ds_read_b128 v[240:243], v166 offset:53248
	ds_read_b128 v[224:227], v162
	ds_read_b128 v[228:231], v162 offset:4096
	s_mov_b32 s15, 0
.Lgd_loop:
	ds_read_b128 v[232:235], v162 offset:8192
	s_waitcnt lgkmcnt(2)
	v_mfma_f32_32x32x16_bf16 v[80:95], v[224:227], v[236:239], v[80:95]
	v_mfma_f32_32x32x16_bf16 v[64:79], v[224:227], v[240:243], v[64:79]
	s_mov_b64 s[16:17], 0x5872080
	s_add_u32 m0, s100, 0x6000
	v_lshl_add_u64 v[106:107], v[252:253], 0, s[16:17]
	global_load_lds_dwordx4 v[106:107], off
	ds_read_b128 v[244:247], v167 offset:49152
	ds_read_b128 v[248:251], v167 offset:53248
	ds_read_b128 v[224:227], v163
	s_waitcnt lgkmcnt(4)
	v_mfma_f32_32x32x16_bf16 v[48:63], v[228:231], v[236:239], v[48:63]
	v_mfma_f32_32x32x16_bf16 v[32:47], v[228:231], v[240:243], v[32:47]
	s_mov_b64 s[16:17], 0x589e080
	s_add_u32 m0, s100, 0x7000
	v_lshl_add_u64 v[106:107], v[252:253], 0, s[16:17]
	global_load_lds_dwordx4 v[106:107], off
	ds_read_b128 v[228:231], v163 offset:4096
	s_waitcnt lgkmcnt(4)
	v_mfma_f32_32x32x16_bf16 v[16:31], v[232:235], v[236:239], v[16:31]
	v_mfma_f32_32x32x16_bf16 v[0:15], v[232:235], v[240:243], v[0:15]
	s_mov_b64 s[16:17], 0x58ca080
	s_add_u32 m0, s100, 0x8000
	v_lshl_add_u64 v[106:107], v[252:253], 0, s[16:17]
	global_load_lds_dwordx4 v[106:107], off
	ds_read_b128 v[232:235], v163 offset:8192
	s_waitcnt lgkmcnt(2)
	v_mfma_f32_32x32x16_bf16 v[80:95], v[224:227], v[244:247], v[80:95]
	v_mfma_f32_32x32x16_bf16 v[64:79], v[224:227], v[248:251], v[64:79]
	s_mov_b64 s[16:17], 0x58f6080
	s_add_u32 m0, s100, 0x9000
	v_lshl_add_u64 v[106:107], v[252:253], 0, s[16:17]
	global_load_lds_dwordx4 v[106:107], off
	ds_read_b128 v[236:239], v168 offset:49152
	ds_read_b128 v[240:243], v168 offset:53248
	ds_read_b128 v[224:227], v164
	s_waitcnt lgkmcnt(4)
	v_mfma_f32_32x32x16_bf16 v[48:63], v[228:231], v[244:247], v[48:63]
	v_mfma_f32_32x32x16_bf16 v[32:47], v[228:231], v[248:251], v[32:47]
	s_mov_b64 s[16:17], 0x5922080
	s_add_u32 m0, s100, 0xa000
	v_lshl_add_u64 v[106:107], v[252:253], 0, s[16:17]
	global_load_lds_dwordx4 v[106:107], off
	ds_read_b128 v[228:231], v164 offset:4096
	s_waitcnt lgkmcnt(4)
	v_mfma_f32_32x32x16_bf16 v[16:31], v[232:235], v[244:247], v[16:31]
	v_mfma_f32_32x32x16_bf16 v[0:15], v[232:235], v[248:251], v[0:15]
	s_mov_b64 s[16:17], 0x594e080
	s_add_u32 m0, s100, 0xb000
	v_lshl_add_u64 v[106:107], v[252:253], 0, s[16:17]
	global_load_lds_dwordx4 v[106:107], off
	v_lshl_add_u64 v[252:253], v[252:253], 0, s[4:5]
	ds_read_b128 v[232:235], v164 offset:8192
	s_waitcnt lgkmcnt(2)
	v_mfma_f32_32x32x16_bf16 v[80:95], v[224:227], v[236:239], v[80:95]
	v_mfma_f32_32x32x16_bf16 v[64:79], v[224:227], v[240:243], v[64:79]
	s_mov_b64 s[16:17], 0x1600080
	s_add_u32 m0, s100, 0x10000
	v_lshl_add_u64 v[106:107], v[254:255], 0, s[16:17]
	global_load_lds_dwordx4 v[106:107], off
	ds_read_b128 v[244:247], v169 offset:49152
	ds_read_b128 v[248:251], v169 offset:53248
	ds_read_b128 v[224:227], v165
	s_waitcnt lgkmcnt(4)
	v_mfma_f32_32x32x16_bf16 v[48:63], v[228:231], v[236:239], v[48:63]
	v_mfma_f32_32x32x16_bf16 v[32:47], v[228:231], v[240:243], v[32:47]
	s_mov_b64 s[16:17], 0x162c080
	s_add_u32 m0, s100, 0x11000
	v_lshl_add_u64 v[106:107], v[254:255], 0, s[16:17]
	global_load_lds_dwordx4 v[106:107], off
	ds_read_b128 v[228:231], v165 offset:4096
	s_waitcnt lgkmcnt(4)
	v_mfma_f32_32x32x16_bf16 v[16:31], v[232:235], v[236:239], v[16:31]
	v_mfma_f32_32x32x16_bf16 v[0:15], v[232:235], v[240:243], v[0:15]
	s_mov_b64 s[16:17], 0x1658080
	s_add_u32 m0, s100, 0x12000
	v_lshl_add_u64 v[106:107], v[254:255], 0, s[16:17]
	global_load_lds_dwordx4 v[106:107], off
	ds_read_b128 v[232:235], v165 offset:8192
	s_waitcnt lgkmcnt(2)
	v_mfma_f32_32x32x16_bf16 v[80:95], v[224:227], v[244:247], v[80:95]
	v_mfma_f32_32x32x16_bf16 v[64:79], v[224:227], v[248:251], v[64:79]
	s_mov_b64 s[16:17], 0x1684080
	s_add_u32 m0, s100, 0x13000
	v_lshl_add_u64 v[106:107], v[254:255], 0, s[16:17]
	global_load_lds_dwordx4 v[106:107], off
	v_lshl_add_u64 v[254:255], v[254:255], 0, s[4:5]
	s_waitcnt lgkmcnt(0)
	s_waitcnt vmcnt(0)
	s_barrier
; template <int EPI, int MI>
; DI void gemm_tile(const GemmDesc& g, int tm, int tn, char* smem) {
;     ...
;   for (int kt = 0; kt < nk; kt += 2) {
;     if (kt + 1 < nk) G_GLDS(kt + 1, 1);
;     G_COMPUTE(0);
;     asm volatile("s_waitcnt vmcnt(0)" ::: "memory");
;     __syncthreads();
;     if (kt + 1 < nk) {
;       if (kt + 2 < nk) G_GLDS(kt + 2, 0);
;       G_COMPUTE(1);
;       asm volatile("s_waitcnt vmcnt(0)" ::: "memory");
;       __syncthreads();
;     }
;   }
	ds_read_b128 v[236:239], v170
	ds_read_b128 v[240:243], v170 offset:4096
	ds_read_b128 v[224:227], v162 offset:24576
	v_mfma_f32_32x32x16_bf16 v[48:63], v[228:231], v[244:247], v[48:63]
	v_mfma_f32_32x32x16_bf16 v[32:47], v[228:231], v[248:251], v[32:47]
	ds_read_b128 v[228:231], v162 offset:28672
	v_mfma_f32_32x32x16_bf16 v[16:31], v[232:235], v[244:247], v[16:31]
	v_mfma_f32_32x32x16_bf16 v[0:15], v[232:235], v[248:251], v[0:15]
	s_cmp_eq_u32 s15, 42
	s_cbranch_scc1 .Lgd_last
	ds_read_b128 v[232:235], v162 offset:32768
	s_waitcnt lgkmcnt(2)
	v_mfma_f32_32x32x16_bf16 v[80:95], v[224:227], v[236:239], v[80:95]
	v_mfma_f32_32x32x16_bf16 v[64:79], v[224:227], v[240:243], v[64:79]
	s_mov_b64 s[16:17], 0x5872080
	s_mov_b32 m0, s100
	v_lshl_add_u64 v[106:107], v[252:253], 0, s[16:17]
	global_load_lds_dwordx4 v[106:107], off
	ds_read_b128 v[244:247], v171
	ds_read_b128 v[248:251], v171 offset:4096
	ds_read_b128 v[224:227], v163 offset:24576
	s_waitcnt lgkmcnt(4)
	v_mfma_f32_32x32x16_bf16 v[48:63], v[228:231], v[236:239], v[48:63]
	v_mfma_f32_32x32x16_bf16 v[32:47], v[228:231], v[240:243], v[32:47]
	s_mov_b64 s[16:17], 0x589e080
	s_add_u32 m0, s100, 0x1000
	v_lshl_add_u64 v[106:107], v[252:253], 0, s[16:17]
	global_load_lds_dwordx4 v[106:107], off
	ds_read_b128 v[228:231], v163 offset:28672
	s_waitcnt lgkmcnt(4)
	v_mfma_f32_32x32x16_bf16 v[16:31], v[232:235], v[236:239], v[16:31]
	v_mfma_f32_32x32x16_bf16 v[0:15], v[232:235], v[240:243], v[0:15]
	s_mov_b64 s[16:17], 0x58ca080
	s_add_u32 m0, s100, 0x2000
	v_lshl_add_u64 v[106:107], v[252:253], 0, s[16:17]
	global_load_lds_dwordx4 v[106:107], off
	ds_read_b128 v[232:235], v163 offset:32768
	s_waitcnt lgkmcnt(2)
	v_mfma_f32_32x32x16_bf16 v[80:95], v[224:227], v[244:247], v[80:95]
	v_mfma_f32_32x32x16_bf16 v[64:79], v[224:227], v[248:251], v[64:79]
	s_mov_b64 s[16:17], 0x58f6080
	s_add_u32 m0, s100, 0x3000
	v_lshl_add_u64 v[106:107], v[252:253], 0, s[16:17]
	global_load_lds_dwordx4 v[106:107], off
	ds_read_b128 v[236:239], v172
	ds_read_b128 v[240:243], v172 offset:4096
	ds_read_b128 v[224:227], v164 offset:24576
	s_waitcnt lgkmcnt(4)
	v_mfma_f32_32x32x16_bf16 v[48:63], v[228:231], v[244:247], v[48:63]
	v_mfma_f32_32x32x16_bf16 v[32:47], v[228:231], v[248:251], v[32:47]
	s_mov_b64 s[16:17], 0x5922080
	s_add_u32 m0, s100, 0x4000
	v_lshl_add_u64 v[106:107], v[252:253], 0, s[16:17]
	global_load_lds_dwordx4 v[106:107], off
	ds_read_b128 v[228:231], v164 offset:28672
	s_waitcnt lgkmcnt(4)
	v_mfma_f32_32x32x16_bf16 v[16:31], v[232:235], v[244:247], v[16:31]
	v_mfma_f32_32x32x16_bf16 v[0:15], v[232:235], v[248:251], v[0:15]
	s_mov_b64 s[16:17], 0x594e080
	s_add_u32 m0, s100, 0x5000
	v_lshl_add_u64 v[106:107], v[252:253], 0, s[16:17]
	global_load_lds_dwordx4 v[106:107], off
	v_lshl_add_u64 v[252:253], v[252:253], 0, s[4:5]
	ds_read_b128 v[232:235], v164 offset:32768
	s_waitcnt lgkmcnt(2)
	v_mfma_f32_32x32x16_bf16 v[80:95], v[224:227], v[236:239], v[80:95]
	v_mfma_f32_32x32x16_bf16 v[64:79], v[224:227], v[240:243], v[64:79]
	s_mov_b64 s[16:17], 0x1600080
	s_add_u32 m0, s100, 0xc000
	v_lshl_add_u64 v[106:107], v[254:255], 0, s[16:17]
	global_load_lds_dwordx4 v[106:107], off
	ds_read_b128 v[244:247], v173
	ds_read_b128 v[248:251], v173 offset:4096
	ds_read_b128 v[224:227], v165 offset:24576
	s_waitcnt lgkmcnt(4)
	v_mfma_f32_32x32x16_bf16 v[48:63], v[228:231], v[236:239], v[48:63]
	v_mfma_f32_32x32x16_bf16 v[32:47], v[228:231], v[240:243], v[32:47]
	s_mov_b64 s[16:17], 0x162c080
	s_add_u32 m0, s100, 0xd000
	v_lshl_add_u64 v[106:107], v[254:255], 0, s[16:17]
	global_load_lds_dwordx4 v[106:107], off
	ds_read_b128 v[228:231], v165 offset:28672
	s_waitcnt lgkmcnt(4)
	v_mfma_f32_32x32x16_bf16 v[16:31], v[232:235], v[236:239], v[16:31]
	v_mfma_f32_32x32x16_bf16 v[0:15], v[232:235], v[240:243], v[0:15]
	s_mov_b64 s[16:17], 0x1658080
	s_add_u32 m0, s100, 0xe000
	v_lshl_add_u64 v[106:107], v[254:255], 0, s[16:17]
	global_load_lds_dwordx4 v[106:107], off
	ds_read_b128 v[232:235], v165 offset:32768
	s_waitcnt lgkmcnt(2)
	v_mfma_f32_32x32x16_bf16 v[80:95], v[224:227], v[244:247], v[80:95]
	v_mfma_f32_32x32x16_bf16 v[64:79], v[224:227], v[248:251], v[64:79]
	s_mov_b64 s[16:17], 0x1684080
	s_add_u32 m0, s100, 0xf000
	v_lshl_add_u64 v[106:107], v[254:255], 0, s[16:17]
	global_load_lds_dwordx4 v[106:107], off
	v_lshl_add_u64 v[254:255], v[254:255], 0, s[4:5]
	s_waitcnt lgkmcnt(0)
	s_waitcnt vmcnt(0)
	s_barrier
	ds_read_b128 v[236:239], v166 offset:49152
	ds_read_b128 v[240:243], v166 offset:53248
	ds_read_b128 v[224:227], v162
	v_mfma_f32_32x32x16_bf16 v[48:63], v[228:231], v[244:247], v[48:63]
	v_mfma_f32_32x32x16_bf16 v[32:47], v[228:231], v[248:251], v[32:47]
	ds_read_b128 v[228:231], v162 offset:4096
	v_mfma_f32_32x32x16_bf16 v[16:31], v[232:235], v[244:247], v[16:31]
	v_mfma_f32_32x32x16_bf16 v[0:15], v[232:235], v[248:251], v[0:15]
	s_add_u32 s15, s15, 2
	s_branch .Lgd_loop
; template <int EPI, int MI>
; DI void gemm_tile(const GemmDesc& g, int tm, int tn, char* smem) {
;     ...
;   for (int kt = 0; kt < nk; kt += 2) {
;     if (kt + 1 < nk) G_GLDS(kt + 1, 1);
;     G_COMPUTE(0);
;     asm volatile("s_waitcnt vmcnt(0)" ::: "memory");
;     __syncthreads();
;     if (kt + 1 < nk) {
;       if (kt + 2 < nk) G_GLDS(kt + 2, 0);
;       G_COMPUTE(1);
;       asm volatile("s_waitcnt vmcnt(0)" ::: "memory");
;       __syncthreads();
;     }
;   }
;     ...
;     float* es = (float*)smem;
;     const int c4 = (tid & 31) * 4;
;     const int rgA = m0 < LAT ? (m0 >> 11) : 8;
;     const int mlast = m0 + BM - 1;
;     const int rgB = mlast < LAT ? (mlast >> 11) : 8;
;     const f32x4v m4a = *(const f32x4v*)(g.mod + (size_t)rgA * 9216 + g.gidx * 1024 + n0 + c4);
;     const f32x4v m4b = *(const f32x4v*)(g.mod + (size_t)rgB * 9216 + g.gidx * 1024 + n0 + c4);
; #pragma unroll
;     for (int mi = 0; mi < MI; ++mi) {
; #pragma unroll
;       for (int ni = 0; ni < 2; ++ni)
; #pragma unroll
;         for (int i = 0; i < 16; ++i) {
;           const int lrow = wm * 32 + (i & 3) + 8 * (i >> 2) + 4 * hh;
;           es[lrow * 128 + wn * 64 + ni * 32 + r] = acc[mi][ni][i];
;         }
;       __syncthreads();
; #pragma unroll 4
;       for (int j = 0; j < 8; ++j) {
;         const int lrow = (tid >> 5) + 8 * j;
;         const int grow = m0 + (lrow >> 5) * (32 * MI) + mi * 32 + (lrow & 31);
;         const f32x4v a4 = *(const f32x4v*)(es + lrow * 128 + c4);
;         const int rg = grow < LAT ? (grow >> 11) : 8;
;         const f32x4v m4 = rg == rgA ? m4a : m4b;
;         float* rp = (grow < LAT ? g.xres + (size_t)grow * 1024 : g.hres + (size_t)(grow - LAT) * 1024) + n0 + c4;
;         f32x4v x4 = *(const f32x4v*)rp;
.Lgd_last:
	ds_read_b128 v[232:235], v162 offset:32768
	s_waitcnt lgkmcnt(2)
	v_mfma_f32_32x32x16_bf16 v[80:95], v[224:227], v[236:239], v[80:95]
	v_mfma_f32_32x32x16_bf16 v[64:79], v[224:227], v[240:243], v[64:79]
	ds_read_b128 v[244:247], v171
	ds_read_b128 v[248:251], v171 offset:4096
	ds_read_b128 v[224:227], v163 offset:24576
	s_waitcnt lgkmcnt(4)
	v_mfma_f32_32x32x16_bf16 v[48:63], v[228:231], v[236:239], v[48:63]
	v_mfma_f32_32x32x16_bf16 v[32:47], v[228:231], v[240:243], v[32:47]
	ds_read_b128 v[228:231], v163 offset:28672
	s_waitcnt lgkmcnt(4)
	v_mfma_f32_32x32x16_bf16 v[16:31], v[232:235], v[236:239], v[16:31]
	v_mfma_f32_32x32x16_bf16 v[0:15], v[232:235], v[240:243], v[0:15]
	ds_read_b128 v[232:235], v163 offset:32768
	s_waitcnt lgkmcnt(2)
	v_mfma_f32_32x32x16_bf16 v[80:95], v[224:227], v[244:247], v[80:95]
	v_mfma_f32_32x32x16_bf16 v[64:79], v[224:227], v[248:251], v[64:79]
	ds_read_b128 v[236:239], v172
	ds_read_b128 v[240:243], v172 offset:4096
	ds_read_b128 v[224:227], v164 offset:24576
	s_waitcnt lgkmcnt(4)
	v_mfma_f32_32x32x16_bf16 v[48:63], v[228:231], v[244:247], v[48:63]
	v_mfma_f32_32x32x16_bf16 v[32:47], v[228:231], v[248:251], v[32:47]
	ds_read_b128 v[228:231], v164 offset:28672
	s_waitcnt lgkmcnt(4)
	v_mfma_f32_32x32x16_bf16 v[16:31], v[232:235], v[244:247], v[16:31]
	v_mfma_f32_32x32x16_bf16 v[0:15], v[232:235], v[248:251], v[0:15]
	ds_read_b128 v[232:235], v164 offset:32768
	s_waitcnt lgkmcnt(2)
	v_mfma_f32_32x32x16_bf16 v[80:95], v[224:227], v[236:239], v[80:95]
	v_mfma_f32_32x32x16_bf16 v[64:79], v[224:227], v[240:243], v[64:79]
	ds_read_b128 v[244:247], v173
	ds_read_b128 v[248:251], v173 offset:4096
	ds_read_b128 v[224:227], v165 offset:24576
	s_waitcnt lgkmcnt(4)
	v_mfma_f32_32x32x16_bf16 v[48:63], v[228:231], v[236:239], v[48:63]
	v_mfma_f32_32x32x16_bf16 v[32:47], v[228:231], v[240:243], v[32:47]
	ds_read_b128 v[228:231], v165 offset:28672
	s_waitcnt lgkmcnt(4)
	v_mfma_f32_32x32x16_bf16 v[16:31], v[232:235], v[236:239], v[16:31]
	v_mfma_f32_32x32x16_bf16 v[0:15], v[232:235], v[240:243], v[0:15]
	ds_read_b128 v[232:235], v165 offset:32768
	s_waitcnt lgkmcnt(2)
	v_mfma_f32_32x32x16_bf16 v[80:95], v[224:227], v[244:247], v[80:95]
	v_mfma_f32_32x32x16_bf16 v[64:79], v[224:227], v[248:251], v[64:79]
	s_waitcnt lgkmcnt(0)
	s_barrier
	v_mfma_f32_32x32x16_bf16 v[48:63], v[228:231], v[244:247], v[48:63]
	v_mfma_f32_32x32x16_bf16 v[32:47], v[228:231], v[248:251], v[32:47]
	v_mfma_f32_32x32x16_bf16 v[16:31], v[232:235], v[244:247], v[16:31]
	v_mfma_f32_32x32x16_bf16 v[0:15], v[232:235], v[248:251], v[0:15]
	s_branch .LBB0_258
.LBB0_258:
	s_ashr_i32 s4, s43, 11
	s_cmpk_lt_i32 s1, 0x56
	s_cselect_b32 s15, s4, 8
	s_add_i32 s4, s43, 0xbf
	s_ashr_i32 s4, s4, 11
	s_cmpk_lt_i32 s1, 0x55
	s_cselect_b32 s16, s4, 8
	s_mul_i32 s4, s15, 0x9000
	s_mul_hi_i32 s1, s15, 0x9000
	s_add_u32 s17, s20, s4
	s_addc_u32 s18, s38, s1
	s_ashr_i32 s1, s0, 31
	v_lshlrev_b32_e32 v98, 2, v97
	s_lshl_b64 s[4:5], s[0:1], 2
	v_and_b32_e32 v106, 0x7c, v98
	s_add_u32 s0, s17, s4
	s_addc_u32 s1, s18, s5
	v_lshlrev_b32_e32 v102, 2, v106
	global_load_dwordx4 v[98:101], v102, s[0:1]
	s_mul_hi_i32 s0, s16, 0x9000
	s_mul_i32 s16, s16, 0x9000
	s_add_u32 s1, s20, s16
	s_addc_u32 s16, s38, s0
	s_add_u32 s0, s1, s4
	s_addc_u32 s1, s16, s5
	global_load_dwordx4 v[102:105], v102, s[0:1]
	v_and_b32_e32 v107, 64, v97
	v_lshlrev_b32_e32 v115, 11, v115
	v_lshlrev_b32_e32 v107, 2, v107
	v_lshlrev_b32_e32 v109, 14, v109
	v_add3_u32 v107, 0, v115, v107
	v_lshlrev_b32_e32 v115, 2, v108
	v_ashrrev_i32_e32 v97, 5, v97
	v_add3_u32 v107, v107, v115, v109
	ds_write2_b32 v107, v80, v64 offset1:32
	ds_write2_b32 v107, v81, v65 offset0:128 offset1:160
	v_add_u32_e32 v80, 0x400, v107
	v_add_u32_e32 v64, 8, v97
	ds_write2_b32 v80, v82, v66 offset1:32
	ds_write2_b32 v80, v83, v67 offset0:128 offset1:160
	v_add_u32_e32 v81, 0x1000, v107
	v_add_u32_e32 v82, 0x1400, v107
	v_and_b32_e32 v67, 31, v64
	v_add_u32_e32 v64, 24, v97
	ds_write2_b32 v81, v84, v68 offset1:32
	ds_write2_b32 v81, v85, v69 offset0:128 offset1:160
	ds_write2_b32 v82, v86, v70 offset1:32
	ds_write2_b32 v82, v87, v71 offset0:128 offset1:160
	v_add_u32_e32 v71, 0x2000, v107
	v_and_b32_e32 v69, 31, v64
	v_lshlrev_b32_e32 v64, 4, v108
	ds_write2_b32 v71, v88, v72 offset1:32
	ds_write2_b32 v71, v89, v73 offset0:128 offset1:160
	v_add_u32_e32 v72, 0x2400, v107
	v_lshl_or_b32 v64, v97, 9, v64
	ds_write2_b32 v72, v90, v74 offset1:32
	ds_write2_b32 v72, v91, v75 offset0:128 offset1:160
	v_add_u32_e32 v73, 0x3000, v107
	v_add_u32_e32 v74, 0x3400, v107
	v_and_b32_e32 v66, 31, v97
	v_bitop3_b32 v68, v97, 16, 31 bitop3:0x6c
	v_add_u32_e32 v70, 0, v64
	s_mov_b32 s16, 0
	v_mov_b32_e32 v75, v97
	ds_write2_b32 v73, v92, v76 offset1:32
	ds_write2_b32 v73, v93, v77 offset0:128 offset1:160
	ds_write2_b32 v74, v94, v78 offset1:32
	ds_write2_b32 v74, v95, v79 offset0:128 offset1:160
	v_lshlrev_b32_e32 v64, 2, v106
	v_mov_b32_e32 v65, 0
	s_mov_b32 s16, s43
	v_or_b32_e32 v224, s16, v66
	v_mov_b32_e32 v226, s68
	v_mov_b32_e32 v227, s69
	v_mov_b32_e32 v162, s3
	v_mov_b32_e32 v163, s33
	v_cmp_gt_i32_e32 vcc, s8, v224
	v_add_u32_e32 v225, 0xffffc000, v224
	s_nop 0
	v_cndmask_b32_e32 v224, v225, v224, vcc
	v_cndmask_b32_e32 v226, v162, v226, vcc
	v_cndmask_b32_e32 v227, v163, v227, vcc
	v_mov_b32_e32 v225, 0
	v_lshlrev_b64 v[224:225], 12, v[224:225]
	v_lshl_add_u64 v[224:225], v[226:227], 0, v[224:225]
	v_lshl_add_u64 v[224:225], v[224:225], 0, s[4:5]
	v_lshl_add_u64 v[162:163], v[224:225], 0, v[64:65]
	global_load_dwordx4 v[224:227], v[162:163], off
	v_or_b32_e32 v228, s16, v67
	v_mov_b32_e32 v230, s68
	v_mov_b32_e32 v231, s69
	v_mov_b32_e32 v164, s3
; template <int EPI, int MI>
; DI void gemm_tile(const GemmDesc& g, int tm, int tn, char* smem) {
;     ...
;       for (int j = 0; j < 8; ++j) {
;         const int lrow = (tid >> 5) + 8 * j;
;         const int grow = m0 + (lrow >> 5) * (32 * MI) + mi * 32 + (lrow & 31);
;         const f32x4v a4 = *(const f32x4v*)(es + lrow * 128 + c4);
;         const int rg = grow < LAT ? (grow >> 11) : 8;
;         const f32x4v m4 = rg == rgA ? m4a : m4b;
;         float* rp = (grow < LAT ? g.xres + (size_t)grow * 1024 : g.hres + (size_t)(grow - LAT) * 1024) + n0 + c4;
;         f32x4v x4 = *(const f32x4v*)rp;
;         x4 += (m4 * a4) * g.coef;
;         *(f32x4v*)rp = x4;
;       }
	v_mov_b32_e32 v165, s33
	v_cmp_gt_i32_e32 vcc, s8, v228
	v_add_u32_e32 v229, 0xffffc000, v228
	s_nop 0
	v_cndmask_b32_e32 v228, v229, v228, vcc
	v_cndmask_b32_e32 v230, v164, v230, vcc
	v_cndmask_b32_e32 v231, v165, v231, vcc
	v_mov_b32_e32 v229, 0
	v_lshlrev_b64 v[228:229], 12, v[228:229]
	v_lshl_add_u64 v[228:229], v[230:231], 0, v[228:229]
	v_lshl_add_u64 v[228:229], v[228:229], 0, s[4:5]
	v_lshl_add_u64 v[164:165], v[228:229], 0, v[64:65]
	global_load_dwordx4 v[228:231], v[164:165], off
	v_or_b32_e32 v232, s16, v68
	v_mov_b32_e32 v234, s68
	v_mov_b32_e32 v235, s69
	v_mov_b32_e32 v166, s3
	v_mov_b32_e32 v167, s33
	v_cmp_gt_i32_e32 vcc, s8, v232
	v_add_u32_e32 v233, 0xffffc000, v232
	s_nop 0
	v_cndmask_b32_e32 v232, v233, v232, vcc
	v_cndmask_b32_e32 v234, v166, v234, vcc
	v_cndmask_b32_e32 v235, v167, v235, vcc
	v_mov_b32_e32 v233, 0
	v_lshlrev_b64 v[232:233], 12, v[232:233]
	v_lshl_add_u64 v[232:233], v[234:235], 0, v[232:233]
	v_lshl_add_u64 v[232:233], v[232:233], 0, s[4:5]
	v_lshl_add_u64 v[166:167], v[232:233], 0, v[64:65]
	global_load_dwordx4 v[232:235], v[166:167], off
	v_or_b32_e32 v236, s16, v69
	v_mov_b32_e32 v238, s68
	v_mov_b32_e32 v239, s69
	v_mov_b32_e32 v168, s3
	v_mov_b32_e32 v169, s33
	v_cmp_gt_i32_e32 vcc, s8, v236
	v_add_u32_e32 v237, 0xffffc000, v236
	s_nop 0
	v_cndmask_b32_e32 v236, v237, v236, vcc
	v_cndmask_b32_e32 v238, v168, v238, vcc
	v_cndmask_b32_e32 v239, v169, v239, vcc
	v_mov_b32_e32 v237, 0
	v_lshlrev_b64 v[236:237], 12, v[236:237]
	v_lshl_add_u64 v[236:237], v[238:239], 0, v[236:237]
	v_lshl_add_u64 v[236:237], v[236:237], 0, s[4:5]
	v_lshl_add_u64 v[168:169], v[236:237], 0, v[64:65]
	global_load_dwordx4 v[236:239], v[168:169], off
	s_add_u32 s16, s43, 96
	v_or_b32_e32 v240, s16, v66
	v_mov_b32_e32 v242, s68
	v_mov_b32_e32 v243, s69
	v_mov_b32_e32 v170, s3
	v_mov_b32_e32 v171, s33
	v_cmp_gt_i32_e32 vcc, s8, v240
	v_add_u32_e32 v241, 0xffffc000, v240
	s_nop 0
	v_cndmask_b32_e32 v240, v241, v240, vcc
	v_cndmask_b32_e32 v242, v170, v242, vcc
	v_cndmask_b32_e32 v243, v171, v243, vcc
	v_mov_b32_e32 v241, 0
	v_lshlrev_b64 v[240:241], 12, v[240:241]
	v_lshl_add_u64 v[240:241], v[242:243], 0, v[240:241]
	v_lshl_add_u64 v[240:241], v[240:241], 0, s[4:5]
	v_lshl_add_u64 v[170:171], v[240:241], 0, v[64:65]
	global_load_dwordx4 v[240:243], v[170:171], off
	v_or_b32_e32 v244, s16, v67
	v_mov_b32_e32 v246, s68
	v_mov_b32_e32 v247, s69
	v_mov_b32_e32 v172, s3
	v_mov_b32_e32 v173, s33
	v_cmp_gt_i32_e32 vcc, s8, v244
	v_add_u32_e32 v245, 0xffffc000, v244
	s_nop 0
	v_cndmask_b32_e32 v244, v245, v244, vcc
	v_cndmask_b32_e32 v246, v172, v246, vcc
	v_cndmask_b32_e32 v247, v173, v247, vcc
	v_mov_b32_e32 v245, 0
	v_lshlrev_b64 v[244:245], 12, v[244:245]
	v_lshl_add_u64 v[244:245], v[246:247], 0, v[244:245]
	v_lshl_add_u64 v[244:245], v[244:245], 0, s[4:5]
	v_lshl_add_u64 v[172:173], v[244:245], 0, v[64:65]
	global_load_dwordx4 v[244:247], v[172:173], off
	v_or_b32_e32 v248, s16, v68
	v_mov_b32_e32 v250, s68
	v_mov_b32_e32 v251, s69
	v_mov_b32_e32 v174, s3
	v_mov_b32_e32 v175, s33
	v_cmp_gt_i32_e32 vcc, s8, v248
	v_add_u32_e32 v249, 0xffffc000, v248
	s_nop 0
	v_cndmask_b32_e32 v248, v249, v248, vcc
	v_cndmask_b32_e32 v250, v174, v250, vcc
	v_cndmask_b32_e32 v251, v175, v251, vcc
	v_mov_b32_e32 v249, 0
	v_lshlrev_b64 v[248:249], 12, v[248:249]
	v_lshl_add_u64 v[248:249], v[250:251], 0, v[248:249]
	v_lshl_add_u64 v[248:249], v[248:249], 0, s[4:5]
	v_lshl_add_u64 v[174:175], v[248:249], 0, v[64:65]
	global_load_dwordx4 v[248:251], v[174:175], off
	v_or_b32_e32 v252, s16, v69
	v_mov_b32_e32 v254, s68
	v_mov_b32_e32 v255, s69
	v_mov_b32_e32 v176, s3
	v_mov_b32_e32 v177, s33
	v_cmp_gt_i32_e32 vcc, s8, v252
	v_add_u32_e32 v253, 0xffffc000, v252
	s_nop 0
	v_cndmask_b32_e32 v252, v253, v252, vcc
	v_cndmask_b32_e32 v254, v176, v254, vcc
	v_cndmask_b32_e32 v255, v177, v255, vcc
	v_mov_b32_e32 v253, 0
	v_lshlrev_b64 v[252:253], 12, v[252:253]
	v_lshl_add_u64 v[252:253], v[254:255], 0, v[252:253]
	v_lshl_add_u64 v[252:253], v[252:253], 0, s[4:5]
	v_lshl_add_u64 v[176:177], v[252:253], 0, v[64:65]
	global_load_dwordx4 v[252:255], v[176:177], off
	s_waitcnt lgkmcnt(0)
	s_barrier
	s_waitcnt vmcnt(8)
	ds_read_b128 v[84:87], v70
	s_mov_b32 s16, s43
	s_ashr_i32 s17, s16, 11
	v_or_b32_e32 v88, s16, v66
	v_mov_b32_e32 v89, s17
	v_cmp_gt_i32_e32 vcc, s8, v88
	ds_read_b128 v[92:95], v70 offset:4096
	s_nop 0
	v_cndmask_b32_e32 v89, 8, v89, vcc
	v_cmp_eq_u32_e64 s[0:1], s15, v89
	s_nop 1
	v_cndmask_b32_e64 v89, v103, v99, s[0:1]
	v_cndmask_b32_e64 v88, v102, v98, s[0:1]
	v_cndmask_b32_e64 v91, v105, v101, s[0:1]
	v_cndmask_b32_e64 v90, v104, v100, s[0:1]
	s_waitcnt lgkmcnt(1)
	v_pk_mul_f32 v[86:87], v[86:87], v[90:91]
	v_pk_mul_f32 v[84:85], v[84:85], v[88:89]
	s_waitcnt vmcnt(7)
	v_pk_fma_f32 v[84:85], v[84:85], 0.5, v[224:225] op_sel_hi:[1,0,1]
	v_pk_fma_f32 v[86:87], v[86:87], 0.5, v[226:227] op_sel_hi:[1,0,1]
	global_store_dwordx4 v[162:163], v[84:87], off
	v_or_b32_e32 v88, s16, v67
	v_mov_b32_e32 v89, s17
	v_cmp_gt_i32_e32 vcc, s8, v88
	ds_read_b128 v[84:87], v70 offset:8192
	s_nop 0
	v_cndmask_b32_e32 v89, 8, v89, vcc
	v_cmp_eq_u32_e64 s[0:1], s15, v89
	s_nop 1
	v_cndmask_b32_e64 v89, v103, v99, s[0:1]
	v_cndmask_b32_e64 v88, v102, v98, s[0:1]
	v_cndmask_b32_e64 v91, v105, v101, s[0:1]
	v_cndmask_b32_e64 v90, v104, v100, s[0:1]
	s_waitcnt lgkmcnt(1)
	v_pk_mul_f32 v[94:95], v[94:95], v[90:91]
	v_pk_mul_f32 v[92:93], v[92:93], v[88:89]
	s_waitcnt vmcnt(7)
; template <int EPI, int MI>
; DI void gemm_tile(const GemmDesc& g, int tm, int tn, char* smem) {
;     ...
;       for (int j = 0; j < 8; ++j) {
;         const int lrow = (tid >> 5) + 8 * j;
;         const int grow = m0 + (lrow >> 5) * (32 * MI) + mi * 32 + (lrow & 31);
;         const f32x4v a4 = *(const f32x4v*)(es + lrow * 128 + c4);
;         const int rg = grow < LAT ? (grow >> 11) : 8;
;         const f32x4v m4 = rg == rgA ? m4a : m4b;
;         float* rp = (grow < LAT ? g.xres + (size_t)grow * 1024 : g.hres + (size_t)(grow - LAT) * 1024) + n0 + c4;
;         f32x4v x4 = *(const f32x4v*)rp;
;         x4 += (m4 * a4) * g.coef;
;         *(f32x4v*)rp = x4;
;       }
	v_pk_fma_f32 v[92:93], v[92:93], 0.5, v[228:229] op_sel_hi:[1,0,1]
	v_pk_fma_f32 v[94:95], v[94:95], 0.5, v[230:231] op_sel_hi:[1,0,1]
	global_store_dwordx4 v[164:165], v[92:95], off
	v_or_b32_e32 v88, s16, v68
	v_mov_b32_e32 v89, s17
	v_cmp_gt_i32_e32 vcc, s8, v88
	ds_read_b128 v[92:95], v70 offset:12288
	s_nop 0
	v_cndmask_b32_e32 v89, 8, v89, vcc
	v_cmp_eq_u32_e64 s[0:1], s15, v89
	s_nop 1
	v_cndmask_b32_e64 v89, v103, v99, s[0:1]
	v_cndmask_b32_e64 v88, v102, v98, s[0:1]
	v_cndmask_b32_e64 v91, v105, v101, s[0:1]
	v_cndmask_b32_e64 v90, v104, v100, s[0:1]
	s_waitcnt lgkmcnt(1)
	v_pk_mul_f32 v[86:87], v[86:87], v[90:91]
	v_pk_mul_f32 v[84:85], v[84:85], v[88:89]
	s_waitcnt vmcnt(7)
	v_pk_fma_f32 v[84:85], v[84:85], 0.5, v[232:233] op_sel_hi:[1,0,1]
	v_pk_fma_f32 v[86:87], v[86:87], 0.5, v[234:235] op_sel_hi:[1,0,1]
	global_store_dwordx4 v[166:167], v[84:87], off
	v_or_b32_e32 v88, s16, v69
	v_mov_b32_e32 v89, s17
	v_cmp_gt_i32_e32 vcc, s8, v88
	ds_read_b128 v[84:87], v70 offset:16384
	s_nop 0
	v_cndmask_b32_e32 v89, 8, v89, vcc
	v_cmp_eq_u32_e64 s[0:1], s15, v89
	s_nop 1
	v_cndmask_b32_e64 v89, v103, v99, s[0:1]
	v_cndmask_b32_e64 v88, v102, v98, s[0:1]
	v_cndmask_b32_e64 v91, v105, v101, s[0:1]
	v_cndmask_b32_e64 v90, v104, v100, s[0:1]
	s_waitcnt lgkmcnt(1)
	v_pk_mul_f32 v[94:95], v[94:95], v[90:91]
	v_pk_mul_f32 v[92:93], v[92:93], v[88:89]
	s_waitcnt vmcnt(7)
	v_pk_fma_f32 v[92:93], v[92:93], 0.5, v[236:237] op_sel_hi:[1,0,1]
	v_pk_fma_f32 v[94:95], v[94:95], 0.5, v[238:239] op_sel_hi:[1,0,1]
	global_store_dwordx4 v[168:169], v[92:95], off
	s_add_u32 s16, s43, 96
	s_ashr_i32 s17, s16, 11
	v_or_b32_e32 v88, s16, v66
	v_mov_b32_e32 v89, s17
	v_cmp_gt_i32_e32 vcc, s8, v88
	ds_read_b128 v[92:95], v70 offset:20480
	s_nop 0
	v_cndmask_b32_e32 v89, 8, v89, vcc
	v_cmp_eq_u32_e64 s[0:1], s15, v89
	s_nop 1
	v_cndmask_b32_e64 v89, v103, v99, s[0:1]
	v_cndmask_b32_e64 v88, v102, v98, s[0:1]
	v_cndmask_b32_e64 v91, v105, v101, s[0:1]
	v_cndmask_b32_e64 v90, v104, v100, s[0:1]
	s_waitcnt lgkmcnt(1)
	v_pk_mul_f32 v[86:87], v[86:87], v[90:91]
	v_pk_mul_f32 v[84:85], v[84:85], v[88:89]
	s_waitcnt vmcnt(7)
	v_pk_fma_f32 v[84:85], v[84:85], 0.5, v[240:241] op_sel_hi:[1,0,1]
	v_pk_fma_f32 v[86:87], v[86:87], 0.5, v[242:243] op_sel_hi:[1,0,1]
	global_store_dwordx4 v[170:171], v[84:87], off
	v_or_b32_e32 v88, s16, v67
	v_mov_b32_e32 v89, s17
	v_cmp_gt_i32_e32 vcc, s8, v88
	ds_read_b128 v[84:87], v70 offset:24576
	s_nop 0
	v_cndmask_b32_e32 v89, 8, v89, vcc
	v_cmp_eq_u32_e64 s[0:1], s15, v89
	s_nop 1
	v_cndmask_b32_e64 v89, v103, v99, s[0:1]
	v_cndmask_b32_e64 v88, v102, v98, s[0:1]
	v_cndmask_b32_e64 v91, v105, v101, s[0:1]
	v_cndmask_b32_e64 v90, v104, v100, s[0:1]
	s_waitcnt lgkmcnt(1)
	v_pk_mul_f32 v[94:95], v[94:95], v[90:91]
	v_pk_mul_f32 v[92:93], v[92:93], v[88:89]
	s_waitcnt vmcnt(7)
	v_pk_fma_f32 v[92:93], v[92:93], 0.5, v[244:245] op_sel_hi:[1,0,1]
	v_pk_fma_f32 v[94:95], v[94:95], 0.5, v[246:247] op_sel_hi:[1,0,1]
	global_store_dwordx4 v[172:173], v[92:95], off
	v_or_b32_e32 v88, s16, v68
	v_mov_b32_e32 v89, s17
	v_cmp_gt_i32_e32 vcc, s8, v88
	ds_read_b128 v[92:95], v70 offset:28672
	s_nop 0
	v_cndmask_b32_e32 v89, 8, v89, vcc
	v_cmp_eq_u32_e64 s[0:1], s15, v89
	s_nop 1
	v_cndmask_b32_e64 v89, v103, v99, s[0:1]
	v_cndmask_b32_e64 v88, v102, v98, s[0:1]
	v_cndmask_b32_e64 v91, v105, v101, s[0:1]
	v_cndmask_b32_e64 v90, v104, v100, s[0:1]
	s_waitcnt lgkmcnt(1)
	v_pk_mul_f32 v[86:87], v[86:87], v[90:91]
	v_pk_mul_f32 v[84:85], v[84:85], v[88:89]
	s_waitcnt vmcnt(7)
	v_pk_fma_f32 v[84:85], v[84:85], 0.5, v[248:249] op_sel_hi:[1,0,1]
	v_pk_fma_f32 v[86:87], v[86:87], 0.5, v[250:251] op_sel_hi:[1,0,1]
	global_store_dwordx4 v[174:175], v[84:87], off
	v_or_b32_e32 v88, s16, v69
	v_mov_b32_e32 v89, s17
	v_cmp_gt_i32_e32 vcc, s8, v88
	s_nop 1
	v_cndmask_b32_e32 v89, 8, v89, vcc
	v_cmp_eq_u32_e64 s[0:1], s15, v89
	s_nop 1
	v_cndmask_b32_e64 v89, v103, v99, s[0:1]
	v_cndmask_b32_e64 v88, v102, v98, s[0:1]
	v_cndmask_b32_e64 v91, v105, v101, s[0:1]
	v_cndmask_b32_e64 v90, v104, v100, s[0:1]
	s_waitcnt lgkmcnt(0)
	v_pk_mul_f32 v[94:95], v[94:95], v[90:91]
	v_pk_mul_f32 v[92:93], v[92:93], v[88:89]
	s_waitcnt vmcnt(7)
	v_pk_fma_f32 v[92:93], v[92:93], 0.5, v[252:253] op_sel_hi:[1,0,1]
	v_pk_fma_f32 v[94:95], v[94:95], 0.5, v[254:255] op_sel_hi:[1,0,1]
	global_store_dwordx4 v[176:177], v[92:95], off
	s_add_u32 s16, s43, 32
	v_or_b32_e32 v224, s16, v66
	v_mov_b32_e32 v226, s68
	v_mov_b32_e32 v227, s69
	v_mov_b32_e32 v162, s3
	v_mov_b32_e32 v163, s33
	v_cmp_gt_i32_e32 vcc, s8, v224
	v_add_u32_e32 v225, 0xffffc000, v224
	s_nop 0
	v_cndmask_b32_e32 v224, v225, v224, vcc
	v_cndmask_b32_e32 v226, v162, v226, vcc
	v_cndmask_b32_e32 v227, v163, v227, vcc
	v_mov_b32_e32 v225, 0
	v_lshlrev_b64 v[224:225], 12, v[224:225]
	v_lshl_add_u64 v[224:225], v[226:227], 0, v[224:225]
	v_lshl_add_u64 v[224:225], v[224:225], 0, s[4:5]
	v_lshl_add_u64 v[162:163], v[224:225], 0, v[64:65]
	global_load_dwordx4 v[224:227], v[162:163], off
	v_or_b32_e32 v228, s16, v67
	v_mov_b32_e32 v230, s68
	v_mov_b32_e32 v231, s69
	v_mov_b32_e32 v164, s3
	v_mov_b32_e32 v165, s33
	v_cmp_gt_i32_e32 vcc, s8, v228
	v_add_u32_e32 v229, 0xffffc000, v228
	s_nop 0
	v_cndmask_b32_e32 v228, v229, v228, vcc
	v_cndmask_b32_e32 v230, v164, v230, vcc
	v_cndmask_b32_e32 v231, v165, v231, vcc
	v_mov_b32_e32 v229, 0
	v_lshlrev_b64 v[228:229], 12, v[228:229]
	v_lshl_add_u64 v[228:229], v[230:231], 0, v[228:229]
	v_lshl_add_u64 v[228:229], v[228:229], 0, s[4:5]
	v_lshl_add_u64 v[164:165], v[228:229], 0, v[64:65]
	global_load_dwordx4 v[228:231], v[164:165], off
	v_or_b32_e32 v232, s16, v68
	v_mov_b32_e32 v234, s68
; template <int EPI, int MI>
; DI void gemm_tile(const GemmDesc& g, int tm, int tn, char* smem) {
;     ...
;     for (int mi = 0; mi < MI; ++mi) {
; #pragma unroll
;       for (int ni = 0; ni < 2; ++ni)
; #pragma unroll
;         for (int i = 0; i < 16; ++i) {
;           const int lrow = wm * 32 + (i & 3) + 8 * (i >> 2) + 4 * hh;
;           es[lrow * 128 + wn * 64 + ni * 32 + r] = acc[mi][ni][i];
;         }
;       __syncthreads();
	v_mov_b32_e32 v235, s69
	v_mov_b32_e32 v166, s3
	v_mov_b32_e32 v167, s33
	v_cmp_gt_i32_e32 vcc, s8, v232
	v_add_u32_e32 v233, 0xffffc000, v232
	s_nop 0
	v_cndmask_b32_e32 v232, v233, v232, vcc
	v_cndmask_b32_e32 v234, v166, v234, vcc
	v_cndmask_b32_e32 v235, v167, v235, vcc
	v_mov_b32_e32 v233, 0
	v_lshlrev_b64 v[232:233], 12, v[232:233]
	v_lshl_add_u64 v[232:233], v[234:235], 0, v[232:233]
	v_lshl_add_u64 v[232:233], v[232:233], 0, s[4:5]
	v_lshl_add_u64 v[166:167], v[232:233], 0, v[64:65]
	global_load_dwordx4 v[232:235], v[166:167], off
	v_or_b32_e32 v236, s16, v69
	v_mov_b32_e32 v238, s68
	v_mov_b32_e32 v239, s69
	v_mov_b32_e32 v168, s3
	v_mov_b32_e32 v169, s33
	v_cmp_gt_i32_e32 vcc, s8, v236
	v_add_u32_e32 v237, 0xffffc000, v236
	s_nop 0
	v_cndmask_b32_e32 v236, v237, v236, vcc
	v_cndmask_b32_e32 v238, v168, v238, vcc
	v_cndmask_b32_e32 v239, v169, v239, vcc
	v_mov_b32_e32 v237, 0
	v_lshlrev_b64 v[236:237], 12, v[236:237]
	v_lshl_add_u64 v[236:237], v[238:239], 0, v[236:237]
	v_lshl_add_u64 v[236:237], v[236:237], 0, s[4:5]
	v_lshl_add_u64 v[168:169], v[236:237], 0, v[64:65]
	global_load_dwordx4 v[236:239], v[168:169], off
	s_add_u32 s16, s43, 128
	v_or_b32_e32 v240, s16, v66
	v_mov_b32_e32 v242, s68
	v_mov_b32_e32 v243, s69
	v_mov_b32_e32 v170, s3
	v_mov_b32_e32 v171, s33
	v_cmp_gt_i32_e32 vcc, s8, v240
	v_add_u32_e32 v241, 0xffffc000, v240
	s_nop 0
	v_cndmask_b32_e32 v240, v241, v240, vcc
	v_cndmask_b32_e32 v242, v170, v242, vcc
	v_cndmask_b32_e32 v243, v171, v243, vcc
	v_mov_b32_e32 v241, 0
	v_lshlrev_b64 v[240:241], 12, v[240:241]
	v_lshl_add_u64 v[240:241], v[242:243], 0, v[240:241]
	v_lshl_add_u64 v[240:241], v[240:241], 0, s[4:5]
	v_lshl_add_u64 v[170:171], v[240:241], 0, v[64:65]
	global_load_dwordx4 v[240:243], v[170:171], off
	v_or_b32_e32 v244, s16, v67
	v_mov_b32_e32 v246, s68
	v_mov_b32_e32 v247, s69
	v_mov_b32_e32 v172, s3
	v_mov_b32_e32 v173, s33
	v_cmp_gt_i32_e32 vcc, s8, v244
	v_add_u32_e32 v245, 0xffffc000, v244
	s_nop 0
	v_cndmask_b32_e32 v244, v245, v244, vcc
	v_cndmask_b32_e32 v246, v172, v246, vcc
	v_cndmask_b32_e32 v247, v173, v247, vcc
	v_mov_b32_e32 v245, 0
	v_lshlrev_b64 v[244:245], 12, v[244:245]
	v_lshl_add_u64 v[244:245], v[246:247], 0, v[244:245]
	v_lshl_add_u64 v[244:245], v[244:245], 0, s[4:5]
	v_lshl_add_u64 v[172:173], v[244:245], 0, v[64:65]
	global_load_dwordx4 v[244:247], v[172:173], off
	v_or_b32_e32 v248, s16, v68
	v_mov_b32_e32 v250, s68
	v_mov_b32_e32 v251, s69
	v_mov_b32_e32 v174, s3
	v_mov_b32_e32 v175, s33
	v_cmp_gt_i32_e32 vcc, s8, v248
	v_add_u32_e32 v249, 0xffffc000, v248
	s_nop 0
	v_cndmask_b32_e32 v248, v249, v248, vcc
	v_cndmask_b32_e32 v250, v174, v250, vcc
	v_cndmask_b32_e32 v251, v175, v251, vcc
	v_mov_b32_e32 v249, 0
	v_lshlrev_b64 v[248:249], 12, v[248:249]
	v_lshl_add_u64 v[248:249], v[250:251], 0, v[248:249]
	v_lshl_add_u64 v[248:249], v[248:249], 0, s[4:5]
	v_lshl_add_u64 v[174:175], v[248:249], 0, v[64:65]
	global_load_dwordx4 v[248:251], v[174:175], off
	v_or_b32_e32 v252, s16, v69
	v_mov_b32_e32 v254, s68
	v_mov_b32_e32 v255, s69
	v_mov_b32_e32 v176, s3
	v_mov_b32_e32 v177, s33
	v_cmp_gt_i32_e32 vcc, s8, v252
	v_add_u32_e32 v253, 0xffffc000, v252
	s_nop 0
	v_cndmask_b32_e32 v252, v253, v252, vcc
	v_cndmask_b32_e32 v254, v176, v254, vcc
	v_cndmask_b32_e32 v255, v177, v255, vcc
	v_mov_b32_e32 v253, 0
	v_lshlrev_b64 v[252:253], 12, v[252:253]
	v_lshl_add_u64 v[252:253], v[254:255], 0, v[252:253]
	v_lshl_add_u64 v[252:253], v[252:253], 0, s[4:5]
	v_lshl_add_u64 v[176:177], v[252:253], 0, v[64:65]
	global_load_dwordx4 v[252:255], v[176:177], off
	s_barrier
	ds_write2_b32 v107, v48, v32 offset1:32
	ds_write2_b32 v107, v49, v33 offset0:128 offset1:160
	ds_write2_b32 v80, v50, v34 offset1:32
	ds_write2_b32 v80, v51, v35 offset0:128 offset1:160
	ds_write2_b32 v81, v52, v36 offset1:32
	ds_write2_b32 v81, v53, v37 offset0:128 offset1:160
	ds_write2_b32 v82, v54, v38 offset1:32
	ds_write2_b32 v82, v55, v39 offset0:128 offset1:160
	ds_write2_b32 v71, v56, v40 offset1:32
	ds_write2_b32 v71, v57, v41 offset0:128 offset1:160
	ds_write2_b32 v72, v58, v42 offset1:32
	ds_write2_b32 v72, v59, v43 offset0:128 offset1:160
	ds_write2_b32 v73, v60, v44 offset1:32
	ds_write2_b32 v73, v61, v45 offset0:128 offset1:160
	ds_write2_b32 v74, v62, v46 offset1:32
	ds_write2_b32 v74, v63, v47 offset0:128 offset1:160
	s_or_b32 s16, s43, 32
	s_mov_b32 s17, 0
	v_mov_b32_e32 v32, v97
	s_waitcnt lgkmcnt(0)
	s_barrier
; template <int EPI, int MI>
; DI void gemm_tile(const GemmDesc& g, int tm, int tn, char* smem) {
;     ...
;       for (int j = 0; j < 8; ++j) {
;         const int lrow = (tid >> 5) + 8 * j;
;         const int grow = m0 + (lrow >> 5) * (32 * MI) + mi * 32 + (lrow & 31);
;         const f32x4v a4 = *(const f32x4v*)(es + lrow * 128 + c4);
;         const int rg = grow < LAT ? (grow >> 11) : 8;
;         const f32x4v m4 = rg == rgA ? m4a : m4b;
;         float* rp = (grow < LAT ? g.xres + (size_t)grow * 1024 : g.hres + (size_t)(grow - LAT) * 1024) + n0 + c4;
;         f32x4v x4 = *(const f32x4v*)rp;
;         x4 += (m4 * a4) * g.coef;
;         *(f32x4v*)rp = x4;
;       }
	ds_read_b128 v[84:87], v70
	s_add_u32 s16, s43, 32
	s_ashr_i32 s17, s16, 11
	v_or_b32_e32 v88, s16, v66
	v_mov_b32_e32 v89, s17
	v_cmp_gt_i32_e32 vcc, s8, v88
	ds_read_b128 v[92:95], v70 offset:4096
	s_nop 0
	v_cndmask_b32_e32 v89, 8, v89, vcc
	v_cmp_eq_u32_e64 s[0:1], s15, v89
	s_nop 1
	v_cndmask_b32_e64 v89, v103, v99, s[0:1]
	v_cndmask_b32_e64 v88, v102, v98, s[0:1]
	v_cndmask_b32_e64 v91, v105, v101, s[0:1]
	v_cndmask_b32_e64 v90, v104, v100, s[0:1]
	s_waitcnt lgkmcnt(1)
	v_pk_mul_f32 v[86:87], v[86:87], v[90:91]
	v_pk_mul_f32 v[84:85], v[84:85], v[88:89]
	s_waitcnt vmcnt(7)
	v_pk_fma_f32 v[84:85], v[84:85], 0.5, v[224:225] op_sel_hi:[1,0,1]
	v_pk_fma_f32 v[86:87], v[86:87], 0.5, v[226:227] op_sel_hi:[1,0,1]
	global_store_dwordx4 v[162:163], v[84:87], off
	v_or_b32_e32 v88, s16, v67
	v_mov_b32_e32 v89, s17
	v_cmp_gt_i32_e32 vcc, s8, v88
	ds_read_b128 v[84:87], v70 offset:8192
	s_nop 0
	v_cndmask_b32_e32 v89, 8, v89, vcc
	v_cmp_eq_u32_e64 s[0:1], s15, v89
	s_nop 1
	v_cndmask_b32_e64 v89, v103, v99, s[0:1]
	v_cndmask_b32_e64 v88, v102, v98, s[0:1]
	v_cndmask_b32_e64 v91, v105, v101, s[0:1]
	v_cndmask_b32_e64 v90, v104, v100, s[0:1]
	s_waitcnt lgkmcnt(1)
	v_pk_mul_f32 v[94:95], v[94:95], v[90:91]
	v_pk_mul_f32 v[92:93], v[92:93], v[88:89]
	s_waitcnt vmcnt(7)
	v_pk_fma_f32 v[92:93], v[92:93], 0.5, v[228:229] op_sel_hi:[1,0,1]
	v_pk_fma_f32 v[94:95], v[94:95], 0.5, v[230:231] op_sel_hi:[1,0,1]
	global_store_dwordx4 v[164:165], v[92:95], off
	v_or_b32_e32 v88, s16, v68
	v_mov_b32_e32 v89, s17
	v_cmp_gt_i32_e32 vcc, s8, v88
	ds_read_b128 v[92:95], v70 offset:12288
	s_nop 0
	v_cndmask_b32_e32 v89, 8, v89, vcc
	v_cmp_eq_u32_e64 s[0:1], s15, v89
	s_nop 1
	v_cndmask_b32_e64 v89, v103, v99, s[0:1]
	v_cndmask_b32_e64 v88, v102, v98, s[0:1]
	v_cndmask_b32_e64 v91, v105, v101, s[0:1]
	v_cndmask_b32_e64 v90, v104, v100, s[0:1]
	s_waitcnt lgkmcnt(1)
	v_pk_mul_f32 v[86:87], v[86:87], v[90:91]
	v_pk_mul_f32 v[84:85], v[84:85], v[88:89]
	s_waitcnt vmcnt(7)
	v_pk_fma_f32 v[84:85], v[84:85], 0.5, v[232:233] op_sel_hi:[1,0,1]
	v_pk_fma_f32 v[86:87], v[86:87], 0.5, v[234:235] op_sel_hi:[1,0,1]
	global_store_dwordx4 v[166:167], v[84:87], off
	v_or_b32_e32 v88, s16, v69
	v_mov_b32_e32 v89, s17
	v_cmp_gt_i32_e32 vcc, s8, v88
	ds_read_b128 v[84:87], v70 offset:16384
	s_nop 0
	v_cndmask_b32_e32 v89, 8, v89, vcc
	v_cmp_eq_u32_e64 s[0:1], s15, v89
	s_nop 1
	v_cndmask_b32_e64 v89, v103, v99, s[0:1]
	v_cndmask_b32_e64 v88, v102, v98, s[0:1]
	v_cndmask_b32_e64 v91, v105, v101, s[0:1]
	v_cndmask_b32_e64 v90, v104, v100, s[0:1]
	s_waitcnt lgkmcnt(1)
	v_pk_mul_f32 v[94:95], v[94:95], v[90:91]
	v_pk_mul_f32 v[92:93], v[92:93], v[88:89]
	s_waitcnt vmcnt(7)
	v_pk_fma_f32 v[92:93], v[92:93], 0.5, v[236:237] op_sel_hi:[1,0,1]
	v_pk_fma_f32 v[94:95], v[94:95], 0.5, v[238:239] op_sel_hi:[1,0,1]
	global_store_dwordx4 v[168:169], v[92:95], off
	s_add_u32 s16, s43, 128
	s_ashr_i32 s17, s16, 11
	v_or_b32_e32 v88, s16, v66
	v_mov_b32_e32 v89, s17
	v_cmp_gt_i32_e32 vcc, s8, v88
	ds_read_b128 v[92:95], v70 offset:20480
	s_nop 0
	v_cndmask_b32_e32 v89, 8, v89, vcc
	v_cmp_eq_u32_e64 s[0:1], s15, v89
	s_nop 1
	v_cndmask_b32_e64 v89, v103, v99, s[0:1]
	v_cndmask_b32_e64 v88, v102, v98, s[0:1]
	v_cndmask_b32_e64 v91, v105, v101, s[0:1]
	v_cndmask_b32_e64 v90, v104, v100, s[0:1]
	s_waitcnt lgkmcnt(1)
	v_pk_mul_f32 v[86:87], v[86:87], v[90:91]
	v_pk_mul_f32 v[84:85], v[84:85], v[88:89]
	s_waitcnt vmcnt(7)
	v_pk_fma_f32 v[84:85], v[84:85], 0.5, v[240:241] op_sel_hi:[1,0,1]
	v_pk_fma_f32 v[86:87], v[86:87], 0.5, v[242:243] op_sel_hi:[1,0,1]
	global_store_dwordx4 v[170:171], v[84:87], off
	v_or_b32_e32 v88, s16, v67
	v_mov_b32_e32 v89, s17
	v_cmp_gt_i32_e32 vcc, s8, v88
	ds_read_b128 v[84:87], v70 offset:24576
	s_nop 0
	v_cndmask_b32_e32 v89, 8, v89, vcc
	v_cmp_eq_u32_e64 s[0:1], s15, v89
	s_nop 1
	v_cndmask_b32_e64 v89, v103, v99, s[0:1]
	v_cndmask_b32_e64 v88, v102, v98, s[0:1]
	v_cndmask_b32_e64 v91, v105, v101, s[0:1]
	v_cndmask_b32_e64 v90, v104, v100, s[0:1]
	s_waitcnt lgkmcnt(1)
	v_pk_mul_f32 v[94:95], v[94:95], v[90:91]
	v_pk_mul_f32 v[92:93], v[92:93], v[88:89]
	s_waitcnt vmcnt(7)
	v_pk_fma_f32 v[92:93], v[92:93], 0.5, v[244:245] op_sel_hi:[1,0,1]
	v_pk_fma_f32 v[94:95], v[94:95], 0.5, v[246:247] op_sel_hi:[1,0,1]
	global_store_dwordx4 v[172:173], v[92:95], off
	v_or_b32_e32 v88, s16, v68
	v_mov_b32_e32 v89, s17
	v_cmp_gt_i32_e32 vcc, s8, v88
	ds_read_b128 v[92:95], v70 offset:28672
	s_nop 0
	v_cndmask_b32_e32 v89, 8, v89, vcc
	v_cmp_eq_u32_e64 s[0:1], s15, v89
	s_nop 1
	v_cndmask_b32_e64 v89, v103, v99, s[0:1]
	v_cndmask_b32_e64 v88, v102, v98, s[0:1]
	v_cndmask_b32_e64 v91, v105, v101, s[0:1]
	v_cndmask_b32_e64 v90, v104, v100, s[0:1]
	s_waitcnt lgkmcnt(1)
	v_pk_mul_f32 v[86:87], v[86:87], v[90:91]
	v_pk_mul_f32 v[84:85], v[84:85], v[88:89]
	s_waitcnt vmcnt(7)
	v_pk_fma_f32 v[84:85], v[84:85], 0.5, v[248:249] op_sel_hi:[1,0,1]
	v_pk_fma_f32 v[86:87], v[86:87], 0.5, v[250:251] op_sel_hi:[1,0,1]
	global_store_dwordx4 v[174:175], v[84:87], off
	v_or_b32_e32 v88, s16, v69
	v_mov_b32_e32 v89, s17
	v_cmp_gt_i32_e32 vcc, s8, v88
	s_nop 1
	v_cndmask_b32_e32 v89, 8, v89, vcc
	v_cmp_eq_u32_e64 s[0:1], s15, v89
	s_nop 1
	v_cndmask_b32_e64 v89, v103, v99, s[0:1]
	v_cndmask_b32_e64 v88, v102, v98, s[0:1]
	v_cndmask_b32_e64 v91, v105, v101, s[0:1]
	v_cndmask_b32_e64 v90, v104, v100, s[0:1]
	s_waitcnt lgkmcnt(0)
	v_pk_mul_f32 v[94:95], v[94:95], v[90:91]
	v_pk_mul_f32 v[92:93], v[92:93], v[88:89]
	s_waitcnt vmcnt(7)
; template <int EPI, int MI>
; DI void gemm_tile(const GemmDesc& g, int tm, int tn, char* smem) {
;     ...
;     for (int mi = 0; mi < MI; ++mi) {
; #pragma unroll
;       for (int ni = 0; ni < 2; ++ni)
; #pragma unroll
;         for (int i = 0; i < 16; ++i) {
;           const int lrow = wm * 32 + (i & 3) + 8 * (i >> 2) + 4 * hh;
;           es[lrow * 128 + wn * 64 + ni * 32 + r] = acc[mi][ni][i];
;         }
;       __syncthreads();
; #pragma unroll 4
;       for (int j = 0; j < 8; ++j) {
;         const int lrow = (tid >> 5) + 8 * j;
;         const int grow = m0 + (lrow >> 5) * (32 * MI) + mi * 32 + (lrow & 31);
;         const f32x4v a4 = *(const f32x4v*)(es + lrow * 128 + c4);
;         const int rg = grow < LAT ? (grow >> 11) : 8;
;         const f32x4v m4 = rg == rgA ? m4a : m4b;
;         float* rp = (grow < LAT ? g.xres + (size_t)grow * 1024 : g.hres + (size_t)(grow - LAT) * 1024) + n0 + c4;
;         f32x4v x4 = *(const f32x4v*)rp;
;         x4 += (m4 * a4) * g.coef;
;         *(f32x4v*)rp = x4;
;       }
;       __syncthreads();
	v_pk_fma_f32 v[92:93], v[92:93], 0.5, v[252:253] op_sel_hi:[1,0,1]
	v_pk_fma_f32 v[94:95], v[94:95], 0.5, v[254:255] op_sel_hi:[1,0,1]
	global_store_dwordx4 v[176:177], v[92:95], off
	s_add_u32 s16, s43, 64
	v_or_b32_e32 v224, s16, v66
	v_mov_b32_e32 v226, s68
	v_mov_b32_e32 v227, s69
	v_mov_b32_e32 v162, s3
	v_mov_b32_e32 v163, s33
	v_cmp_gt_i32_e32 vcc, s8, v224
	v_add_u32_e32 v225, 0xffffc000, v224
	s_nop 0
	v_cndmask_b32_e32 v224, v225, v224, vcc
	v_cndmask_b32_e32 v226, v162, v226, vcc
	v_cndmask_b32_e32 v227, v163, v227, vcc
	v_mov_b32_e32 v225, 0
	v_lshlrev_b64 v[224:225], 12, v[224:225]
	v_lshl_add_u64 v[224:225], v[226:227], 0, v[224:225]
	v_lshl_add_u64 v[224:225], v[224:225], 0, s[4:5]
	v_lshl_add_u64 v[162:163], v[224:225], 0, v[64:65]
	global_load_dwordx4 v[224:227], v[162:163], off
	v_or_b32_e32 v228, s16, v67
	v_mov_b32_e32 v230, s68
	v_mov_b32_e32 v231, s69
	v_mov_b32_e32 v164, s3
	v_mov_b32_e32 v165, s33
	v_cmp_gt_i32_e32 vcc, s8, v228
	v_add_u32_e32 v229, 0xffffc000, v228
	s_nop 0
	v_cndmask_b32_e32 v228, v229, v228, vcc
	v_cndmask_b32_e32 v230, v164, v230, vcc
	v_cndmask_b32_e32 v231, v165, v231, vcc
	v_mov_b32_e32 v229, 0
	v_lshlrev_b64 v[228:229], 12, v[228:229]
	v_lshl_add_u64 v[228:229], v[230:231], 0, v[228:229]
	v_lshl_add_u64 v[228:229], v[228:229], 0, s[4:5]
	v_lshl_add_u64 v[164:165], v[228:229], 0, v[64:65]
	global_load_dwordx4 v[228:231], v[164:165], off
	v_or_b32_e32 v232, s16, v68
	v_mov_b32_e32 v234, s68
	v_mov_b32_e32 v235, s69
	v_mov_b32_e32 v166, s3
	v_mov_b32_e32 v167, s33
	v_cmp_gt_i32_e32 vcc, s8, v232
	v_add_u32_e32 v233, 0xffffc000, v232
	s_nop 0
	v_cndmask_b32_e32 v232, v233, v232, vcc
	v_cndmask_b32_e32 v234, v166, v234, vcc
	v_cndmask_b32_e32 v235, v167, v235, vcc
	v_mov_b32_e32 v233, 0
	v_lshlrev_b64 v[232:233], 12, v[232:233]
	v_lshl_add_u64 v[232:233], v[234:235], 0, v[232:233]
	v_lshl_add_u64 v[232:233], v[232:233], 0, s[4:5]
	v_lshl_add_u64 v[166:167], v[232:233], 0, v[64:65]
	global_load_dwordx4 v[232:235], v[166:167], off
	v_or_b32_e32 v236, s16, v69
	v_mov_b32_e32 v238, s68
	v_mov_b32_e32 v239, s69
	v_mov_b32_e32 v168, s3
	v_mov_b32_e32 v169, s33
	v_cmp_gt_i32_e32 vcc, s8, v236
	v_add_u32_e32 v237, 0xffffc000, v236
	s_nop 0
	v_cndmask_b32_e32 v236, v237, v236, vcc
	v_cndmask_b32_e32 v238, v168, v238, vcc
	v_cndmask_b32_e32 v239, v169, v239, vcc
	v_mov_b32_e32 v237, 0
	v_lshlrev_b64 v[236:237], 12, v[236:237]
	v_lshl_add_u64 v[236:237], v[238:239], 0, v[236:237]
	v_lshl_add_u64 v[236:237], v[236:237], 0, s[4:5]
	v_lshl_add_u64 v[168:169], v[236:237], 0, v[64:65]
	global_load_dwordx4 v[236:239], v[168:169], off
	s_add_u32 s16, s43, 160
	v_or_b32_e32 v240, s16, v66
	v_mov_b32_e32 v242, s68
	v_mov_b32_e32 v243, s69
	v_mov_b32_e32 v170, s3
	v_mov_b32_e32 v171, s33
	v_cmp_gt_i32_e32 vcc, s8, v240
	v_add_u32_e32 v241, 0xffffc000, v240
	s_nop 0
	v_cndmask_b32_e32 v240, v241, v240, vcc
	v_cndmask_b32_e32 v242, v170, v242, vcc
	v_cndmask_b32_e32 v243, v171, v243, vcc
	v_mov_b32_e32 v241, 0
	v_lshlrev_b64 v[240:241], 12, v[240:241]
	v_lshl_add_u64 v[240:241], v[242:243], 0, v[240:241]
	v_lshl_add_u64 v[240:241], v[240:241], 0, s[4:5]
	v_lshl_add_u64 v[170:171], v[240:241], 0, v[64:65]
	global_load_dwordx4 v[240:243], v[170:171], off
	v_or_b32_e32 v244, s16, v67
	v_mov_b32_e32 v246, s68
	v_mov_b32_e32 v247, s69
	v_mov_b32_e32 v172, s3
	v_mov_b32_e32 v173, s33
	v_cmp_gt_i32_e32 vcc, s8, v244
	v_add_u32_e32 v245, 0xffffc000, v244
	s_nop 0
	v_cndmask_b32_e32 v244, v245, v244, vcc
	v_cndmask_b32_e32 v246, v172, v246, vcc
	v_cndmask_b32_e32 v247, v173, v247, vcc
	v_mov_b32_e32 v245, 0
	v_lshlrev_b64 v[244:245], 12, v[244:245]
	v_lshl_add_u64 v[244:245], v[246:247], 0, v[244:245]
	v_lshl_add_u64 v[244:245], v[244:245], 0, s[4:5]
	v_lshl_add_u64 v[172:173], v[244:245], 0, v[64:65]
	global_load_dwordx4 v[244:247], v[172:173], off
	v_or_b32_e32 v248, s16, v68
	v_mov_b32_e32 v250, s68
	v_mov_b32_e32 v251, s69
	v_mov_b32_e32 v174, s3
	v_mov_b32_e32 v175, s33
	v_cmp_gt_i32_e32 vcc, s8, v248
	v_add_u32_e32 v249, 0xffffc000, v248
	s_nop 0
	v_cndmask_b32_e32 v248, v249, v248, vcc
	v_cndmask_b32_e32 v250, v174, v250, vcc
	v_cndmask_b32_e32 v251, v175, v251, vcc
	v_mov_b32_e32 v249, 0
	v_lshlrev_b64 v[248:249], 12, v[248:249]
	v_lshl_add_u64 v[248:249], v[250:251], 0, v[248:249]
	v_lshl_add_u64 v[248:249], v[248:249], 0, s[4:5]
	v_lshl_add_u64 v[174:175], v[248:249], 0, v[64:65]
	global_load_dwordx4 v[248:251], v[174:175], off
	v_or_b32_e32 v252, s16, v69
	v_mov_b32_e32 v254, s68
	v_mov_b32_e32 v255, s69
	v_mov_b32_e32 v176, s3
	v_mov_b32_e32 v177, s33
	v_cmp_gt_i32_e32 vcc, s8, v252
	v_add_u32_e32 v253, 0xffffc000, v252
	s_nop 0
	v_cndmask_b32_e32 v252, v253, v252, vcc
	v_cndmask_b32_e32 v254, v176, v254, vcc
	v_cndmask_b32_e32 v255, v177, v255, vcc
	v_mov_b32_e32 v253, 0
	v_lshlrev_b64 v[252:253], 12, v[252:253]
	v_lshl_add_u64 v[252:253], v[254:255], 0, v[252:253]
	v_lshl_add_u64 v[252:253], v[252:253], 0, s[4:5]
	v_lshl_add_u64 v[176:177], v[252:253], 0, v[64:65]
	global_load_dwordx4 v[252:255], v[176:177], off
	s_add_i32 s43, s43, 64
	s_mov_b32 s16, 0
	s_barrier
	ds_write2_b32 v107, v16, v0 offset1:32
	ds_write2_b32 v107, v17, v1 offset0:128 offset1:160
	ds_write2_b32 v80, v18, v2 offset1:32
	ds_write2_b32 v80, v19, v3 offset0:128 offset1:160
	ds_write2_b32 v81, v20, v4 offset1:32
	ds_write2_b32 v81, v21, v5 offset0:128 offset1:160
	ds_write2_b32 v82, v22, v6 offset1:32
	ds_write2_b32 v82, v23, v7 offset0:128 offset1:160
	ds_write2_b32 v71, v24, v8 offset1:32
	ds_write2_b32 v71, v25, v9 offset0:128 offset1:160
	ds_write2_b32 v72, v26, v10 offset1:32
	ds_write2_b32 v72, v27, v11 offset0:128 offset1:160
	ds_write2_b32 v73, v28, v12 offset1:32
	ds_write2_b32 v73, v29, v13 offset0:128 offset1:160
	ds_write2_b32 v74, v30, v14 offset1:32
	ds_write2_b32 v74, v31, v15 offset0:128 offset1:160
	s_waitcnt lgkmcnt(0)
	s_barrier
; template <int EPI, int MI>
; DI void gemm_tile(const GemmDesc& g, int tm, int tn, char* smem) {
;     ...
; #pragma unroll 4
;       for (int j = 0; j < 8; ++j) {
;         const int lrow = (tid >> 5) + 8 * j;
;         const int grow = m0 + (lrow >> 5) * (32 * MI) + mi * 32 + (lrow & 31);
;         const f32x4v a4 = *(const f32x4v*)(es + lrow * 128 + c4);
;         const int rg = grow < LAT ? (grow >> 11) : 8;
;         const f32x4v m4 = rg == rgA ? m4a : m4b;
;         float* rp = (grow < LAT ? g.xres + (size_t)grow * 1024 : g.hres + (size_t)(grow - LAT) * 1024) + n0 + c4;
;         f32x4v x4 = *(const f32x4v*)rp;
;         x4 += (m4 * a4) * g.coef;
;         *(f32x4v*)rp = x4;
;       }
;       __syncthreads();
; template <int EPI, int MI>
; DI void gemm_phase(const GemmDesc& g, char* smem, int vb, int nvb) {
;     ...
;   for (int q = start; q < local; q += step) {
;     const int mg = q / per;
;     const int rem = q - mg * per;
;     const int tn = rem / PM;
;     const int tm = mbase + mg * PM + (rem - tn * PM);
;     gemm_tile<EPI, MI>(g, tm, tn, smem);
	ds_read_b128 v[84:87], v70
	s_mov_b32 s16, s43
	s_ashr_i32 s17, s16, 11
	v_or_b32_e32 v88, s16, v66
	v_mov_b32_e32 v89, s17
	v_cmp_gt_i32_e32 vcc, s8, v88
	ds_read_b128 v[92:95], v70 offset:4096
	s_nop 0
	v_cndmask_b32_e32 v89, 8, v89, vcc
	v_cmp_eq_u32_e64 s[0:1], s15, v89
	s_nop 1
	v_cndmask_b32_e64 v89, v103, v99, s[0:1]
	v_cndmask_b32_e64 v88, v102, v98, s[0:1]
	v_cndmask_b32_e64 v91, v105, v101, s[0:1]
	v_cndmask_b32_e64 v90, v104, v100, s[0:1]
	s_waitcnt lgkmcnt(1)
	v_pk_mul_f32 v[86:87], v[86:87], v[90:91]
	v_pk_mul_f32 v[84:85], v[84:85], v[88:89]
	s_waitcnt vmcnt(7)
	v_pk_fma_f32 v[84:85], v[84:85], 0.5, v[224:225] op_sel_hi:[1,0,1]
	v_pk_fma_f32 v[86:87], v[86:87], 0.5, v[226:227] op_sel_hi:[1,0,1]
	global_store_dwordx4 v[162:163], v[84:87], off
	v_or_b32_e32 v88, s16, v67
	v_mov_b32_e32 v89, s17
	v_cmp_gt_i32_e32 vcc, s8, v88
	ds_read_b128 v[84:87], v70 offset:8192
	s_nop 0
	v_cndmask_b32_e32 v89, 8, v89, vcc
	v_cmp_eq_u32_e64 s[0:1], s15, v89
	s_nop 1
	v_cndmask_b32_e64 v89, v103, v99, s[0:1]
	v_cndmask_b32_e64 v88, v102, v98, s[0:1]
	v_cndmask_b32_e64 v91, v105, v101, s[0:1]
	v_cndmask_b32_e64 v90, v104, v100, s[0:1]
	s_waitcnt lgkmcnt(1)
	v_pk_mul_f32 v[94:95], v[94:95], v[90:91]
	v_pk_mul_f32 v[92:93], v[92:93], v[88:89]
	s_waitcnt vmcnt(7)
	v_pk_fma_f32 v[92:93], v[92:93], 0.5, v[228:229] op_sel_hi:[1,0,1]
	v_pk_fma_f32 v[94:95], v[94:95], 0.5, v[230:231] op_sel_hi:[1,0,1]
	global_store_dwordx4 v[164:165], v[92:95], off
	v_or_b32_e32 v88, s16, v68
	v_mov_b32_e32 v89, s17
	v_cmp_gt_i32_e32 vcc, s8, v88
	ds_read_b128 v[92:95], v70 offset:12288
	s_nop 0
	v_cndmask_b32_e32 v89, 8, v89, vcc
	v_cmp_eq_u32_e64 s[0:1], s15, v89
	s_nop 1
	v_cndmask_b32_e64 v89, v103, v99, s[0:1]
	v_cndmask_b32_e64 v88, v102, v98, s[0:1]
	v_cndmask_b32_e64 v91, v105, v101, s[0:1]
	v_cndmask_b32_e64 v90, v104, v100, s[0:1]
	s_waitcnt lgkmcnt(1)
	v_pk_mul_f32 v[86:87], v[86:87], v[90:91]
	v_pk_mul_f32 v[84:85], v[84:85], v[88:89]
	s_waitcnt vmcnt(7)
	v_pk_fma_f32 v[84:85], v[84:85], 0.5, v[232:233] op_sel_hi:[1,0,1]
	v_pk_fma_f32 v[86:87], v[86:87], 0.5, v[234:235] op_sel_hi:[1,0,1]
	global_store_dwordx4 v[166:167], v[84:87], off
	v_or_b32_e32 v88, s16, v69
	v_mov_b32_e32 v89, s17
	v_cmp_gt_i32_e32 vcc, s8, v88
	ds_read_b128 v[84:87], v70 offset:16384
	s_nop 0
	v_cndmask_b32_e32 v89, 8, v89, vcc
	v_cmp_eq_u32_e64 s[0:1], s15, v89
	s_nop 1
	v_cndmask_b32_e64 v89, v103, v99, s[0:1]
	v_cndmask_b32_e64 v88, v102, v98, s[0:1]
	v_cndmask_b32_e64 v91, v105, v101, s[0:1]
	v_cndmask_b32_e64 v90, v104, v100, s[0:1]
	s_waitcnt lgkmcnt(1)
	v_pk_mul_f32 v[94:95], v[94:95], v[90:91]
	v_pk_mul_f32 v[92:93], v[92:93], v[88:89]
	s_waitcnt vmcnt(7)
	v_pk_fma_f32 v[92:93], v[92:93], 0.5, v[236:237] op_sel_hi:[1,0,1]
	v_pk_fma_f32 v[94:95], v[94:95], 0.5, v[238:239] op_sel_hi:[1,0,1]
	global_store_dwordx4 v[168:169], v[92:95], off
	s_add_u32 s16, s43, 96
	s_ashr_i32 s17, s16, 11
	v_or_b32_e32 v88, s16, v66
	v_mov_b32_e32 v89, s17
	v_cmp_gt_i32_e32 vcc, s8, v88
	ds_read_b128 v[92:95], v70 offset:20480
	s_nop 0
	v_cndmask_b32_e32 v89, 8, v89, vcc
	v_cmp_eq_u32_e64 s[0:1], s15, v89
	s_nop 1
	v_cndmask_b32_e64 v89, v103, v99, s[0:1]
	v_cndmask_b32_e64 v88, v102, v98, s[0:1]
	v_cndmask_b32_e64 v91, v105, v101, s[0:1]
	v_cndmask_b32_e64 v90, v104, v100, s[0:1]
	s_waitcnt lgkmcnt(1)
	v_pk_mul_f32 v[86:87], v[86:87], v[90:91]
	v_pk_mul_f32 v[84:85], v[84:85], v[88:89]
	s_waitcnt vmcnt(7)
	v_pk_fma_f32 v[84:85], v[84:85], 0.5, v[240:241] op_sel_hi:[1,0,1]
	v_pk_fma_f32 v[86:87], v[86:87], 0.5, v[242:243] op_sel_hi:[1,0,1]
	global_store_dwordx4 v[170:171], v[84:87], off
	v_or_b32_e32 v88, s16, v67
	v_mov_b32_e32 v89, s17
	v_cmp_gt_i32_e32 vcc, s8, v88
	ds_read_b128 v[84:87], v70 offset:24576
	s_nop 0
	v_cndmask_b32_e32 v89, 8, v89, vcc
	v_cmp_eq_u32_e64 s[0:1], s15, v89
	s_nop 1
	v_cndmask_b32_e64 v89, v103, v99, s[0:1]
	v_cndmask_b32_e64 v88, v102, v98, s[0:1]
	v_cndmask_b32_e64 v91, v105, v101, s[0:1]
	v_cndmask_b32_e64 v90, v104, v100, s[0:1]
	s_waitcnt lgkmcnt(1)
	v_pk_mul_f32 v[94:95], v[94:95], v[90:91]
	v_pk_mul_f32 v[92:93], v[92:93], v[88:89]
	s_waitcnt vmcnt(7)
	v_pk_fma_f32 v[92:93], v[92:93], 0.5, v[244:245] op_sel_hi:[1,0,1]
	v_pk_fma_f32 v[94:95], v[94:95], 0.5, v[246:247] op_sel_hi:[1,0,1]
	global_store_dwordx4 v[172:173], v[92:95], off
	v_or_b32_e32 v88, s16, v68
	v_mov_b32_e32 v89, s17
	v_cmp_gt_i32_e32 vcc, s8, v88
	ds_read_b128 v[92:95], v70 offset:28672
	s_nop 0
	v_cndmask_b32_e32 v89, 8, v89, vcc
	v_cmp_eq_u32_e64 s[0:1], s15, v89
	s_nop 1
	v_cndmask_b32_e64 v89, v103, v99, s[0:1]
	v_cndmask_b32_e64 v88, v102, v98, s[0:1]
	v_cndmask_b32_e64 v91, v105, v101, s[0:1]
	v_cndmask_b32_e64 v90, v104, v100, s[0:1]
	s_waitcnt lgkmcnt(1)
	v_pk_mul_f32 v[86:87], v[86:87], v[90:91]
	v_pk_mul_f32 v[84:85], v[84:85], v[88:89]
	s_waitcnt vmcnt(7)
	v_pk_fma_f32 v[84:85], v[84:85], 0.5, v[248:249] op_sel_hi:[1,0,1]
	v_pk_fma_f32 v[86:87], v[86:87], 0.5, v[250:251] op_sel_hi:[1,0,1]
	global_store_dwordx4 v[174:175], v[84:87], off
	v_or_b32_e32 v88, s16, v69
	v_mov_b32_e32 v89, s17
	v_cmp_gt_i32_e32 vcc, s8, v88
	s_nop 1
	v_cndmask_b32_e32 v89, 8, v89, vcc
	v_cmp_eq_u32_e64 s[0:1], s15, v89
	s_nop 1
	v_cndmask_b32_e64 v89, v103, v99, s[0:1]
	v_cndmask_b32_e64 v88, v102, v98, s[0:1]
	v_cndmask_b32_e64 v91, v105, v101, s[0:1]
	v_cndmask_b32_e64 v90, v104, v100, s[0:1]
	s_waitcnt lgkmcnt(0)
	v_pk_mul_f32 v[94:95], v[94:95], v[90:91]
	v_pk_mul_f32 v[92:93], v[92:93], v[88:89]
	s_waitcnt vmcnt(7)
	v_pk_fma_f32 v[92:93], v[92:93], 0.5, v[252:253] op_sel_hi:[1,0,1]
	v_pk_fma_f32 v[94:95], v[94:95], 0.5, v[254:255] op_sel_hi:[1,0,1]
	global_store_dwordx4 v[176:177], v[92:95], off
	v_readlane_b32 s0, v218, 38
	s_add_i32 s42, s42, s0
	v_readlane_b32 s0, v218, 31
	s_add_i32 s39, s39, s0
	v_readlane_b32 s0, v221, 13
	s_cmp_lt_i32 s42, s0
	s_barrier
	s_cbranch_scc1 .LBB0_254

; template <int EPI, int MI>
; DI void gemm_tile(const GemmDesc& g, int tm, int tn, char* smem) {
;     ...
;   char* As = smem;
;   char* Bs = smem + 2 * ABYTES;
;   const int tid = get_tid(), lane = tid & 63, wave = tid >> 6, r = lane & 31, hh = lane >> 5;
;   const int wm = wave >> 1, wn = wave & 1;
;   const int m0 = tm * BM, n0 = tn * 128;
;   const int nk = g.K >> 6;
;   f32x16 acc[MI][2];
; #pragma unroll
;   for (int a = 0; a < MI; ++a)
; #pragma unroll
;     for (int b = 0; b < 2; ++b)
; #pragma unroll
;       for (int i = 0; i < 16; ++i) acc[a][b][i] = 0.f;
;   const int srow = tid >> 3;
;   const int schunk = (tid & 7) ^ ((srow & 7) ^ ((srow >> 3) & 3));
;     ...
;   const int rowA = wm * (32 * MI) + r, rowB = wn * 64 + r;
;   const int hk = hh ^ ((r & 7) ^ ((r >> 3) & 3));
;     ...
;   G_GLDS(0, 0);
;   asm volatile("s_waitcnt vmcnt(0)" ::: "memory");
;   __syncthreads();
; template <int EPI, int MI>
; DI void gemm_phase(const GemmDesc& g, char* smem, int vb, int nvb) {
;     ...
;   for (int q = start; q < local; q += step) {
;     const int mg = q / per;
;     const int rem = q - mg * per;
;     const int tn = rem / PM;
;     const int tm = mbase + mg * PM + (rem - tn * PM);
;     gemm_tile<EPI, MI>(g, tm, tn, smem);
.LBB0_1491:
	s_abs_i32 s0, s40
	v_readlane_b32 s1, v219, 48
	s_mul_hi_u32 s1, s0, s1
	v_readlane_b32 s17, v219, 47
	s_mul_i32 s4, s1, s17
	s_sub_i32 s0, s0, s4
	s_ashr_i32 s15, s40, 31
	s_add_i32 s4, s1, 1
	s_sub_i32 s5, s0, s17
	s_cmp_ge_u32 s0, s17
	s_cselect_b32 s1, s4, s1
	s_cselect_b32 s0, s5, s0
	s_add_i32 s4, s1, 1
	s_cmp_ge_u32 s0, s17
	s_cselect_b32 s0, s4, s1
	s_xor_b32 s16, s0, s15
	s_sub_i32 s0, s16, s15
	s_mul_i32 s1, s0, s17
	s_sub_i32 s1, s40, s1
	s_abs_i32 s4, s1
	v_readlane_b32 s5, v219, 46
	s_mul_hi_u32 s5, s4, s5
	v_readlane_b32 s41, v218, 32
	s_mul_i32 s18, s5, s41
	s_sub_i32 s4, s4, s18
	s_ashr_i32 s17, s1, 31
	s_add_i32 s18, s5, 1
	s_sub_i32 s19, s4, s41
	s_cmp_ge_u32 s4, s41
	s_cselect_b32 s5, s18, s5
	s_cselect_b32 s4, s19, s4
	s_add_i32 s18, s5, 1
	s_cmp_ge_u32 s4, s41
	s_cselect_b32 s4, s18, s5
	s_xor_b32 s18, s4, s17
	v_mov_b32_e32 v97, v132
	s_sub_i32 s4, s18, s17
	s_mul_i32 s0, s0, s41
	v_ashrrev_i32_e32 v6, 3, v97
	s_mul_i32 s5, s4, s41
	s_waitcnt vmcnt(8)
	v_ashrrev_i32_e32 v109, 7, v97
	v_bfe_u32 v1, v97, 6, 2
	v_xor_b32_e32 v2, v6, v97
	s_add_i32 s0, s0, s54
	s_sub_i32 s1, s1, s5
	v_and_b32_e32 v108, 31, v97
	v_bitop3_b32 v2, v2, v1, 7 bitop3:0x6c
	v_mul_lo_u32 v1, v109, s6
	s_add_i32 s1, s0, s1
	s_lshl_b32 s0, s4, 7
	v_and_b32_e32 v0, 7, v97
	v_or_b32_e32 v7, v1, v108
	v_lshrrev_b32_e32 v1, 3, v97
	v_readlane_b32 s4, v221, 5
	s_mul_i32 s41, s1, 0xc0
	v_bfe_u32 v115, v97, 5, 1
	v_bitop3_b32 v0, v1, v0, 3 bitop3:0x6c
	v_readlane_b32 s5, v221, 6
	v_xor_b32_e32 v8, v0, v115
	v_add_u32_e32 v3, s41, v6
	v_mov_b64_e32 v[0:1], s[4:5]
	s_movk_i32 s19, 0x1600
	v_mad_i64_i32 v[0:1], s[4:5], v3, s19, v[0:1]
	v_readlane_b32 s4, v220, 56
	v_readlane_b32 s5, v220, 57
	v_lshlrev_b32_e32 v98, 4, v2
	v_add_u32_e32 v9, s0, v6
	v_mov_b64_e32 v[2:3], s[4:5]
	v_lshlrev_b32_e32 v120, 4, v97
	v_mad_i64_i32 v[2:3], s[4:5], v9, s19, v[2:3]
	v_add_u32_e32 v121, 0, v120
	v_mov_b32_e32 v99, v96
	v_readfirstlane_b32 s4, v121
	v_add_u32_e32 v122, 0x1000, v121
	v_lshl_add_u64 v[0:1], v[0:1], 0, v[98:99]
	s_mov_b32 m0, s4
	s_mov_b64 s[42:43], 0x2c000
	v_readfirstlane_b32 s4, v122
	v_add_u32_e32 v123, 0x2000, v121
	global_load_lds_dwordx4 v[0:1], off
	v_lshl_add_u64 v[4:5], v[0:1], 0, s[42:43]
	s_mov_b32 m0, s4
	s_mov_b64 s[44:45], 0x58000
	v_readfirstlane_b32 s4, v123
	v_add_u32_e32 v124, 0x3000, v121
	global_load_lds_dwordx4 v[4:5], off
	v_lshl_add_u64 v[4:5], v[0:1], 0, s[44:45]
	s_mov_b32 m0, s4
	s_mov_b64 s[46:47], 0x84000
	v_readfirstlane_b32 s4, v124
	global_load_lds_dwordx4 v[4:5], off
	v_lshl_add_u64 v[4:5], v[0:1], 0, s[46:47]
	s_mov_b32 m0, s4
	s_mov_b64 s[4:5], 0xb0000
	v_add_u32_e32 v125, 0x4000, v121
	global_load_lds_dwordx4 v[4:5], off
	v_lshl_add_u64 v[4:5], v[0:1], 0, s[4:5]
	v_readfirstlane_b32 s4, v125
	s_mov_b32 m0, s4
	s_mov_b64 s[4:5], 0xdc000
	v_add_u32_e32 v126, 0x5000, v121
	v_lshl_add_u64 v[0:1], v[0:1], 0, s[4:5]
	v_readfirstlane_b32 s4, v126
	v_add_u32_e32 v127, 0xc000, v121
	global_load_lds_dwordx4 v[4:5], off
	s_mov_b32 m0, s4
	v_readfirstlane_b32 s4, v127
	v_add_u32_e32 v128, 0xd000, v121
	global_load_lds_dwordx4 v[0:1], off
	v_lshl_add_u64 v[0:1], v[2:3], 0, v[98:99]
	s_mov_b32 m0, s4
	v_readfirstlane_b32 s4, v128
	v_add_u32_e32 v129, 0xe000, v121
	global_load_lds_dwordx4 v[0:1], off
	v_lshl_add_u64 v[2:3], v[0:1], 0, s[42:43]
	s_mov_b32 m0, s4
	v_readfirstlane_b32 s4, v129
	v_add_u32_e32 v130, 0xf000, v121
	global_load_lds_dwordx4 v[2:3], off
	v_lshl_add_u64 v[2:3], v[0:1], 0, s[44:45]
	s_mov_b32 m0, s4
	v_readfirstlane_b32 s4, v130
	global_load_lds_dwordx4 v[2:3], off
	v_lshl_add_u64 v[0:1], v[0:1], 0, s[46:47]
	s_mov_b32 m0, s4
	s_mul_i32 s15, s15, 7
	global_load_lds_dwordx4 v[0:1], off
	s_add_i32 s17, s17, s15
	s_sub_i32 s4, s17, s18
	s_mul_i32 s16, s16, 7
	s_sub_i32 s4, s4, s16
	v_readlane_b32 s5, v218, 33
	v_lshlrev_b32_e32 v0, 7, v97
	s_mul_i32 s4, s5, s4
	v_and_b32_e32 v0, 0x2f80, v0
	s_add_i32 s4, s4, s39
	s_waitcnt vmcnt(0)
	v_add_u32_e32 v153, 0, v0
	v_add_u32_e32 v155, s10, v0
	v_add_u32_e32 v2, s4, v6
	v_mov_b64_e32 v[0:1], s[70:71]
	v_lshlrev_b32_e32 v154, 4, v8
	v_mad_i64_i32 v[100:101], s[4:5], v2, s19, v[0:1]
	v_mad_i64_i32 v[102:103], s[4:5], v9, s19, v[0:1]
	v_mov_b32_e32 v0, 0
	v_lshl_add_u32 v131, v7, 7, 0
	v_xor_b32_e32 v156, 32, v154
	v_xor_b32_e32 v157, 64, v154
	v_xor_b32_e32 v158, 0x60, v154
	s_mov_b32 s15, 0
	v_mov_b32_e32 v1, v0
	v_mov_b32_e32 v2, v0
	v_mov_b32_e32 v3, v0
	v_mov_b32_e32 v4, v0
	v_mov_b32_e32 v5, v0
	v_mov_b32_e32 v6, v0
	v_mov_b32_e32 v7, v0
	v_mov_b32_e32 v8, v0
	v_mov_b32_e32 v9, v0
	v_mov_b32_e32 v10, v0
	v_mov_b32_e32 v11, v0
	v_mov_b32_e32 v12, v0
	v_mov_b32_e32 v13, v0
	v_mov_b32_e32 v14, v0
	v_mov_b32_e32 v15, v0
	v_mov_b32_e32 v16, v0
	v_mov_b32_e32 v17, v0
	v_mov_b32_e32 v18, v0
	v_mov_b32_e32 v19, v0
	v_mov_b32_e32 v20, v0
	v_mov_b32_e32 v21, v0
	v_mov_b32_e32 v22, v0
	v_mov_b32_e32 v23, v0
	v_mov_b32_e32 v24, v0
	v_mov_b32_e32 v25, v0
	v_mov_b32_e32 v26, v0
	v_mov_b32_e32 v27, v0
	v_mov_b32_e32 v28, v0
	v_mov_b32_e32 v29, v0
	v_mov_b32_e32 v30, v0
	v_mov_b32_e32 v31, v0
	v_mov_b32_e32 v32, v0
	v_mov_b32_e32 v33, v0
	v_mov_b32_e32 v34, v0
	v_mov_b32_e32 v35, v0
	v_mov_b32_e32 v36, v0
	v_mov_b32_e32 v37, v0
	v_mov_b32_e32 v38, v0
	v_mov_b32_e32 v39, v0
	v_mov_b32_e32 v40, v0
	v_mov_b32_e32 v41, v0
	v_mov_b32_e32 v42, v0
	v_mov_b32_e32 v43, v0
	v_mov_b32_e32 v44, v0
	v_mov_b32_e32 v45, v0
	v_mov_b32_e32 v46, v0
	v_mov_b32_e32 v47, v0
	v_mov_b32_e32 v48, v0
	s_waitcnt vmcnt(0)
; template <int EPI, int MI>
; DI void gemm_tile(const GemmDesc& g, int tm, int tn, char* smem) {
;     ...
;   f32x16 acc[MI][2];
; #pragma unroll
;   for (int a = 0; a < MI; ++a)
; #pragma unroll
;     for (int b = 0; b < 2; ++b)
; #pragma unroll
;       for (int i = 0; i < 16; ++i) acc[a][b][i] = 0.f;
;   const int srow = tid >> 3;
;   const int schunk = (tid & 7) ^ ((srow & 7) ^ ((srow >> 3) & 3));
;     ...
;   const int rowA = wm * (32 * MI) + r, rowB = wn * 64 + r;
;   const int hk = hh ^ ((r & 7) ^ ((r >> 3) & 3));
;     ...
;   G_GLDS(0, 0);
;   asm volatile("s_waitcnt vmcnt(0)" ::: "memory");
;   __syncthreads();
;   for (int kt = 0; kt < nk; kt += 2) {
;     if (kt + 1 < nk) G_GLDS(kt + 1, 1);
;     G_COMPUTE(0);
;     asm volatile("s_waitcnt vmcnt(0)" ::: "memory");
;     __syncthreads();
;     if (kt + 1 < nk) {
;       if (kt + 2 < nk) G_GLDS(kt + 2, 0);
;       G_COMPUTE(1);
;       asm volatile("s_waitcnt vmcnt(0)" ::: "memory");
;       __syncthreads();
;     }
;   }
	v_mov_b32_e32 v49, v0
	v_mov_b32_e32 v50, v0
	v_mov_b32_e32 v51, v0
	v_mov_b32_e32 v52, v0
	v_mov_b32_e32 v53, v0
	v_mov_b32_e32 v54, v0
	v_mov_b32_e32 v55, v0
	v_mov_b32_e32 v56, v0
	v_mov_b32_e32 v57, v0
	v_mov_b32_e32 v58, v0
	v_mov_b32_e32 v59, v0
	v_mov_b32_e32 v60, v0
	v_mov_b32_e32 v61, v0
	v_mov_b32_e32 v62, v0
	v_mov_b32_e32 v63, v0
	v_mov_b32_e32 v64, v0
	v_mov_b32_e32 v65, v0
	v_mov_b32_e32 v66, v0
	v_mov_b32_e32 v67, v0
	v_mov_b32_e32 v68, v0
	v_mov_b32_e32 v69, v0
	v_mov_b32_e32 v70, v0
	v_mov_b32_e32 v71, v0
	v_mov_b32_e32 v72, v0
	v_mov_b32_e32 v73, v0
	v_mov_b32_e32 v74, v0
	v_mov_b32_e32 v75, v0
	v_mov_b32_e32 v76, v0
	v_mov_b32_e32 v77, v0
	v_mov_b32_e32 v78, v0
	v_mov_b32_e32 v79, v0
	v_mov_b32_e32 v80, v0
	v_mov_b32_e32 v81, v0
	v_mov_b32_e32 v82, v0
	v_mov_b32_e32 v83, v0
	v_mov_b32_e32 v84, v0
	v_mov_b32_e32 v85, v0
	v_mov_b32_e32 v86, v0
	v_mov_b32_e32 v87, v0
	v_mov_b32_e32 v88, v0
	v_mov_b32_e32 v89, v0
	v_mov_b32_e32 v90, v0
	v_mov_b32_e32 v91, v0
	v_mov_b32_e32 v92, v0
	v_mov_b32_e32 v93, v0
	v_mov_b32_e32 v94, v0
	v_mov_b32_e32 v95, v0
	v_add_u32_e32 v162, v131, v154
	v_add_u32_e32 v163, v131, v156
	v_add_u32_e32 v164, v131, v157
	v_add_u32_e32 v165, v131, v158
	v_add_u32_e32 v166, v153, v154
	v_add_u32_e32 v167, v153, v156
	v_add_u32_e32 v168, v153, v157
	v_add_u32_e32 v169, v153, v158
	v_add_u32_e32 v170, v155, v154
	v_add_u32_e32 v171, v155, v156
	v_add_u32_e32 v172, v155, v157
	v_add_u32_e32 v173, v155, v158
	v_lshl_add_u64 v[252:253], v[100:101], 0, v[98:99]
	v_lshl_add_u64 v[254:255], v[102:103], 0, v[98:99]
	v_readfirstlane_b32 s100, v121
	s_mov_b64 s[4:5], 0x80
	s_waitcnt vmcnt(0) lgkmcnt(0)
	s_barrier
	ds_read_b128 v[236:239], v166 offset:49152
	ds_read_b128 v[240:243], v166 offset:53248
	ds_read_b128 v[224:227], v162
	ds_read_b128 v[228:231], v162 offset:4096
	s_mov_b32 s15, 0
.Lge_loop:
	ds_read_b128 v[232:235], v162 offset:8192
	s_waitcnt lgkmcnt(2)
	v_mfma_f32_32x32x16_bf16 v[80:95], v[224:227], v[236:239], v[80:95]
	v_mfma_f32_32x32x16_bf16 v[64:79], v[224:227], v[240:243], v[64:79]
	s_mov_b64 s[16:17], 0x5872080
	s_add_u32 m0, s100, 0x6000
	v_lshl_add_u64 v[106:107], v[252:253], 0, s[16:17]
	global_load_lds_dwordx4 v[106:107], off
	ds_read_b128 v[244:247], v167 offset:49152
	ds_read_b128 v[248:251], v167 offset:53248
	ds_read_b128 v[224:227], v163
	s_waitcnt lgkmcnt(4)
	v_mfma_f32_32x32x16_bf16 v[48:63], v[228:231], v[236:239], v[48:63]
	v_mfma_f32_32x32x16_bf16 v[32:47], v[228:231], v[240:243], v[32:47]
	s_mov_b64 s[16:17], 0x589e080
	s_add_u32 m0, s100, 0x7000
	v_lshl_add_u64 v[106:107], v[252:253], 0, s[16:17]
	global_load_lds_dwordx4 v[106:107], off
	ds_read_b128 v[228:231], v163 offset:4096
	s_waitcnt lgkmcnt(4)
	v_mfma_f32_32x32x16_bf16 v[16:31], v[232:235], v[236:239], v[16:31]
	v_mfma_f32_32x32x16_bf16 v[0:15], v[232:235], v[240:243], v[0:15]
	s_mov_b64 s[16:17], 0x58ca080
	s_add_u32 m0, s100, 0x8000
	v_lshl_add_u64 v[106:107], v[252:253], 0, s[16:17]
	global_load_lds_dwordx4 v[106:107], off
	ds_read_b128 v[232:235], v163 offset:8192
	s_waitcnt lgkmcnt(2)
	v_mfma_f32_32x32x16_bf16 v[80:95], v[224:227], v[244:247], v[80:95]
	v_mfma_f32_32x32x16_bf16 v[64:79], v[224:227], v[248:251], v[64:79]
	s_mov_b64 s[16:17], 0x58f6080
	s_add_u32 m0, s100, 0x9000
	v_lshl_add_u64 v[106:107], v[252:253], 0, s[16:17]
	global_load_lds_dwordx4 v[106:107], off
	ds_read_b128 v[236:239], v168 offset:49152
	ds_read_b128 v[240:243], v168 offset:53248
	ds_read_b128 v[224:227], v164
	s_waitcnt lgkmcnt(4)
	v_mfma_f32_32x32x16_bf16 v[48:63], v[228:231], v[244:247], v[48:63]
	v_mfma_f32_32x32x16_bf16 v[32:47], v[228:231], v[248:251], v[32:47]
	s_mov_b64 s[16:17], 0x5922080
	s_add_u32 m0, s100, 0xa000
	v_lshl_add_u64 v[106:107], v[252:253], 0, s[16:17]
	global_load_lds_dwordx4 v[106:107], off
	ds_read_b128 v[228:231], v164 offset:4096
	s_waitcnt lgkmcnt(4)
	v_mfma_f32_32x32x16_bf16 v[16:31], v[232:235], v[244:247], v[16:31]
	v_mfma_f32_32x32x16_bf16 v[0:15], v[232:235], v[248:251], v[0:15]
	s_mov_b64 s[16:17], 0x594e080
	s_add_u32 m0, s100, 0xb000
	v_lshl_add_u64 v[106:107], v[252:253], 0, s[16:17]
	global_load_lds_dwordx4 v[106:107], off
	v_lshl_add_u64 v[252:253], v[252:253], 0, s[4:5]
	ds_read_b128 v[232:235], v164 offset:8192
	s_waitcnt lgkmcnt(2)
	v_mfma_f32_32x32x16_bf16 v[80:95], v[224:227], v[236:239], v[80:95]
	v_mfma_f32_32x32x16_bf16 v[64:79], v[224:227], v[240:243], v[64:79]
	s_mov_b64 s[16:17], 0x1b80080
	s_add_u32 m0, s100, 0x10000
	v_lshl_add_u64 v[106:107], v[254:255], 0, s[16:17]
	global_load_lds_dwordx4 v[106:107], off
	ds_read_b128 v[244:247], v169 offset:49152
	ds_read_b128 v[248:251], v169 offset:53248
	ds_read_b128 v[224:227], v165
	s_waitcnt lgkmcnt(4)
	v_mfma_f32_32x32x16_bf16 v[48:63], v[228:231], v[236:239], v[48:63]
	v_mfma_f32_32x32x16_bf16 v[32:47], v[228:231], v[240:243], v[32:47]
	s_mov_b64 s[16:17], 0x1bac080
	s_add_u32 m0, s100, 0x11000
	v_lshl_add_u64 v[106:107], v[254:255], 0, s[16:17]
	global_load_lds_dwordx4 v[106:107], off
	ds_read_b128 v[228:231], v165 offset:4096
	s_waitcnt lgkmcnt(4)
	v_mfma_f32_32x32x16_bf16 v[16:31], v[232:235], v[236:239], v[16:31]
	v_mfma_f32_32x32x16_bf16 v[0:15], v[232:235], v[240:243], v[0:15]
	s_mov_b64 s[16:17], 0x1bd8080
	s_add_u32 m0, s100, 0x12000
	v_lshl_add_u64 v[106:107], v[254:255], 0, s[16:17]
	global_load_lds_dwordx4 v[106:107], off
	ds_read_b128 v[232:235], v165 offset:8192
	s_waitcnt lgkmcnt(2)
	v_mfma_f32_32x32x16_bf16 v[80:95], v[224:227], v[244:247], v[80:95]
	v_mfma_f32_32x32x16_bf16 v[64:79], v[224:227], v[248:251], v[64:79]
	s_mov_b64 s[16:17], 0x1c04080
	s_add_u32 m0, s100, 0x13000
	v_lshl_add_u64 v[106:107], v[254:255], 0, s[16:17]
	global_load_lds_dwordx4 v[106:107], off
	v_lshl_add_u64 v[254:255], v[254:255], 0, s[4:5]
	s_waitcnt lgkmcnt(0)
	s_waitcnt vmcnt(0)
	s_barrier
; template <int EPI, int MI>
; DI void gemm_tile(const GemmDesc& g, int tm, int tn, char* smem) {
;     ...
;   G_GLDS(0, 0);
;   asm volatile("s_waitcnt vmcnt(0)" ::: "memory");
;   __syncthreads();
;   for (int kt = 0; kt < nk; kt += 2) {
;     if (kt + 1 < nk) G_GLDS(kt + 1, 1);
;     G_COMPUTE(0);
;     asm volatile("s_waitcnt vmcnt(0)" ::: "memory");
;     __syncthreads();
;     if (kt + 1 < nk) {
;       if (kt + 2 < nk) G_GLDS(kt + 2, 0);
;       G_COMPUTE(1);
;       asm volatile("s_waitcnt vmcnt(0)" ::: "memory");
;       __syncthreads();
;     }
;   }
	ds_read_b128 v[236:239], v170
	ds_read_b128 v[240:243], v170 offset:4096
	ds_read_b128 v[224:227], v162 offset:24576
	v_mfma_f32_32x32x16_bf16 v[48:63], v[228:231], v[244:247], v[48:63]
	v_mfma_f32_32x32x16_bf16 v[32:47], v[228:231], v[248:251], v[32:47]
	ds_read_b128 v[228:231], v162 offset:28672
	v_mfma_f32_32x32x16_bf16 v[16:31], v[232:235], v[244:247], v[16:31]
	v_mfma_f32_32x32x16_bf16 v[0:15], v[232:235], v[248:251], v[0:15]
	s_cmp_eq_u32 s15, 42
	s_cbranch_scc1 .Lge_last
	ds_read_b128 v[232:235], v162 offset:32768
	s_waitcnt lgkmcnt(2)
	v_mfma_f32_32x32x16_bf16 v[80:95], v[224:227], v[236:239], v[80:95]
	v_mfma_f32_32x32x16_bf16 v[64:79], v[224:227], v[240:243], v[64:79]
	s_mov_b64 s[16:17], 0x5872080
	s_mov_b32 m0, s100
	v_lshl_add_u64 v[106:107], v[252:253], 0, s[16:17]
	global_load_lds_dwordx4 v[106:107], off
	ds_read_b128 v[244:247], v171
	ds_read_b128 v[248:251], v171 offset:4096
	ds_read_b128 v[224:227], v163 offset:24576
	s_waitcnt lgkmcnt(4)
	v_mfma_f32_32x32x16_bf16 v[48:63], v[228:231], v[236:239], v[48:63]
	v_mfma_f32_32x32x16_bf16 v[32:47], v[228:231], v[240:243], v[32:47]
	s_mov_b64 s[16:17], 0x589e080
	s_add_u32 m0, s100, 0x1000
	v_lshl_add_u64 v[106:107], v[252:253], 0, s[16:17]
	global_load_lds_dwordx4 v[106:107], off
	ds_read_b128 v[228:231], v163 offset:28672
	s_waitcnt lgkmcnt(4)
	v_mfma_f32_32x32x16_bf16 v[16:31], v[232:235], v[236:239], v[16:31]
	v_mfma_f32_32x32x16_bf16 v[0:15], v[232:235], v[240:243], v[0:15]
	s_mov_b64 s[16:17], 0x58ca080
	s_add_u32 m0, s100, 0x2000
	v_lshl_add_u64 v[106:107], v[252:253], 0, s[16:17]
	global_load_lds_dwordx4 v[106:107], off
	ds_read_b128 v[232:235], v163 offset:32768
	s_waitcnt lgkmcnt(2)
	v_mfma_f32_32x32x16_bf16 v[80:95], v[224:227], v[244:247], v[80:95]
	v_mfma_f32_32x32x16_bf16 v[64:79], v[224:227], v[248:251], v[64:79]
	s_mov_b64 s[16:17], 0x58f6080
	s_add_u32 m0, s100, 0x3000
	v_lshl_add_u64 v[106:107], v[252:253], 0, s[16:17]
	global_load_lds_dwordx4 v[106:107], off
	ds_read_b128 v[236:239], v172
	ds_read_b128 v[240:243], v172 offset:4096
	ds_read_b128 v[224:227], v164 offset:24576
	s_waitcnt lgkmcnt(4)
	v_mfma_f32_32x32x16_bf16 v[48:63], v[228:231], v[244:247], v[48:63]
	v_mfma_f32_32x32x16_bf16 v[32:47], v[228:231], v[248:251], v[32:47]
	s_mov_b64 s[16:17], 0x5922080
	s_add_u32 m0, s100, 0x4000
	v_lshl_add_u64 v[106:107], v[252:253], 0, s[16:17]
	global_load_lds_dwordx4 v[106:107], off
	ds_read_b128 v[228:231], v164 offset:28672
	s_waitcnt lgkmcnt(4)
	v_mfma_f32_32x32x16_bf16 v[16:31], v[232:235], v[244:247], v[16:31]
	v_mfma_f32_32x32x16_bf16 v[0:15], v[232:235], v[248:251], v[0:15]
	s_mov_b64 s[16:17], 0x594e080
	s_add_u32 m0, s100, 0x5000
	v_lshl_add_u64 v[106:107], v[252:253], 0, s[16:17]
	global_load_lds_dwordx4 v[106:107], off
	v_lshl_add_u64 v[252:253], v[252:253], 0, s[4:5]
	ds_read_b128 v[232:235], v164 offset:32768
	s_waitcnt lgkmcnt(2)
	v_mfma_f32_32x32x16_bf16 v[80:95], v[224:227], v[236:239], v[80:95]
	v_mfma_f32_32x32x16_bf16 v[64:79], v[224:227], v[240:243], v[64:79]
	s_mov_b64 s[16:17], 0x1b80080
	s_add_u32 m0, s100, 0xc000
	v_lshl_add_u64 v[106:107], v[254:255], 0, s[16:17]
	global_load_lds_dwordx4 v[106:107], off
	ds_read_b128 v[244:247], v173
	ds_read_b128 v[248:251], v173 offset:4096
	ds_read_b128 v[224:227], v165 offset:24576
	s_waitcnt lgkmcnt(4)
	v_mfma_f32_32x32x16_bf16 v[48:63], v[228:231], v[236:239], v[48:63]
	v_mfma_f32_32x32x16_bf16 v[32:47], v[228:231], v[240:243], v[32:47]
	s_mov_b64 s[16:17], 0x1bac080
	s_add_u32 m0, s100, 0xd000
	v_lshl_add_u64 v[106:107], v[254:255], 0, s[16:17]
	global_load_lds_dwordx4 v[106:107], off
	ds_read_b128 v[228:231], v165 offset:28672
	s_waitcnt lgkmcnt(4)
	v_mfma_f32_32x32x16_bf16 v[16:31], v[232:235], v[236:239], v[16:31]
	v_mfma_f32_32x32x16_bf16 v[0:15], v[232:235], v[240:243], v[0:15]
	s_mov_b64 s[16:17], 0x1bd8080
	s_add_u32 m0, s100, 0xe000
	v_lshl_add_u64 v[106:107], v[254:255], 0, s[16:17]
	global_load_lds_dwordx4 v[106:107], off
	ds_read_b128 v[232:235], v165 offset:32768
	s_waitcnt lgkmcnt(2)
	v_mfma_f32_32x32x16_bf16 v[80:95], v[224:227], v[244:247], v[80:95]
	v_mfma_f32_32x32x16_bf16 v[64:79], v[224:227], v[248:251], v[64:79]
	s_mov_b64 s[16:17], 0x1c04080
	s_add_u32 m0, s100, 0xf000
	v_lshl_add_u64 v[106:107], v[254:255], 0, s[16:17]
	global_load_lds_dwordx4 v[106:107], off
	v_lshl_add_u64 v[254:255], v[254:255], 0, s[4:5]
	s_waitcnt lgkmcnt(0)
	s_waitcnt vmcnt(0)
	s_barrier
	ds_read_b128 v[236:239], v166 offset:49152
	ds_read_b128 v[240:243], v166 offset:53248
	ds_read_b128 v[224:227], v162
	v_mfma_f32_32x32x16_bf16 v[48:63], v[228:231], v[244:247], v[48:63]
	v_mfma_f32_32x32x16_bf16 v[32:47], v[228:231], v[248:251], v[32:47]
	ds_read_b128 v[228:231], v162 offset:4096
	v_mfma_f32_32x32x16_bf16 v[16:31], v[232:235], v[244:247], v[16:31]
	v_mfma_f32_32x32x16_bf16 v[0:15], v[232:235], v[248:251], v[0:15]
	s_add_u32 s15, s15, 2
	s_branch .Lge_loop
; template <int EPI, int MI>
; DI void gemm_tile(const GemmDesc& g, int tm, int tn, char* smem) {
;     ...
;   for (int kt = 0; kt < nk; kt += 2) {
;     if (kt + 1 < nk) G_GLDS(kt + 1, 1);
;     G_COMPUTE(0);
;     asm volatile("s_waitcnt vmcnt(0)" ::: "memory");
;     __syncthreads();
;     if (kt + 1 < nk) {
;       if (kt + 2 < nk) G_GLDS(kt + 2, 0);
;       G_COMPUTE(1);
;       asm volatile("s_waitcnt vmcnt(0)" ::: "memory");
;       __syncthreads();
;     }
;   }
;     ...
;   } else if (EPI == EPI_RES) {
;     float* es = (float*)smem;
;     const int c4 = (tid & 31) * 4;
;     const int rgA = m0 < LAT ? (m0 >> 11) : 8;
;     const int mlast = m0 + BM - 1;
;     const int rgB = mlast < LAT ? (mlast >> 11) : 8;
;     const f32x4v m4a = *(const f32x4v*)(g.mod + (size_t)rgA * 9216 + g.gidx * 1024 + n0 + c4);
;     const f32x4v m4b = *(const f32x4v*)(g.mod + (size_t)rgB * 9216 + g.gidx * 1024 + n0 + c4);
; #pragma unroll
;     for (int mi = 0; mi < MI; ++mi) {
; #pragma unroll
;       for (int ni = 0; ni < 2; ++ni)
; #pragma unroll
;         for (int i = 0; i < 16; ++i) {
;           const int lrow = wm * 32 + (i & 3) + 8 * (i >> 2) + 4 * hh;
;           es[lrow * 128 + wn * 64 + ni * 32 + r] = acc[mi][ni][i];
;         }
;       __syncthreads();
; #pragma unroll 4
;       for (int j = 0; j < 8; ++j) {
;         const int lrow = (tid >> 5) + 8 * j;
;         const int grow = m0 + (lrow >> 5) * (32 * MI) + mi * 32 + (lrow & 31);
;         const f32x4v a4 = *(const f32x4v*)(es + lrow * 128 + c4);
;         const int rg = grow < LAT ? (grow >> 11) : 8;
;         const f32x4v m4 = rg == rgA ? m4a : m4b;
;         float* rp = (grow < LAT ? g.xres + (size_t)grow * 1024 : g.hres + (size_t)(grow - LAT) * 1024) + n0 + c4;
;         f32x4v x4 = *(const f32x4v*)rp;
.Lge_last:
	ds_read_b128 v[232:235], v162 offset:32768
	s_waitcnt lgkmcnt(2)
	v_mfma_f32_32x32x16_bf16 v[80:95], v[224:227], v[236:239], v[80:95]
	v_mfma_f32_32x32x16_bf16 v[64:79], v[224:227], v[240:243], v[64:79]
	ds_read_b128 v[244:247], v171
	ds_read_b128 v[248:251], v171 offset:4096
	ds_read_b128 v[224:227], v163 offset:24576
	s_waitcnt lgkmcnt(4)
	v_mfma_f32_32x32x16_bf16 v[48:63], v[228:231], v[236:239], v[48:63]
	v_mfma_f32_32x32x16_bf16 v[32:47], v[228:231], v[240:243], v[32:47]
	ds_read_b128 v[228:231], v163 offset:28672
	s_waitcnt lgkmcnt(4)
	v_mfma_f32_32x32x16_bf16 v[16:31], v[232:235], v[236:239], v[16:31]
	v_mfma_f32_32x32x16_bf16 v[0:15], v[232:235], v[240:243], v[0:15]
	ds_read_b128 v[232:235], v163 offset:32768
	s_waitcnt lgkmcnt(2)
	v_mfma_f32_32x32x16_bf16 v[80:95], v[224:227], v[244:247], v[80:95]
	v_mfma_f32_32x32x16_bf16 v[64:79], v[224:227], v[248:251], v[64:79]
	ds_read_b128 v[236:239], v172
	ds_read_b128 v[240:243], v172 offset:4096
	ds_read_b128 v[224:227], v164 offset:24576
	s_waitcnt lgkmcnt(4)
	v_mfma_f32_32x32x16_bf16 v[48:63], v[228:231], v[244:247], v[48:63]
	v_mfma_f32_32x32x16_bf16 v[32:47], v[228:231], v[248:251], v[32:47]
	ds_read_b128 v[228:231], v164 offset:28672
	s_waitcnt lgkmcnt(4)
	v_mfma_f32_32x32x16_bf16 v[16:31], v[232:235], v[244:247], v[16:31]
	v_mfma_f32_32x32x16_bf16 v[0:15], v[232:235], v[248:251], v[0:15]
	ds_read_b128 v[232:235], v164 offset:32768
	s_waitcnt lgkmcnt(2)
	v_mfma_f32_32x32x16_bf16 v[80:95], v[224:227], v[236:239], v[80:95]
	v_mfma_f32_32x32x16_bf16 v[64:79], v[224:227], v[240:243], v[64:79]
	ds_read_b128 v[244:247], v173
	ds_read_b128 v[248:251], v173 offset:4096
	ds_read_b128 v[224:227], v165 offset:24576
	s_waitcnt lgkmcnt(4)
	v_mfma_f32_32x32x16_bf16 v[48:63], v[228:231], v[236:239], v[48:63]
	v_mfma_f32_32x32x16_bf16 v[32:47], v[228:231], v[240:243], v[32:47]
	ds_read_b128 v[228:231], v165 offset:28672
	s_waitcnt lgkmcnt(4)
	v_mfma_f32_32x32x16_bf16 v[16:31], v[232:235], v[236:239], v[16:31]
	v_mfma_f32_32x32x16_bf16 v[0:15], v[232:235], v[240:243], v[0:15]
	ds_read_b128 v[232:235], v165 offset:32768
	s_waitcnt lgkmcnt(2)
	v_mfma_f32_32x32x16_bf16 v[80:95], v[224:227], v[244:247], v[80:95]
	v_mfma_f32_32x32x16_bf16 v[64:79], v[224:227], v[248:251], v[64:79]
	s_waitcnt lgkmcnt(0)
	s_barrier
	v_mfma_f32_32x32x16_bf16 v[48:63], v[228:231], v[244:247], v[48:63]
	v_mfma_f32_32x32x16_bf16 v[32:47], v[228:231], v[248:251], v[32:47]
	v_mfma_f32_32x32x16_bf16 v[16:31], v[232:235], v[244:247], v[16:31]
	v_mfma_f32_32x32x16_bf16 v[0:15], v[232:235], v[248:251], v[0:15]
	s_branch .LBB0_1495
.LBB0_1495:
	s_ashr_i32 s4, s41, 11
	s_cmpk_lt_i32 s1, 0x56
	s_cselect_b32 s15, s4, 8
	s_add_i32 s4, s41, 0xbf
	s_ashr_i32 s4, s4, 11
	s_cmpk_lt_i32 s1, 0x55
	s_cselect_b32 s16, s4, 8
	s_mul_i32 s4, s15, 0x9000
	s_mul_hi_i32 s1, s15, 0x9000
	s_add_u32 s17, s20, s4
	s_addc_u32 s18, s38, s1
	s_ashr_i32 s1, s0, 31
	v_lshlrev_b32_e32 v98, 2, v97
	s_lshl_b64 s[4:5], s[0:1], 2
	v_and_b32_e32 v106, 0x7c, v98
	s_add_u32 s0, s17, s4
	s_addc_u32 s1, s18, s5
	v_lshlrev_b32_e32 v102, 2, v106
	global_load_dwordx4 v[98:101], v102, s[0:1]
	s_mul_hi_i32 s0, s16, 0x9000
	s_mul_i32 s16, s16, 0x9000
	s_add_u32 s1, s20, s16
	s_addc_u32 s16, s38, s0
	s_add_u32 s0, s1, s4
	s_addc_u32 s1, s16, s5
	global_load_dwordx4 v[102:105], v102, s[0:1]
	v_and_b32_e32 v107, 64, v97
	v_lshlrev_b32_e32 v115, 11, v115
	v_lshlrev_b32_e32 v107, 2, v107
	v_lshlrev_b32_e32 v109, 14, v109
	v_add3_u32 v107, 0, v115, v107
	v_lshlrev_b32_e32 v115, 2, v108
	v_ashrrev_i32_e32 v97, 5, v97
	v_add3_u32 v107, v107, v115, v109
	ds_write2_b32 v107, v80, v64 offset1:32
	ds_write2_b32 v107, v81, v65 offset0:128 offset1:160
	v_add_u32_e32 v80, 0x400, v107
	v_add_u32_e32 v64, 8, v97
	ds_write2_b32 v80, v82, v66 offset1:32
	ds_write2_b32 v80, v83, v67 offset0:128 offset1:160
	v_add_u32_e32 v81, 0x1000, v107
	v_add_u32_e32 v82, 0x1400, v107
	v_and_b32_e32 v67, 31, v64
	v_add_u32_e32 v64, 24, v97
	ds_write2_b32 v81, v84, v68 offset1:32
	ds_write2_b32 v81, v85, v69 offset0:128 offset1:160
	ds_write2_b32 v82, v86, v70 offset1:32
	ds_write2_b32 v82, v87, v71 offset0:128 offset1:160
	v_add_u32_e32 v71, 0x2000, v107
	v_and_b32_e32 v69, 31, v64
	v_lshlrev_b32_e32 v64, 4, v108
	ds_write2_b32 v71, v88, v72 offset1:32
	ds_write2_b32 v71, v89, v73 offset0:128 offset1:160
	v_add_u32_e32 v72, 0x2400, v107
	v_lshl_or_b32 v64, v97, 9, v64
	ds_write2_b32 v72, v90, v74 offset1:32
	ds_write2_b32 v72, v91, v75 offset0:128 offset1:160
	v_add_u32_e32 v73, 0x3000, v107
	v_add_u32_e32 v74, 0x3400, v107
	v_and_b32_e32 v66, 31, v97
	v_bitop3_b32 v68, v97, 16, 31 bitop3:0x6c
	v_add_u32_e32 v70, 0, v64
	s_mov_b32 s16, 0
	v_mov_b32_e32 v75, v97
	ds_write2_b32 v73, v92, v76 offset1:32
	ds_write2_b32 v73, v93, v77 offset0:128 offset1:160
	ds_write2_b32 v74, v94, v78 offset1:32
	ds_write2_b32 v74, v95, v79 offset0:128 offset1:160
	v_lshlrev_b32_e32 v64, 2, v106
	v_mov_b32_e32 v65, 0
	s_mov_b32 s16, s41
	v_or_b32_e32 v224, s16, v66
	v_mov_b32_e32 v226, s68
	v_mov_b32_e32 v227, s69
	v_mov_b32_e32 v162, s3
	v_mov_b32_e32 v163, s33
	v_cmp_gt_i32_e32 vcc, s8, v224
	v_add_u32_e32 v225, 0xffffc000, v224
	s_nop 0
	v_cndmask_b32_e32 v224, v225, v224, vcc
	v_cndmask_b32_e32 v226, v162, v226, vcc
	v_cndmask_b32_e32 v227, v163, v227, vcc
	v_mov_b32_e32 v225, 0
	v_lshlrev_b64 v[224:225], 12, v[224:225]
	v_lshl_add_u64 v[224:225], v[226:227], 0, v[224:225]
	v_lshl_add_u64 v[224:225], v[224:225], 0, s[4:5]
	v_lshl_add_u64 v[162:163], v[224:225], 0, v[64:65]
	global_load_dwordx4 v[224:227], v[162:163], off
	v_or_b32_e32 v228, s16, v67
	v_mov_b32_e32 v230, s68
	v_mov_b32_e32 v231, s69
; template <int EPI, int MI>
; DI void gemm_tile(const GemmDesc& g, int tm, int tn, char* smem) {
;     ...
; #pragma unroll 4
;       for (int j = 0; j < 8; ++j) {
;         const int lrow = (tid >> 5) + 8 * j;
;         const int grow = m0 + (lrow >> 5) * (32 * MI) + mi * 32 + (lrow & 31);
;         const f32x4v a4 = *(const f32x4v*)(es + lrow * 128 + c4);
;         const int rg = grow < LAT ? (grow >> 11) : 8;
;         const f32x4v m4 = rg == rgA ? m4a : m4b;
;         float* rp = (grow < LAT ? g.xres + (size_t)grow * 1024 : g.hres + (size_t)(grow - LAT) * 1024) + n0 + c4;
;         f32x4v x4 = *(const f32x4v*)rp;
;         x4 += (m4 * a4) * g.coef;
;         *(f32x4v*)rp = x4;
;       }
	v_mov_b32_e32 v164, s3
	v_mov_b32_e32 v165, s33
	v_cmp_gt_i32_e32 vcc, s8, v228
	v_add_u32_e32 v229, 0xffffc000, v228
	s_nop 0
	v_cndmask_b32_e32 v228, v229, v228, vcc
	v_cndmask_b32_e32 v230, v164, v230, vcc
	v_cndmask_b32_e32 v231, v165, v231, vcc
	v_mov_b32_e32 v229, 0
	v_lshlrev_b64 v[228:229], 12, v[228:229]
	v_lshl_add_u64 v[228:229], v[230:231], 0, v[228:229]
	v_lshl_add_u64 v[228:229], v[228:229], 0, s[4:5]
	v_lshl_add_u64 v[164:165], v[228:229], 0, v[64:65]
	global_load_dwordx4 v[228:231], v[164:165], off
	v_or_b32_e32 v232, s16, v68
	v_mov_b32_e32 v234, s68
	v_mov_b32_e32 v235, s69
	v_mov_b32_e32 v166, s3
	v_mov_b32_e32 v167, s33
	v_cmp_gt_i32_e32 vcc, s8, v232
	v_add_u32_e32 v233, 0xffffc000, v232
	s_nop 0
	v_cndmask_b32_e32 v232, v233, v232, vcc
	v_cndmask_b32_e32 v234, v166, v234, vcc
	v_cndmask_b32_e32 v235, v167, v235, vcc
	v_mov_b32_e32 v233, 0
	v_lshlrev_b64 v[232:233], 12, v[232:233]
	v_lshl_add_u64 v[232:233], v[234:235], 0, v[232:233]
	v_lshl_add_u64 v[232:233], v[232:233], 0, s[4:5]
	v_lshl_add_u64 v[166:167], v[232:233], 0, v[64:65]
	global_load_dwordx4 v[232:235], v[166:167], off
	v_or_b32_e32 v236, s16, v69
	v_mov_b32_e32 v238, s68
	v_mov_b32_e32 v239, s69
	v_mov_b32_e32 v168, s3
	v_mov_b32_e32 v169, s33
	v_cmp_gt_i32_e32 vcc, s8, v236
	v_add_u32_e32 v237, 0xffffc000, v236
	s_nop 0
	v_cndmask_b32_e32 v236, v237, v236, vcc
	v_cndmask_b32_e32 v238, v168, v238, vcc
	v_cndmask_b32_e32 v239, v169, v239, vcc
	v_mov_b32_e32 v237, 0
	v_lshlrev_b64 v[236:237], 12, v[236:237]
	v_lshl_add_u64 v[236:237], v[238:239], 0, v[236:237]
	v_lshl_add_u64 v[236:237], v[236:237], 0, s[4:5]
	v_lshl_add_u64 v[168:169], v[236:237], 0, v[64:65]
	global_load_dwordx4 v[236:239], v[168:169], off
	s_add_u32 s16, s41, 96
	v_or_b32_e32 v240, s16, v66
	v_mov_b32_e32 v242, s68
	v_mov_b32_e32 v243, s69
	v_mov_b32_e32 v170, s3
	v_mov_b32_e32 v171, s33
	v_cmp_gt_i32_e32 vcc, s8, v240
	v_add_u32_e32 v241, 0xffffc000, v240
	s_nop 0
	v_cndmask_b32_e32 v240, v241, v240, vcc
	v_cndmask_b32_e32 v242, v170, v242, vcc
	v_cndmask_b32_e32 v243, v171, v243, vcc
	v_mov_b32_e32 v241, 0
	v_lshlrev_b64 v[240:241], 12, v[240:241]
	v_lshl_add_u64 v[240:241], v[242:243], 0, v[240:241]
	v_lshl_add_u64 v[240:241], v[240:241], 0, s[4:5]
	v_lshl_add_u64 v[170:171], v[240:241], 0, v[64:65]
	global_load_dwordx4 v[240:243], v[170:171], off
	v_or_b32_e32 v244, s16, v67
	v_mov_b32_e32 v246, s68
	v_mov_b32_e32 v247, s69
	v_mov_b32_e32 v172, s3
	v_mov_b32_e32 v173, s33
	v_cmp_gt_i32_e32 vcc, s8, v244
	v_add_u32_e32 v245, 0xffffc000, v244
	s_nop 0
	v_cndmask_b32_e32 v244, v245, v244, vcc
	v_cndmask_b32_e32 v246, v172, v246, vcc
	v_cndmask_b32_e32 v247, v173, v247, vcc
	v_mov_b32_e32 v245, 0
	v_lshlrev_b64 v[244:245], 12, v[244:245]
	v_lshl_add_u64 v[244:245], v[246:247], 0, v[244:245]
	v_lshl_add_u64 v[244:245], v[244:245], 0, s[4:5]
	v_lshl_add_u64 v[172:173], v[244:245], 0, v[64:65]
	global_load_dwordx4 v[244:247], v[172:173], off
	v_or_b32_e32 v248, s16, v68
	v_mov_b32_e32 v250, s68
	v_mov_b32_e32 v251, s69
	v_mov_b32_e32 v174, s3
	v_mov_b32_e32 v175, s33
	v_cmp_gt_i32_e32 vcc, s8, v248
	v_add_u32_e32 v249, 0xffffc000, v248
	s_nop 0
	v_cndmask_b32_e32 v248, v249, v248, vcc
	v_cndmask_b32_e32 v250, v174, v250, vcc
	v_cndmask_b32_e32 v251, v175, v251, vcc
	v_mov_b32_e32 v249, 0
	v_lshlrev_b64 v[248:249], 12, v[248:249]
	v_lshl_add_u64 v[248:249], v[250:251], 0, v[248:249]
	v_lshl_add_u64 v[248:249], v[248:249], 0, s[4:5]
	v_lshl_add_u64 v[174:175], v[248:249], 0, v[64:65]
	global_load_dwordx4 v[248:251], v[174:175], off
	v_or_b32_e32 v252, s16, v69
	v_mov_b32_e32 v254, s68
	v_mov_b32_e32 v255, s69
	v_mov_b32_e32 v176, s3
	v_mov_b32_e32 v177, s33
	v_cmp_gt_i32_e32 vcc, s8, v252
	v_add_u32_e32 v253, 0xffffc000, v252
	s_nop 0
	v_cndmask_b32_e32 v252, v253, v252, vcc
	v_cndmask_b32_e32 v254, v176, v254, vcc
	v_cndmask_b32_e32 v255, v177, v255, vcc
	v_mov_b32_e32 v253, 0
	v_lshlrev_b64 v[252:253], 12, v[252:253]
	v_lshl_add_u64 v[252:253], v[254:255], 0, v[252:253]
	v_lshl_add_u64 v[252:253], v[252:253], 0, s[4:5]
	v_lshl_add_u64 v[176:177], v[252:253], 0, v[64:65]
	global_load_dwordx4 v[252:255], v[176:177], off
	s_waitcnt lgkmcnt(0)
	s_barrier
	s_waitcnt vmcnt(8)
	ds_read_b128 v[84:87], v70
	s_mov_b32 s16, s41
	s_ashr_i32 s17, s16, 11
	v_or_b32_e32 v88, s16, v66
	v_mov_b32_e32 v89, s17
	v_cmp_gt_i32_e32 vcc, s8, v88
	ds_read_b128 v[92:95], v70 offset:4096
	s_nop 0
	v_cndmask_b32_e32 v89, 8, v89, vcc
	v_cmp_eq_u32_e64 s[0:1], s15, v89
	s_nop 1
	v_cndmask_b32_e64 v89, v103, v99, s[0:1]
	v_cndmask_b32_e64 v88, v102, v98, s[0:1]
	v_cndmask_b32_e64 v91, v105, v101, s[0:1]
	v_cndmask_b32_e64 v90, v104, v100, s[0:1]
	s_waitcnt lgkmcnt(1)
	v_pk_mul_f32 v[86:87], v[86:87], v[90:91]
	v_pk_mul_f32 v[84:85], v[84:85], v[88:89]
	s_waitcnt vmcnt(7)
	v_pk_fma_f32 v[84:85], v[84:85], 0.5, v[224:225] op_sel_hi:[1,0,1]
	v_pk_fma_f32 v[86:87], v[86:87], 0.5, v[226:227] op_sel_hi:[1,0,1]
	global_store_dwordx4 v[162:163], v[84:87], off
	v_or_b32_e32 v88, s16, v67
	v_mov_b32_e32 v89, s17
	v_cmp_gt_i32_e32 vcc, s8, v88
	ds_read_b128 v[84:87], v70 offset:8192
	s_nop 0
	v_cndmask_b32_e32 v89, 8, v89, vcc
	v_cmp_eq_u32_e64 s[0:1], s15, v89
	s_nop 1
	v_cndmask_b32_e64 v89, v103, v99, s[0:1]
	v_cndmask_b32_e64 v88, v102, v98, s[0:1]
	v_cndmask_b32_e64 v91, v105, v101, s[0:1]
	v_cndmask_b32_e64 v90, v104, v100, s[0:1]
	s_waitcnt lgkmcnt(1)
	v_pk_mul_f32 v[94:95], v[94:95], v[90:91]
	v_pk_mul_f32 v[92:93], v[92:93], v[88:89]
	s_waitcnt vmcnt(7)
; template <int EPI, int MI>
; DI void gemm_tile(const GemmDesc& g, int tm, int tn, char* smem) {
;     ...
; #pragma unroll 4
;       for (int j = 0; j < 8; ++j) {
;         const int lrow = (tid >> 5) + 8 * j;
;         const int grow = m0 + (lrow >> 5) * (32 * MI) + mi * 32 + (lrow & 31);
;         const f32x4v a4 = *(const f32x4v*)(es + lrow * 128 + c4);
;         const int rg = grow < LAT ? (grow >> 11) : 8;
;         const f32x4v m4 = rg == rgA ? m4a : m4b;
;         float* rp = (grow < LAT ? g.xres + (size_t)grow * 1024 : g.hres + (size_t)(grow - LAT) * 1024) + n0 + c4;
;         f32x4v x4 = *(const f32x4v*)rp;
;         x4 += (m4 * a4) * g.coef;
;         *(f32x4v*)rp = x4;
;       }
	v_pk_fma_f32 v[92:93], v[92:93], 0.5, v[228:229] op_sel_hi:[1,0,1]
	v_pk_fma_f32 v[94:95], v[94:95], 0.5, v[230:231] op_sel_hi:[1,0,1]
	global_store_dwordx4 v[164:165], v[92:95], off
	v_or_b32_e32 v88, s16, v68
	v_mov_b32_e32 v89, s17
	v_cmp_gt_i32_e32 vcc, s8, v88
	ds_read_b128 v[92:95], v70 offset:12288
	s_nop 0
	v_cndmask_b32_e32 v89, 8, v89, vcc
	v_cmp_eq_u32_e64 s[0:1], s15, v89
	s_nop 1
	v_cndmask_b32_e64 v89, v103, v99, s[0:1]
	v_cndmask_b32_e64 v88, v102, v98, s[0:1]
	v_cndmask_b32_e64 v91, v105, v101, s[0:1]
	v_cndmask_b32_e64 v90, v104, v100, s[0:1]
	s_waitcnt lgkmcnt(1)
	v_pk_mul_f32 v[86:87], v[86:87], v[90:91]
	v_pk_mul_f32 v[84:85], v[84:85], v[88:89]
	s_waitcnt vmcnt(7)
	v_pk_fma_f32 v[84:85], v[84:85], 0.5, v[232:233] op_sel_hi:[1,0,1]
	v_pk_fma_f32 v[86:87], v[86:87], 0.5, v[234:235] op_sel_hi:[1,0,1]
	global_store_dwordx4 v[166:167], v[84:87], off
	v_or_b32_e32 v88, s16, v69
	v_mov_b32_e32 v89, s17
	v_cmp_gt_i32_e32 vcc, s8, v88
	ds_read_b128 v[84:87], v70 offset:16384
	s_nop 0
	v_cndmask_b32_e32 v89, 8, v89, vcc
	v_cmp_eq_u32_e64 s[0:1], s15, v89
	s_nop 1
	v_cndmask_b32_e64 v89, v103, v99, s[0:1]
	v_cndmask_b32_e64 v88, v102, v98, s[0:1]
	v_cndmask_b32_e64 v91, v105, v101, s[0:1]
	v_cndmask_b32_e64 v90, v104, v100, s[0:1]
	s_waitcnt lgkmcnt(1)
	v_pk_mul_f32 v[94:95], v[94:95], v[90:91]
	v_pk_mul_f32 v[92:93], v[92:93], v[88:89]
	s_waitcnt vmcnt(7)
	v_pk_fma_f32 v[92:93], v[92:93], 0.5, v[236:237] op_sel_hi:[1,0,1]
	v_pk_fma_f32 v[94:95], v[94:95], 0.5, v[238:239] op_sel_hi:[1,0,1]
	global_store_dwordx4 v[168:169], v[92:95], off
	s_add_u32 s16, s41, 96
	s_ashr_i32 s17, s16, 11
	v_or_b32_e32 v88, s16, v66
	v_mov_b32_e32 v89, s17
	v_cmp_gt_i32_e32 vcc, s8, v88
	ds_read_b128 v[92:95], v70 offset:20480
	s_nop 0
	v_cndmask_b32_e32 v89, 8, v89, vcc
	v_cmp_eq_u32_e64 s[0:1], s15, v89
	s_nop 1
	v_cndmask_b32_e64 v89, v103, v99, s[0:1]
	v_cndmask_b32_e64 v88, v102, v98, s[0:1]
	v_cndmask_b32_e64 v91, v105, v101, s[0:1]
	v_cndmask_b32_e64 v90, v104, v100, s[0:1]
	s_waitcnt lgkmcnt(1)
	v_pk_mul_f32 v[86:87], v[86:87], v[90:91]
	v_pk_mul_f32 v[84:85], v[84:85], v[88:89]
	s_waitcnt vmcnt(7)
	v_pk_fma_f32 v[84:85], v[84:85], 0.5, v[240:241] op_sel_hi:[1,0,1]
	v_pk_fma_f32 v[86:87], v[86:87], 0.5, v[242:243] op_sel_hi:[1,0,1]
	global_store_dwordx4 v[170:171], v[84:87], off
	v_or_b32_e32 v88, s16, v67
	v_mov_b32_e32 v89, s17
	v_cmp_gt_i32_e32 vcc, s8, v88
	ds_read_b128 v[84:87], v70 offset:24576
	s_nop 0
	v_cndmask_b32_e32 v89, 8, v89, vcc
	v_cmp_eq_u32_e64 s[0:1], s15, v89
	s_nop 1
	v_cndmask_b32_e64 v89, v103, v99, s[0:1]
	v_cndmask_b32_e64 v88, v102, v98, s[0:1]
	v_cndmask_b32_e64 v91, v105, v101, s[0:1]
	v_cndmask_b32_e64 v90, v104, v100, s[0:1]
	s_waitcnt lgkmcnt(1)
	v_pk_mul_f32 v[94:95], v[94:95], v[90:91]
	v_pk_mul_f32 v[92:93], v[92:93], v[88:89]
	s_waitcnt vmcnt(7)
	v_pk_fma_f32 v[92:93], v[92:93], 0.5, v[244:245] op_sel_hi:[1,0,1]
	v_pk_fma_f32 v[94:95], v[94:95], 0.5, v[246:247] op_sel_hi:[1,0,1]
	global_store_dwordx4 v[172:173], v[92:95], off
	v_or_b32_e32 v88, s16, v68
	v_mov_b32_e32 v89, s17
	v_cmp_gt_i32_e32 vcc, s8, v88
	ds_read_b128 v[92:95], v70 offset:28672
	s_nop 0
	v_cndmask_b32_e32 v89, 8, v89, vcc
	v_cmp_eq_u32_e64 s[0:1], s15, v89
	s_nop 1
	v_cndmask_b32_e64 v89, v103, v99, s[0:1]
	v_cndmask_b32_e64 v88, v102, v98, s[0:1]
	v_cndmask_b32_e64 v91, v105, v101, s[0:1]
	v_cndmask_b32_e64 v90, v104, v100, s[0:1]
	s_waitcnt lgkmcnt(1)
	v_pk_mul_f32 v[86:87], v[86:87], v[90:91]
	v_pk_mul_f32 v[84:85], v[84:85], v[88:89]
	s_waitcnt vmcnt(7)
	v_pk_fma_f32 v[84:85], v[84:85], 0.5, v[248:249] op_sel_hi:[1,0,1]
	v_pk_fma_f32 v[86:87], v[86:87], 0.5, v[250:251] op_sel_hi:[1,0,1]
	global_store_dwordx4 v[174:175], v[84:87], off
	v_or_b32_e32 v88, s16, v69
	v_mov_b32_e32 v89, s17
	v_cmp_gt_i32_e32 vcc, s8, v88
	s_nop 1
	v_cndmask_b32_e32 v89, 8, v89, vcc
	v_cmp_eq_u32_e64 s[0:1], s15, v89
	s_nop 1
	v_cndmask_b32_e64 v89, v103, v99, s[0:1]
	v_cndmask_b32_e64 v88, v102, v98, s[0:1]
	v_cndmask_b32_e64 v91, v105, v101, s[0:1]
	v_cndmask_b32_e64 v90, v104, v100, s[0:1]
	s_waitcnt lgkmcnt(0)
	v_pk_mul_f32 v[94:95], v[94:95], v[90:91]
	v_pk_mul_f32 v[92:93], v[92:93], v[88:89]
	s_waitcnt vmcnt(7)
	v_pk_fma_f32 v[92:93], v[92:93], 0.5, v[252:253] op_sel_hi:[1,0,1]
	v_pk_fma_f32 v[94:95], v[94:95], 0.5, v[254:255] op_sel_hi:[1,0,1]
	global_store_dwordx4 v[176:177], v[92:95], off
	s_add_u32 s16, s41, 32
	v_or_b32_e32 v224, s16, v66
	v_mov_b32_e32 v226, s68
	v_mov_b32_e32 v227, s69
	v_mov_b32_e32 v162, s3
	v_mov_b32_e32 v163, s33
	v_cmp_gt_i32_e32 vcc, s8, v224
	v_add_u32_e32 v225, 0xffffc000, v224
	s_nop 0
	v_cndmask_b32_e32 v224, v225, v224, vcc
	v_cndmask_b32_e32 v226, v162, v226, vcc
	v_cndmask_b32_e32 v227, v163, v227, vcc
	v_mov_b32_e32 v225, 0
	v_lshlrev_b64 v[224:225], 12, v[224:225]
	v_lshl_add_u64 v[224:225], v[226:227], 0, v[224:225]
	v_lshl_add_u64 v[224:225], v[224:225], 0, s[4:5]
	v_lshl_add_u64 v[162:163], v[224:225], 0, v[64:65]
	global_load_dwordx4 v[224:227], v[162:163], off
	v_or_b32_e32 v228, s16, v67
	v_mov_b32_e32 v230, s68
	v_mov_b32_e32 v231, s69
	v_mov_b32_e32 v164, s3
	v_mov_b32_e32 v165, s33
	v_cmp_gt_i32_e32 vcc, s8, v228
	v_add_u32_e32 v229, 0xffffc000, v228
	s_nop 0
	v_cndmask_b32_e32 v228, v229, v228, vcc
	v_cndmask_b32_e32 v230, v164, v230, vcc
	v_cndmask_b32_e32 v231, v165, v231, vcc
	v_mov_b32_e32 v229, 0
	v_lshlrev_b64 v[228:229], 12, v[228:229]
	v_lshl_add_u64 v[228:229], v[230:231], 0, v[228:229]
	v_lshl_add_u64 v[228:229], v[228:229], 0, s[4:5]
	v_lshl_add_u64 v[164:165], v[228:229], 0, v[64:65]
	global_load_dwordx4 v[228:231], v[164:165], off
	v_or_b32_e32 v232, s16, v68
	v_mov_b32_e32 v234, s68
; template <int EPI, int MI>
; DI void gemm_tile(const GemmDesc& g, int tm, int tn, char* smem) {
;     ...
;     for (int mi = 0; mi < MI; ++mi) {
; #pragma unroll
;       for (int ni = 0; ni < 2; ++ni)
; #pragma unroll
;         for (int i = 0; i < 16; ++i) {
;           const int lrow = wm * 32 + (i & 3) + 8 * (i >> 2) + 4 * hh;
;           es[lrow * 128 + wn * 64 + ni * 32 + r] = acc[mi][ni][i];
;         }
;       __syncthreads();
; #pragma unroll 4
;       for (int j = 0; j < 8; ++j) {
;         const int lrow = (tid >> 5) + 8 * j;
;         const int grow = m0 + (lrow >> 5) * (32 * MI) + mi * 32 + (lrow & 31);
;         const f32x4v a4 = *(const f32x4v*)(es + lrow * 128 + c4);
;         const int rg = grow < LAT ? (grow >> 11) : 8;
;         const f32x4v m4 = rg == rgA ? m4a : m4b;
;         float* rp = (grow < LAT ? g.xres + (size_t)grow * 1024 : g.hres + (size_t)(grow - LAT) * 1024) + n0 + c4;
;         f32x4v x4 = *(const f32x4v*)rp;
	v_mov_b32_e32 v235, s69
	v_mov_b32_e32 v166, s3
	v_mov_b32_e32 v167, s33
	v_cmp_gt_i32_e32 vcc, s8, v232
	v_add_u32_e32 v233, 0xffffc000, v232
	s_nop 0
	v_cndmask_b32_e32 v232, v233, v232, vcc
	v_cndmask_b32_e32 v234, v166, v234, vcc
	v_cndmask_b32_e32 v235, v167, v235, vcc
	v_mov_b32_e32 v233, 0
	v_lshlrev_b64 v[232:233], 12, v[232:233]
	v_lshl_add_u64 v[232:233], v[234:235], 0, v[232:233]
	v_lshl_add_u64 v[232:233], v[232:233], 0, s[4:5]
	v_lshl_add_u64 v[166:167], v[232:233], 0, v[64:65]
	global_load_dwordx4 v[232:235], v[166:167], off
	v_or_b32_e32 v236, s16, v69
	v_mov_b32_e32 v238, s68
	v_mov_b32_e32 v239, s69
	v_mov_b32_e32 v168, s3
	v_mov_b32_e32 v169, s33
	v_cmp_gt_i32_e32 vcc, s8, v236
	v_add_u32_e32 v237, 0xffffc000, v236
	s_nop 0
	v_cndmask_b32_e32 v236, v237, v236, vcc
	v_cndmask_b32_e32 v238, v168, v238, vcc
	v_cndmask_b32_e32 v239, v169, v239, vcc
	v_mov_b32_e32 v237, 0
	v_lshlrev_b64 v[236:237], 12, v[236:237]
	v_lshl_add_u64 v[236:237], v[238:239], 0, v[236:237]
	v_lshl_add_u64 v[236:237], v[236:237], 0, s[4:5]
	v_lshl_add_u64 v[168:169], v[236:237], 0, v[64:65]
	global_load_dwordx4 v[236:239], v[168:169], off
	s_add_u32 s16, s41, 128
	v_or_b32_e32 v240, s16, v66
	v_mov_b32_e32 v242, s68
	v_mov_b32_e32 v243, s69
	v_mov_b32_e32 v170, s3
	v_mov_b32_e32 v171, s33
	v_cmp_gt_i32_e32 vcc, s8, v240
	v_add_u32_e32 v241, 0xffffc000, v240
	s_nop 0
	v_cndmask_b32_e32 v240, v241, v240, vcc
	v_cndmask_b32_e32 v242, v170, v242, vcc
	v_cndmask_b32_e32 v243, v171, v243, vcc
	v_mov_b32_e32 v241, 0
	v_lshlrev_b64 v[240:241], 12, v[240:241]
	v_lshl_add_u64 v[240:241], v[242:243], 0, v[240:241]
	v_lshl_add_u64 v[240:241], v[240:241], 0, s[4:5]
	v_lshl_add_u64 v[170:171], v[240:241], 0, v[64:65]
	global_load_dwordx4 v[240:243], v[170:171], off
	v_or_b32_e32 v244, s16, v67
	v_mov_b32_e32 v246, s68
	v_mov_b32_e32 v247, s69
	v_mov_b32_e32 v172, s3
	v_mov_b32_e32 v173, s33
	v_cmp_gt_i32_e32 vcc, s8, v244
	v_add_u32_e32 v245, 0xffffc000, v244
	s_nop 0
	v_cndmask_b32_e32 v244, v245, v244, vcc
	v_cndmask_b32_e32 v246, v172, v246, vcc
	v_cndmask_b32_e32 v247, v173, v247, vcc
	v_mov_b32_e32 v245, 0
	v_lshlrev_b64 v[244:245], 12, v[244:245]
	v_lshl_add_u64 v[244:245], v[246:247], 0, v[244:245]
	v_lshl_add_u64 v[244:245], v[244:245], 0, s[4:5]
	v_lshl_add_u64 v[172:173], v[244:245], 0, v[64:65]
	global_load_dwordx4 v[244:247], v[172:173], off
	v_or_b32_e32 v248, s16, v68
	v_mov_b32_e32 v250, s68
	v_mov_b32_e32 v251, s69
	v_mov_b32_e32 v174, s3
	v_mov_b32_e32 v175, s33
	v_cmp_gt_i32_e32 vcc, s8, v248
	v_add_u32_e32 v249, 0xffffc000, v248
	s_nop 0
	v_cndmask_b32_e32 v248, v249, v248, vcc
	v_cndmask_b32_e32 v250, v174, v250, vcc
	v_cndmask_b32_e32 v251, v175, v251, vcc
	v_mov_b32_e32 v249, 0
	v_lshlrev_b64 v[248:249], 12, v[248:249]
	v_lshl_add_u64 v[248:249], v[250:251], 0, v[248:249]
	v_lshl_add_u64 v[248:249], v[248:249], 0, s[4:5]
	v_lshl_add_u64 v[174:175], v[248:249], 0, v[64:65]
	global_load_dwordx4 v[248:251], v[174:175], off
	v_or_b32_e32 v252, s16, v69
	v_mov_b32_e32 v254, s68
	v_mov_b32_e32 v255, s69
	v_mov_b32_e32 v176, s3
	v_mov_b32_e32 v177, s33
	v_cmp_gt_i32_e32 vcc, s8, v252
	v_add_u32_e32 v253, 0xffffc000, v252
	s_nop 0
	v_cndmask_b32_e32 v252, v253, v252, vcc
	v_cndmask_b32_e32 v254, v176, v254, vcc
	v_cndmask_b32_e32 v255, v177, v255, vcc
	v_mov_b32_e32 v253, 0
	v_lshlrev_b64 v[252:253], 12, v[252:253]
	v_lshl_add_u64 v[252:253], v[254:255], 0, v[252:253]
	v_lshl_add_u64 v[252:253], v[252:253], 0, s[4:5]
	v_lshl_add_u64 v[176:177], v[252:253], 0, v[64:65]
	global_load_dwordx4 v[252:255], v[176:177], off
	s_barrier
	ds_write2_b32 v107, v48, v32 offset1:32
	ds_write2_b32 v107, v49, v33 offset0:128 offset1:160
	ds_write2_b32 v80, v50, v34 offset1:32
	ds_write2_b32 v80, v51, v35 offset0:128 offset1:160
	ds_write2_b32 v81, v52, v36 offset1:32
	ds_write2_b32 v81, v53, v37 offset0:128 offset1:160
	ds_write2_b32 v82, v54, v38 offset1:32
	ds_write2_b32 v82, v55, v39 offset0:128 offset1:160
	ds_write2_b32 v71, v56, v40 offset1:32
	ds_write2_b32 v71, v57, v41 offset0:128 offset1:160
	ds_write2_b32 v72, v58, v42 offset1:32
	ds_write2_b32 v72, v59, v43 offset0:128 offset1:160
	ds_write2_b32 v73, v60, v44 offset1:32
	ds_write2_b32 v73, v61, v45 offset0:128 offset1:160
	ds_write2_b32 v74, v62, v46 offset1:32
	ds_write2_b32 v74, v63, v47 offset0:128 offset1:160
	s_or_b32 s16, s41, 32
	s_mov_b32 s17, 0
	v_mov_b32_e32 v32, v97
	s_waitcnt lgkmcnt(0)
	s_barrier
; template <int EPI, int MI>
; DI void gemm_tile(const GemmDesc& g, int tm, int tn, char* smem) {
;     ...
; #pragma unroll 4
;       for (int j = 0; j < 8; ++j) {
;         const int lrow = (tid >> 5) + 8 * j;
;         const int grow = m0 + (lrow >> 5) * (32 * MI) + mi * 32 + (lrow & 31);
;         const f32x4v a4 = *(const f32x4v*)(es + lrow * 128 + c4);
;         const int rg = grow < LAT ? (grow >> 11) : 8;
;         const f32x4v m4 = rg == rgA ? m4a : m4b;
;         float* rp = (grow < LAT ? g.xres + (size_t)grow * 1024 : g.hres + (size_t)(grow - LAT) * 1024) + n0 + c4;
;         f32x4v x4 = *(const f32x4v*)rp;
;         x4 += (m4 * a4) * g.coef;
;         *(f32x4v*)rp = x4;
;       }
	ds_read_b128 v[84:87], v70
	s_add_u32 s16, s41, 32
	s_ashr_i32 s17, s16, 11
	v_or_b32_e32 v88, s16, v66
	v_mov_b32_e32 v89, s17
	v_cmp_gt_i32_e32 vcc, s8, v88
	ds_read_b128 v[92:95], v70 offset:4096
	s_nop 0
	v_cndmask_b32_e32 v89, 8, v89, vcc
	v_cmp_eq_u32_e64 s[0:1], s15, v89
	s_nop 1
	v_cndmask_b32_e64 v89, v103, v99, s[0:1]
	v_cndmask_b32_e64 v88, v102, v98, s[0:1]
	v_cndmask_b32_e64 v91, v105, v101, s[0:1]
	v_cndmask_b32_e64 v90, v104, v100, s[0:1]
	s_waitcnt lgkmcnt(1)
	v_pk_mul_f32 v[86:87], v[86:87], v[90:91]
	v_pk_mul_f32 v[84:85], v[84:85], v[88:89]
	s_waitcnt vmcnt(7)
	v_pk_fma_f32 v[84:85], v[84:85], 0.5, v[224:225] op_sel_hi:[1,0,1]
	v_pk_fma_f32 v[86:87], v[86:87], 0.5, v[226:227] op_sel_hi:[1,0,1]
	global_store_dwordx4 v[162:163], v[84:87], off
	v_or_b32_e32 v88, s16, v67
	v_mov_b32_e32 v89, s17
	v_cmp_gt_i32_e32 vcc, s8, v88
	ds_read_b128 v[84:87], v70 offset:8192
	s_nop 0
	v_cndmask_b32_e32 v89, 8, v89, vcc
	v_cmp_eq_u32_e64 s[0:1], s15, v89
	s_nop 1
	v_cndmask_b32_e64 v89, v103, v99, s[0:1]
	v_cndmask_b32_e64 v88, v102, v98, s[0:1]
	v_cndmask_b32_e64 v91, v105, v101, s[0:1]
	v_cndmask_b32_e64 v90, v104, v100, s[0:1]
	s_waitcnt lgkmcnt(1)
	v_pk_mul_f32 v[94:95], v[94:95], v[90:91]
	v_pk_mul_f32 v[92:93], v[92:93], v[88:89]
	s_waitcnt vmcnt(7)
	v_pk_fma_f32 v[92:93], v[92:93], 0.5, v[228:229] op_sel_hi:[1,0,1]
	v_pk_fma_f32 v[94:95], v[94:95], 0.5, v[230:231] op_sel_hi:[1,0,1]
	global_store_dwordx4 v[164:165], v[92:95], off
	v_or_b32_e32 v88, s16, v68
	v_mov_b32_e32 v89, s17
	v_cmp_gt_i32_e32 vcc, s8, v88
	ds_read_b128 v[92:95], v70 offset:12288
	s_nop 0
	v_cndmask_b32_e32 v89, 8, v89, vcc
	v_cmp_eq_u32_e64 s[0:1], s15, v89
	s_nop 1
	v_cndmask_b32_e64 v89, v103, v99, s[0:1]
	v_cndmask_b32_e64 v88, v102, v98, s[0:1]
	v_cndmask_b32_e64 v91, v105, v101, s[0:1]
	v_cndmask_b32_e64 v90, v104, v100, s[0:1]
	s_waitcnt lgkmcnt(1)
	v_pk_mul_f32 v[86:87], v[86:87], v[90:91]
	v_pk_mul_f32 v[84:85], v[84:85], v[88:89]
	s_waitcnt vmcnt(7)
	v_pk_fma_f32 v[84:85], v[84:85], 0.5, v[232:233] op_sel_hi:[1,0,1]
	v_pk_fma_f32 v[86:87], v[86:87], 0.5, v[234:235] op_sel_hi:[1,0,1]
	global_store_dwordx4 v[166:167], v[84:87], off
	v_or_b32_e32 v88, s16, v69
	v_mov_b32_e32 v89, s17
	v_cmp_gt_i32_e32 vcc, s8, v88
	ds_read_b128 v[84:87], v70 offset:16384
	s_nop 0
	v_cndmask_b32_e32 v89, 8, v89, vcc
	v_cmp_eq_u32_e64 s[0:1], s15, v89
	s_nop 1
	v_cndmask_b32_e64 v89, v103, v99, s[0:1]
	v_cndmask_b32_e64 v88, v102, v98, s[0:1]
	v_cndmask_b32_e64 v91, v105, v101, s[0:1]
	v_cndmask_b32_e64 v90, v104, v100, s[0:1]
	s_waitcnt lgkmcnt(1)
	v_pk_mul_f32 v[94:95], v[94:95], v[90:91]
	v_pk_mul_f32 v[92:93], v[92:93], v[88:89]
	s_waitcnt vmcnt(7)
	v_pk_fma_f32 v[92:93], v[92:93], 0.5, v[236:237] op_sel_hi:[1,0,1]
	v_pk_fma_f32 v[94:95], v[94:95], 0.5, v[238:239] op_sel_hi:[1,0,1]
	global_store_dwordx4 v[168:169], v[92:95], off
	s_add_u32 s16, s41, 128
	s_ashr_i32 s17, s16, 11
	v_or_b32_e32 v88, s16, v66
	v_mov_b32_e32 v89, s17
	v_cmp_gt_i32_e32 vcc, s8, v88
	ds_read_b128 v[92:95], v70 offset:20480
	s_nop 0
	v_cndmask_b32_e32 v89, 8, v89, vcc
	v_cmp_eq_u32_e64 s[0:1], s15, v89
	s_nop 1
	v_cndmask_b32_e64 v89, v103, v99, s[0:1]
	v_cndmask_b32_e64 v88, v102, v98, s[0:1]
	v_cndmask_b32_e64 v91, v105, v101, s[0:1]
	v_cndmask_b32_e64 v90, v104, v100, s[0:1]
	s_waitcnt lgkmcnt(1)
	v_pk_mul_f32 v[86:87], v[86:87], v[90:91]
	v_pk_mul_f32 v[84:85], v[84:85], v[88:89]
	s_waitcnt vmcnt(7)
	v_pk_fma_f32 v[84:85], v[84:85], 0.5, v[240:241] op_sel_hi:[1,0,1]
	v_pk_fma_f32 v[86:87], v[86:87], 0.5, v[242:243] op_sel_hi:[1,0,1]
	global_store_dwordx4 v[170:171], v[84:87], off
	v_or_b32_e32 v88, s16, v67
	v_mov_b32_e32 v89, s17
	v_cmp_gt_i32_e32 vcc, s8, v88
	ds_read_b128 v[84:87], v70 offset:24576
	s_nop 0
	v_cndmask_b32_e32 v89, 8, v89, vcc
	v_cmp_eq_u32_e64 s[0:1], s15, v89
	s_nop 1
	v_cndmask_b32_e64 v89, v103, v99, s[0:1]
	v_cndmask_b32_e64 v88, v102, v98, s[0:1]
	v_cndmask_b32_e64 v91, v105, v101, s[0:1]
	v_cndmask_b32_e64 v90, v104, v100, s[0:1]
	s_waitcnt lgkmcnt(1)
	v_pk_mul_f32 v[94:95], v[94:95], v[90:91]
	v_pk_mul_f32 v[92:93], v[92:93], v[88:89]
	s_waitcnt vmcnt(7)
	v_pk_fma_f32 v[92:93], v[92:93], 0.5, v[244:245] op_sel_hi:[1,0,1]
	v_pk_fma_f32 v[94:95], v[94:95], 0.5, v[246:247] op_sel_hi:[1,0,1]
	global_store_dwordx4 v[172:173], v[92:95], off
	v_or_b32_e32 v88, s16, v68
	v_mov_b32_e32 v89, s17
	v_cmp_gt_i32_e32 vcc, s8, v88
	ds_read_b128 v[92:95], v70 offset:28672
	s_nop 0
	v_cndmask_b32_e32 v89, 8, v89, vcc
	v_cmp_eq_u32_e64 s[0:1], s15, v89
	s_nop 1
	v_cndmask_b32_e64 v89, v103, v99, s[0:1]
	v_cndmask_b32_e64 v88, v102, v98, s[0:1]
	v_cndmask_b32_e64 v91, v105, v101, s[0:1]
	v_cndmask_b32_e64 v90, v104, v100, s[0:1]
	s_waitcnt lgkmcnt(1)
	v_pk_mul_f32 v[86:87], v[86:87], v[90:91]
	v_pk_mul_f32 v[84:85], v[84:85], v[88:89]
	s_waitcnt vmcnt(7)
	v_pk_fma_f32 v[84:85], v[84:85], 0.5, v[248:249] op_sel_hi:[1,0,1]
	v_pk_fma_f32 v[86:87], v[86:87], 0.5, v[250:251] op_sel_hi:[1,0,1]
	global_store_dwordx4 v[174:175], v[84:87], off
	v_or_b32_e32 v88, s16, v69
	v_mov_b32_e32 v89, s17
	v_cmp_gt_i32_e32 vcc, s8, v88
	s_nop 1
	v_cndmask_b32_e32 v89, 8, v89, vcc
	v_cmp_eq_u32_e64 s[0:1], s15, v89
	s_nop 1
	v_cndmask_b32_e64 v89, v103, v99, s[0:1]
	v_cndmask_b32_e64 v88, v102, v98, s[0:1]
	v_cndmask_b32_e64 v91, v105, v101, s[0:1]
	v_cndmask_b32_e64 v90, v104, v100, s[0:1]
	s_waitcnt lgkmcnt(0)
	v_pk_mul_f32 v[94:95], v[94:95], v[90:91]
	v_pk_mul_f32 v[92:93], v[92:93], v[88:89]
	s_waitcnt vmcnt(7)
; template <int EPI, int MI>
; DI void gemm_tile(const GemmDesc& g, int tm, int tn, char* smem) {
;     ...
;     for (int mi = 0; mi < MI; ++mi) {
; #pragma unroll
;       for (int ni = 0; ni < 2; ++ni)
; #pragma unroll
;         for (int i = 0; i < 16; ++i) {
;           const int lrow = wm * 32 + (i & 3) + 8 * (i >> 2) + 4 * hh;
;           es[lrow * 128 + wn * 64 + ni * 32 + r] = acc[mi][ni][i];
;         }
;       __syncthreads();
; #pragma unroll 4
;       for (int j = 0; j < 8; ++j) {
;         const int lrow = (tid >> 5) + 8 * j;
;         const int grow = m0 + (lrow >> 5) * (32 * MI) + mi * 32 + (lrow & 31);
;         const f32x4v a4 = *(const f32x4v*)(es + lrow * 128 + c4);
;         const int rg = grow < LAT ? (grow >> 11) : 8;
;         const f32x4v m4 = rg == rgA ? m4a : m4b;
;         float* rp = (grow < LAT ? g.xres + (size_t)grow * 1024 : g.hres + (size_t)(grow - LAT) * 1024) + n0 + c4;
;         f32x4v x4 = *(const f32x4v*)rp;
	v_pk_fma_f32 v[92:93], v[92:93], 0.5, v[252:253] op_sel_hi:[1,0,1]
	v_pk_fma_f32 v[94:95], v[94:95], 0.5, v[254:255] op_sel_hi:[1,0,1]
	global_store_dwordx4 v[176:177], v[92:95], off
	s_add_u32 s16, s41, 64
	v_or_b32_e32 v224, s16, v66
	v_mov_b32_e32 v226, s68
	v_mov_b32_e32 v227, s69
	v_mov_b32_e32 v162, s3
	v_mov_b32_e32 v163, s33
	v_cmp_gt_i32_e32 vcc, s8, v224
	v_add_u32_e32 v225, 0xffffc000, v224
	s_nop 0
	v_cndmask_b32_e32 v224, v225, v224, vcc
	v_cndmask_b32_e32 v226, v162, v226, vcc
	v_cndmask_b32_e32 v227, v163, v227, vcc
	v_mov_b32_e32 v225, 0
	v_lshlrev_b64 v[224:225], 12, v[224:225]
	v_lshl_add_u64 v[224:225], v[226:227], 0, v[224:225]
	v_lshl_add_u64 v[224:225], v[224:225], 0, s[4:5]
	v_lshl_add_u64 v[162:163], v[224:225], 0, v[64:65]
	global_load_dwordx4 v[224:227], v[162:163], off
	v_or_b32_e32 v228, s16, v67
	v_mov_b32_e32 v230, s68
	v_mov_b32_e32 v231, s69
	v_mov_b32_e32 v164, s3
	v_mov_b32_e32 v165, s33
	v_cmp_gt_i32_e32 vcc, s8, v228
	v_add_u32_e32 v229, 0xffffc000, v228
	s_nop 0
	v_cndmask_b32_e32 v228, v229, v228, vcc
	v_cndmask_b32_e32 v230, v164, v230, vcc
	v_cndmask_b32_e32 v231, v165, v231, vcc
	v_mov_b32_e32 v229, 0
	v_lshlrev_b64 v[228:229], 12, v[228:229]
	v_lshl_add_u64 v[228:229], v[230:231], 0, v[228:229]
	v_lshl_add_u64 v[228:229], v[228:229], 0, s[4:5]
	v_lshl_add_u64 v[164:165], v[228:229], 0, v[64:65]
	global_load_dwordx4 v[228:231], v[164:165], off
	v_or_b32_e32 v232, s16, v68
	v_mov_b32_e32 v234, s68
	v_mov_b32_e32 v235, s69
	v_mov_b32_e32 v166, s3
	v_mov_b32_e32 v167, s33
	v_cmp_gt_i32_e32 vcc, s8, v232
	v_add_u32_e32 v233, 0xffffc000, v232
	s_nop 0
	v_cndmask_b32_e32 v232, v233, v232, vcc
	v_cndmask_b32_e32 v234, v166, v234, vcc
	v_cndmask_b32_e32 v235, v167, v235, vcc
	v_mov_b32_e32 v233, 0
	v_lshlrev_b64 v[232:233], 12, v[232:233]
	v_lshl_add_u64 v[232:233], v[234:235], 0, v[232:233]
	v_lshl_add_u64 v[232:233], v[232:233], 0, s[4:5]
	v_lshl_add_u64 v[166:167], v[232:233], 0, v[64:65]
	global_load_dwordx4 v[232:235], v[166:167], off
	v_or_b32_e32 v236, s16, v69
	v_mov_b32_e32 v238, s68
	v_mov_b32_e32 v239, s69
	v_mov_b32_e32 v168, s3
	v_mov_b32_e32 v169, s33
	v_cmp_gt_i32_e32 vcc, s8, v236
	v_add_u32_e32 v237, 0xffffc000, v236
	s_nop 0
	v_cndmask_b32_e32 v236, v237, v236, vcc
	v_cndmask_b32_e32 v238, v168, v238, vcc
	v_cndmask_b32_e32 v239, v169, v239, vcc
	v_mov_b32_e32 v237, 0
	v_lshlrev_b64 v[236:237], 12, v[236:237]
	v_lshl_add_u64 v[236:237], v[238:239], 0, v[236:237]
	v_lshl_add_u64 v[236:237], v[236:237], 0, s[4:5]
	v_lshl_add_u64 v[168:169], v[236:237], 0, v[64:65]
	global_load_dwordx4 v[236:239], v[168:169], off
	s_add_u32 s16, s41, 160
	v_or_b32_e32 v240, s16, v66
	v_mov_b32_e32 v242, s68
	v_mov_b32_e32 v243, s69
	v_mov_b32_e32 v170, s3
	v_mov_b32_e32 v171, s33
	v_cmp_gt_i32_e32 vcc, s8, v240
	v_add_u32_e32 v241, 0xffffc000, v240
	s_nop 0
	v_cndmask_b32_e32 v240, v241, v240, vcc
	v_cndmask_b32_e32 v242, v170, v242, vcc
	v_cndmask_b32_e32 v243, v171, v243, vcc
	v_mov_b32_e32 v241, 0
	v_lshlrev_b64 v[240:241], 12, v[240:241]
	v_lshl_add_u64 v[240:241], v[242:243], 0, v[240:241]
	v_lshl_add_u64 v[240:241], v[240:241], 0, s[4:5]
	v_lshl_add_u64 v[170:171], v[240:241], 0, v[64:65]
	global_load_dwordx4 v[240:243], v[170:171], off
	v_or_b32_e32 v244, s16, v67
	v_mov_b32_e32 v246, s68
	v_mov_b32_e32 v247, s69
	v_mov_b32_e32 v172, s3
	v_mov_b32_e32 v173, s33
	v_cmp_gt_i32_e32 vcc, s8, v244
	v_add_u32_e32 v245, 0xffffc000, v244
	s_nop 0
	v_cndmask_b32_e32 v244, v245, v244, vcc
	v_cndmask_b32_e32 v246, v172, v246, vcc
	v_cndmask_b32_e32 v247, v173, v247, vcc
	v_mov_b32_e32 v245, 0
	v_lshlrev_b64 v[244:245], 12, v[244:245]
	v_lshl_add_u64 v[244:245], v[246:247], 0, v[244:245]
	v_lshl_add_u64 v[244:245], v[244:245], 0, s[4:5]
	v_lshl_add_u64 v[172:173], v[244:245], 0, v[64:65]
	global_load_dwordx4 v[244:247], v[172:173], off
	v_or_b32_e32 v248, s16, v68
	v_mov_b32_e32 v250, s68
	v_mov_b32_e32 v251, s69
	v_mov_b32_e32 v174, s3
	v_mov_b32_e32 v175, s33
	v_cmp_gt_i32_e32 vcc, s8, v248
	v_add_u32_e32 v249, 0xffffc000, v248
	s_nop 0
	v_cndmask_b32_e32 v248, v249, v248, vcc
	v_cndmask_b32_e32 v250, v174, v250, vcc
	v_cndmask_b32_e32 v251, v175, v251, vcc
	v_mov_b32_e32 v249, 0
	v_lshlrev_b64 v[248:249], 12, v[248:249]
	v_lshl_add_u64 v[248:249], v[250:251], 0, v[248:249]
	v_lshl_add_u64 v[248:249], v[248:249], 0, s[4:5]
	v_lshl_add_u64 v[174:175], v[248:249], 0, v[64:65]
	global_load_dwordx4 v[248:251], v[174:175], off
	v_or_b32_e32 v252, s16, v69
	v_mov_b32_e32 v254, s68
	v_mov_b32_e32 v255, s69
	v_mov_b32_e32 v176, s3
	v_mov_b32_e32 v177, s33
	v_cmp_gt_i32_e32 vcc, s8, v252
	v_add_u32_e32 v253, 0xffffc000, v252
	s_nop 0
	v_cndmask_b32_e32 v252, v253, v252, vcc
	v_cndmask_b32_e32 v254, v176, v254, vcc
	v_cndmask_b32_e32 v255, v177, v255, vcc
	v_mov_b32_e32 v253, 0
	v_lshlrev_b64 v[252:253], 12, v[252:253]
	v_lshl_add_u64 v[252:253], v[254:255], 0, v[252:253]
	v_lshl_add_u64 v[252:253], v[252:253], 0, s[4:5]
	v_lshl_add_u64 v[176:177], v[252:253], 0, v[64:65]
	global_load_dwordx4 v[252:255], v[176:177], off
	s_add_i32 s41, s41, 64
	s_mov_b32 s16, 0
	s_barrier
	ds_write2_b32 v107, v16, v0 offset1:32
	ds_write2_b32 v107, v17, v1 offset0:128 offset1:160
	ds_write2_b32 v80, v18, v2 offset1:32
	ds_write2_b32 v80, v19, v3 offset0:128 offset1:160
	ds_write2_b32 v81, v20, v4 offset1:32
	ds_write2_b32 v81, v21, v5 offset0:128 offset1:160
	ds_write2_b32 v82, v22, v6 offset1:32
	ds_write2_b32 v82, v23, v7 offset0:128 offset1:160
	ds_write2_b32 v71, v24, v8 offset1:32
	ds_write2_b32 v71, v25, v9 offset0:128 offset1:160
	ds_write2_b32 v72, v26, v10 offset1:32
	ds_write2_b32 v72, v27, v11 offset0:128 offset1:160
	ds_write2_b32 v73, v28, v12 offset1:32
	ds_write2_b32 v73, v29, v13 offset0:128 offset1:160
	ds_write2_b32 v74, v30, v14 offset1:32
	ds_write2_b32 v74, v31, v15 offset0:128 offset1:160
	s_waitcnt lgkmcnt(0)
	s_barrier
; template <int EPI, int MI>
; DI void gemm_tile(const GemmDesc& g, int tm, int tn, char* smem) {
;     ...
; #pragma unroll 4
;       for (int j = 0; j < 8; ++j) {
;         const int lrow = (tid >> 5) + 8 * j;
;         const int grow = m0 + (lrow >> 5) * (32 * MI) + mi * 32 + (lrow & 31);
;         const f32x4v a4 = *(const f32x4v*)(es + lrow * 128 + c4);
;         const int rg = grow < LAT ? (grow >> 11) : 8;
;         const f32x4v m4 = rg == rgA ? m4a : m4b;
;         float* rp = (grow < LAT ? g.xres + (size_t)grow * 1024 : g.hres + (size_t)(grow - LAT) * 1024) + n0 + c4;
;         f32x4v x4 = *(const f32x4v*)rp;
;         x4 += (m4 * a4) * g.coef;
;         *(f32x4v*)rp = x4;
;       }
;       __syncthreads();
;     }
; template <int EPI, int MI>
; DI void gemm_phase(const GemmDesc& g, char* smem, int vb, int nvb) {
;     ...
;   for (int q = start; q < local; q += step) {
;     const int mg = q / per;
;     const int rem = q - mg * per;
;     const int tn = rem / PM;
;     const int tm = mbase + mg * PM + (rem - tn * PM);
;     gemm_tile<EPI, MI>(g, tm, tn, smem);
	ds_read_b128 v[84:87], v70
	s_mov_b32 s16, s41
	s_ashr_i32 s17, s16, 11
	v_or_b32_e32 v88, s16, v66
	v_mov_b32_e32 v89, s17
	v_cmp_gt_i32_e32 vcc, s8, v88
	ds_read_b128 v[92:95], v70 offset:4096
	s_nop 0
	v_cndmask_b32_e32 v89, 8, v89, vcc
	v_cmp_eq_u32_e64 s[0:1], s15, v89
	s_nop 1
	v_cndmask_b32_e64 v89, v103, v99, s[0:1]
	v_cndmask_b32_e64 v88, v102, v98, s[0:1]
	v_cndmask_b32_e64 v91, v105, v101, s[0:1]
	v_cndmask_b32_e64 v90, v104, v100, s[0:1]
	s_waitcnt lgkmcnt(1)
	v_pk_mul_f32 v[86:87], v[86:87], v[90:91]
	v_pk_mul_f32 v[84:85], v[84:85], v[88:89]
	s_waitcnt vmcnt(7)
	v_pk_fma_f32 v[84:85], v[84:85], 0.5, v[224:225] op_sel_hi:[1,0,1]
	v_pk_fma_f32 v[86:87], v[86:87], 0.5, v[226:227] op_sel_hi:[1,0,1]
	global_store_dwordx4 v[162:163], v[84:87], off
	v_or_b32_e32 v88, s16, v67
	v_mov_b32_e32 v89, s17
	v_cmp_gt_i32_e32 vcc, s8, v88
	ds_read_b128 v[84:87], v70 offset:8192
	s_nop 0
	v_cndmask_b32_e32 v89, 8, v89, vcc
	v_cmp_eq_u32_e64 s[0:1], s15, v89
	s_nop 1
	v_cndmask_b32_e64 v89, v103, v99, s[0:1]
	v_cndmask_b32_e64 v88, v102, v98, s[0:1]
	v_cndmask_b32_e64 v91, v105, v101, s[0:1]
	v_cndmask_b32_e64 v90, v104, v100, s[0:1]
	s_waitcnt lgkmcnt(1)
	v_pk_mul_f32 v[94:95], v[94:95], v[90:91]
	v_pk_mul_f32 v[92:93], v[92:93], v[88:89]
	s_waitcnt vmcnt(7)
	v_pk_fma_f32 v[92:93], v[92:93], 0.5, v[228:229] op_sel_hi:[1,0,1]
	v_pk_fma_f32 v[94:95], v[94:95], 0.5, v[230:231] op_sel_hi:[1,0,1]
	global_store_dwordx4 v[164:165], v[92:95], off
	v_or_b32_e32 v88, s16, v68
	v_mov_b32_e32 v89, s17
	v_cmp_gt_i32_e32 vcc, s8, v88
	ds_read_b128 v[92:95], v70 offset:12288
	s_nop 0
	v_cndmask_b32_e32 v89, 8, v89, vcc
	v_cmp_eq_u32_e64 s[0:1], s15, v89
	s_nop 1
	v_cndmask_b32_e64 v89, v103, v99, s[0:1]
	v_cndmask_b32_e64 v88, v102, v98, s[0:1]
	v_cndmask_b32_e64 v91, v105, v101, s[0:1]
	v_cndmask_b32_e64 v90, v104, v100, s[0:1]
	s_waitcnt lgkmcnt(1)
	v_pk_mul_f32 v[86:87], v[86:87], v[90:91]
	v_pk_mul_f32 v[84:85], v[84:85], v[88:89]
	s_waitcnt vmcnt(7)
	v_pk_fma_f32 v[84:85], v[84:85], 0.5, v[232:233] op_sel_hi:[1,0,1]
	v_pk_fma_f32 v[86:87], v[86:87], 0.5, v[234:235] op_sel_hi:[1,0,1]
	global_store_dwordx4 v[166:167], v[84:87], off
	v_or_b32_e32 v88, s16, v69
	v_mov_b32_e32 v89, s17
	v_cmp_gt_i32_e32 vcc, s8, v88
	ds_read_b128 v[84:87], v70 offset:16384
	s_nop 0
	v_cndmask_b32_e32 v89, 8, v89, vcc
	v_cmp_eq_u32_e64 s[0:1], s15, v89
	s_nop 1
	v_cndmask_b32_e64 v89, v103, v99, s[0:1]
	v_cndmask_b32_e64 v88, v102, v98, s[0:1]
	v_cndmask_b32_e64 v91, v105, v101, s[0:1]
	v_cndmask_b32_e64 v90, v104, v100, s[0:1]
	s_waitcnt lgkmcnt(1)
	v_pk_mul_f32 v[94:95], v[94:95], v[90:91]
	v_pk_mul_f32 v[92:93], v[92:93], v[88:89]
	s_waitcnt vmcnt(7)
	v_pk_fma_f32 v[92:93], v[92:93], 0.5, v[236:237] op_sel_hi:[1,0,1]
	v_pk_fma_f32 v[94:95], v[94:95], 0.5, v[238:239] op_sel_hi:[1,0,1]
	global_store_dwordx4 v[168:169], v[92:95], off
	s_add_u32 s16, s41, 96
	s_ashr_i32 s17, s16, 11
	v_or_b32_e32 v88, s16, v66
	v_mov_b32_e32 v89, s17
	v_cmp_gt_i32_e32 vcc, s8, v88
	ds_read_b128 v[92:95], v70 offset:20480
	s_nop 0
	v_cndmask_b32_e32 v89, 8, v89, vcc
	v_cmp_eq_u32_e64 s[0:1], s15, v89
	s_nop 1
	v_cndmask_b32_e64 v89, v103, v99, s[0:1]
	v_cndmask_b32_e64 v88, v102, v98, s[0:1]
	v_cndmask_b32_e64 v91, v105, v101, s[0:1]
	v_cndmask_b32_e64 v90, v104, v100, s[0:1]
	s_waitcnt lgkmcnt(1)
	v_pk_mul_f32 v[86:87], v[86:87], v[90:91]
	v_pk_mul_f32 v[84:85], v[84:85], v[88:89]
	s_waitcnt vmcnt(7)
	v_pk_fma_f32 v[84:85], v[84:85], 0.5, v[240:241] op_sel_hi:[1,0,1]
	v_pk_fma_f32 v[86:87], v[86:87], 0.5, v[242:243] op_sel_hi:[1,0,1]
	global_store_dwordx4 v[170:171], v[84:87], off
	v_or_b32_e32 v88, s16, v67
	v_mov_b32_e32 v89, s17
	v_cmp_gt_i32_e32 vcc, s8, v88
	ds_read_b128 v[84:87], v70 offset:24576
	s_nop 0
	v_cndmask_b32_e32 v89, 8, v89, vcc
	v_cmp_eq_u32_e64 s[0:1], s15, v89
	s_nop 1
	v_cndmask_b32_e64 v89, v103, v99, s[0:1]
	v_cndmask_b32_e64 v88, v102, v98, s[0:1]
	v_cndmask_b32_e64 v91, v105, v101, s[0:1]
	v_cndmask_b32_e64 v90, v104, v100, s[0:1]
	s_waitcnt lgkmcnt(1)
	v_pk_mul_f32 v[94:95], v[94:95], v[90:91]
	v_pk_mul_f32 v[92:93], v[92:93], v[88:89]
	s_waitcnt vmcnt(7)
	v_pk_fma_f32 v[92:93], v[92:93], 0.5, v[244:245] op_sel_hi:[1,0,1]
	v_pk_fma_f32 v[94:95], v[94:95], 0.5, v[246:247] op_sel_hi:[1,0,1]
	global_store_dwordx4 v[172:173], v[92:95], off
	v_or_b32_e32 v88, s16, v68
	v_mov_b32_e32 v89, s17
	v_cmp_gt_i32_e32 vcc, s8, v88
	ds_read_b128 v[92:95], v70 offset:28672
	s_nop 0
	v_cndmask_b32_e32 v89, 8, v89, vcc
	v_cmp_eq_u32_e64 s[0:1], s15, v89
	s_nop 1
	v_cndmask_b32_e64 v89, v103, v99, s[0:1]
	v_cndmask_b32_e64 v88, v102, v98, s[0:1]
	v_cndmask_b32_e64 v91, v105, v101, s[0:1]
	v_cndmask_b32_e64 v90, v104, v100, s[0:1]
	s_waitcnt lgkmcnt(1)
	v_pk_mul_f32 v[86:87], v[86:87], v[90:91]
	v_pk_mul_f32 v[84:85], v[84:85], v[88:89]
	s_waitcnt vmcnt(7)
	v_pk_fma_f32 v[84:85], v[84:85], 0.5, v[248:249] op_sel_hi:[1,0,1]
	v_pk_fma_f32 v[86:87], v[86:87], 0.5, v[250:251] op_sel_hi:[1,0,1]
	global_store_dwordx4 v[174:175], v[84:87], off
	v_or_b32_e32 v88, s16, v69
	v_mov_b32_e32 v89, s17
	v_cmp_gt_i32_e32 vcc, s8, v88
	s_nop 1
	v_cndmask_b32_e32 v89, 8, v89, vcc
	v_cmp_eq_u32_e64 s[0:1], s15, v89
	s_nop 1
	v_cndmask_b32_e64 v89, v103, v99, s[0:1]
	v_cndmask_b32_e64 v88, v102, v98, s[0:1]
	v_cndmask_b32_e64 v91, v105, v101, s[0:1]
	v_cndmask_b32_e64 v90, v104, v100, s[0:1]
	s_waitcnt lgkmcnt(0)
	v_pk_mul_f32 v[94:95], v[94:95], v[90:91]
	v_pk_mul_f32 v[92:93], v[92:93], v[88:89]
	s_waitcnt vmcnt(7)
	v_pk_fma_f32 v[92:93], v[92:93], 0.5, v[252:253] op_sel_hi:[1,0,1]
	v_pk_fma_f32 v[94:95], v[94:95], 0.5, v[254:255] op_sel_hi:[1,0,1]
	global_store_dwordx4 v[176:177], v[92:95], off
	v_readlane_b32 s0, v218, 38
	s_add_i32 s40, s40, s0
	v_readlane_b32 s0, v218, 31
	s_add_i32 s39, s39, s0
	v_readlane_b32 s0, v221, 13
	s_cmp_ge_i32 s40, s0
	s_barrier
	s_cbranch_scc0 .LBB0_1491
